# GEMM K-loops: removed the mid-cluster s_setprio 0/1 yield pairs (32 MFMAs back-to-back at prio 1)
# speedup vs baseline: 1.0102x; 1.0017x over previous
; #define PG8_STAGE(bufoff, gbase, voff) do { _Pragma("unroll") for (int _i = 0; _i < 2; ++_i) \
;         __builtin_amdgcn_global_load_lds((const unsigned*)((const char*)(gbase) + (voff)[_i]), (LAS unsigned*)(lds + (bufoff) + ldsw + _i * 8192), 16, 0, 0); } while (0)
; #define PG8_LDA(dst, b, h) do { _Pragma("unroll") for (int m = 0; m < 4; ++m) _Pragma("unroll") for (int k = 0; k < 2; ++k) dst[m][k] = *(const LAS bf16x8*)(lds + PG8_SA(b, h) + aoff + m * 2048 + k * 1024); } while (0)
; #define PG8_LDB(dst, b, h) do { _Pragma("unroll") for (int n = 0; n < 2; ++n) _Pragma("unroll") for (int k = 0; k < 2; ++k) dst[n][k] = *(const LAS bf16x8*)(lds + PG8_SB(b, h) + boff + n * 2048 + k * 1024); } while (0)
; #define PG8_MMA(ai, bj, At, Bt) do { __builtin_amdgcn_s_setprio(1); _Pragma("unroll") for (int m = 0; m < 4; ++m) _Pragma("unroll") for (int n = 0; n < 2; ++n) _Pragma("unroll") for (int k = 0; k < 2; ++k) \
;         acc[ai][bj][m][n] = __builtin_amdgcn_mfma_f32_16x16x32_bf16(Bt[n][k], At[m][k], acc[ai][bj][m][n], 0, 0, 0); __builtin_amdgcn_s_setprio(0); } while (0)
; #define PG8_WAIT_V(n) asm volatile("s_waitcnt vmcnt(" #n ")" ::: "memory")
; #define PG8_WAIT_L(n) asm volatile("s_waitcnt lgkmcnt(" #n ")" ::: "memory")
; #define PG8_BAR __builtin_amdgcn_s_barrier()
; #define PG8_SCHED __builtin_amdgcn_sched_barrier(0)
; template <class Epi>
; DI void gemm_phase(LAS unsigned char* lds, const Gemm g, const StaticOrder& S, const Epi& E, int wv0) {
;     ...
;             PG8_LDB(B0, 0, 0); PG8_LDB(B1, 0, 1); PG8_SCHED; PG8_LDA(At, 0, 0); PG8_STAGE(PG8_SA(1, 1), a1 + hstepA, voffA);
;             PG8_WAIT_V(8); PG8_WAIT_L(0); PG8_BAR; PG8_MMA(0, 0, At, B0); PG8_MMA(0, 1, At, B1); PG8_BAR; PG8_SCHED;
;             PG8_LDA(At, 0, 1); PG8_STAGE(PG8_SB(0, 0), b2, voffB); PG8_STAGE(PG8_SB(0, 1), b2 + hstepB, voffB); PG8_STAGE(PG8_SA(0, 0), a2, voffA);
;             PG8_WAIT_V(8); PG8_WAIT_L(0); PG8_BAR; PG8_MMA(1, 0, At, B0); PG8_MMA(1, 1, At, B1); PG8_BAR; PG8_SCHED;
.LBB0_417:
	v_add_u32_e32 v140, s66, v142
	ds_read_b128 v[144:147], v140
	ds_read_b128 v[148:151], v140 offset:1024
	ds_read_b128 v[152:155], v140 offset:2048
	ds_read_b128 v[178:181], v140 offset:3072
	v_add_u32_e32 v140, s67, v142
	ds_read_b128 v[182:185], v140
	ds_read_b128 v[186:189], v140 offset:1024
	ds_read_b128 v[190:193], v140 offset:2048
	ds_read_b128 v[194:197], v140 offset:3072
	s_add_u32 s18, s16, 0xfffc0080
	s_addc_u32 s19, s17, -1
	s_cmp_eq_u32 s57, 12
	s_cselect_b32 s21, s11, s19
	s_cselect_b32 s20, s53, s18
	s_cselect_b32 s19, s9, s56
	s_cselect_b32 s18, s54, s55
	v_lshl_add_u64 v[140:141], s[16:17], 0, v[138:139]
	s_add_i32 m0, s30, 0xc000
	ds_read_b128 v[210:213], v143
	ds_read_b128 v[214:217], v143 offset:1024
	ds_read_b128 v[218:221], v143 offset:2048
	ds_read_b128 v[222:225], v143 offset:3072
	ds_read_b128 v[226:229], v143 offset:4096
	ds_read_b128 v[230:233], v143 offset:5120
	ds_read_b128 v[234:237], v143 offset:6144
	ds_read_b128 v[238:241], v143 offset:7168
	global_load_lds_dwordx4 v[140:141], off
	v_lshl_add_u64 v[140:141], s[16:17], 0, v[136:137]
	s_add_i32 m0, s30, 0xe000
	s_nop 0
	global_load_lds_dwordx4 v[140:141], off
	s_waitcnt vmcnt(8)
	s_waitcnt lgkmcnt(0)
	s_barrier
	s_setprio 1
	s_waitcnt lgkmcnt(0)
	v_mfma_f32_16x16x32_bf16 v[126:129], v[144:147], v[210:213], v[126:129]
	v_mfma_f32_16x16x32_bf16 v[122:125], v[152:155], v[210:213], v[122:125]
	v_mfma_f32_16x16x32_bf16 v[110:113], v[144:147], v[218:221], v[110:113]
	v_mfma_f32_16x16x32_bf16 v[106:109], v[152:155], v[218:221], v[106:109]
	v_mfma_f32_16x16x32_bf16 v[94:97], v[144:147], v[226:229], v[94:97]
	v_mfma_f32_16x16x32_bf16 v[90:93], v[152:155], v[226:229], v[90:93]
	v_mfma_f32_16x16x32_bf16 v[78:81], v[144:147], v[234:237], v[78:81]
	v_mfma_f32_16x16x32_bf16 v[74:77], v[152:155], v[234:237], v[74:77]
	v_mfma_f32_16x16x32_bf16 v[126:129], v[148:151], v[214:217], v[126:129]
	v_mfma_f32_16x16x32_bf16 v[122:125], v[178:181], v[214:217], v[122:125]
	v_mfma_f32_16x16x32_bf16 v[110:113], v[148:151], v[222:225], v[110:113]
	v_mfma_f32_16x16x32_bf16 v[106:109], v[178:181], v[222:225], v[106:109]
	v_mfma_f32_16x16x32_bf16 v[94:97], v[148:151], v[230:233], v[94:97]
	v_mfma_f32_16x16x32_bf16 v[90:93], v[178:181], v[230:233], v[90:93]
	v_mfma_f32_16x16x32_bf16 v[78:81], v[148:151], v[238:241], v[78:81]
	v_mfma_f32_16x16x32_bf16 v[74:77], v[178:181], v[238:241], v[74:77]
	v_mfma_f32_16x16x32_bf16 v[118:121], v[182:185], v[210:213], v[118:121]
	v_mfma_f32_16x16x32_bf16 v[114:117], v[190:193], v[210:213], v[114:117]
	v_mfma_f32_16x16x32_bf16 v[102:105], v[182:185], v[218:221], v[102:105]
	v_mfma_f32_16x16x32_bf16 v[98:101], v[190:193], v[218:221], v[98:101]
	v_mfma_f32_16x16x32_bf16 v[86:89], v[182:185], v[226:229], v[86:89]
	v_mfma_f32_16x16x32_bf16 v[82:85], v[190:193], v[226:229], v[82:85]
	v_mfma_f32_16x16x32_bf16 v[70:73], v[182:185], v[234:237], v[70:73]
	v_mfma_f32_16x16x32_bf16 v[66:69], v[190:193], v[234:237], v[66:69]
	v_mfma_f32_16x16x32_bf16 v[118:121], v[186:189], v[214:217], v[118:121]
	v_mfma_f32_16x16x32_bf16 v[114:117], v[194:197], v[214:217], v[114:117]
	v_mfma_f32_16x16x32_bf16 v[102:105], v[186:189], v[222:225], v[102:105]
	v_mfma_f32_16x16x32_bf16 v[98:101], v[194:197], v[222:225], v[98:101]
	v_mfma_f32_16x16x32_bf16 v[86:89], v[186:189], v[230:233], v[86:89]
	v_mfma_f32_16x16x32_bf16 v[82:85], v[194:197], v[230:233], v[82:85]
	v_mfma_f32_16x16x32_bf16 v[70:73], v[186:189], v[238:241], v[70:73]
	v_mfma_f32_16x16x32_bf16 v[66:69], v[194:197], v[238:241], v[66:69]
	s_setprio 0
	s_barrier
	s_mov_b32 m0, s26
	v_lshl_add_u64 v[140:141], s[18:19], 0, v[0:1]
	s_add_u32 s58, s18, 0x40000
	ds_read_b128 v[210:213], v143 offset:16384
	ds_read_b128 v[214:217], v143 offset:17408
	ds_read_b128 v[218:221], v143 offset:18432
	ds_read_b128 v[222:225], v143 offset:19456
	ds_read_b128 v[226:229], v143 offset:20480
	ds_read_b128 v[230:233], v143 offset:21504
	ds_read_b128 v[234:237], v143 offset:22528
	ds_read_b128 v[238:241], v143 offset:23552
	global_load_lds_dwordx4 v[140:141], off
	v_lshl_add_u64 v[158:159], s[18:19], 0, v[130:131]
	s_mov_b32 m0, s27
	s_addc_u32 s59, s19, 0
	global_load_lds_dwordx4 v[158:159], off
	v_lshl_add_u64 v[160:161], s[58:59], 0, v[0:1]
	s_mov_b32 m0, s28
	v_lshl_add_u64 v[162:163], s[20:21], 0, v[132:133]
	global_load_lds_dwordx4 v[160:161], off
	v_lshl_add_u64 v[160:161], s[58:59], 0, v[130:131]
	s_mov_b32 m0, s29
	s_nop 0
	global_load_lds_dwordx4 v[160:161], off
	v_lshl_add_u64 v[160:161], s[20:21], 0, v[134:135]
	s_mov_b32 m0, s30
	s_nop 0
	global_load_lds_dwordx4 v[160:161], off
	s_mov_b32 m0, s31
	s_nop 0
	global_load_lds_dwordx4 v[162:163], off
	s_waitcnt vmcnt(8)
	s_waitcnt lgkmcnt(0)
	s_barrier
; #define PG8_STAGE(bufoff, gbase, voff) do { _Pragma("unroll") for (int _i = 0; _i < 2; ++_i) \
;         __builtin_amdgcn_global_load_lds((const unsigned*)((const char*)(gbase) + (voff)[_i]), (LAS unsigned*)(lds + (bufoff) + ldsw + _i * 8192), 16, 0, 0); } while (0)
; #define PG8_LDA(dst, b, h) do { _Pragma("unroll") for (int m = 0; m < 4; ++m) _Pragma("unroll") for (int k = 0; k < 2; ++k) dst[m][k] = *(const LAS bf16x8*)(lds + PG8_SA(b, h) + aoff + m * 2048 + k * 1024); } while (0)
; #define PG8_LDB(dst, b, h) do { _Pragma("unroll") for (int n = 0; n < 2; ++n) _Pragma("unroll") for (int k = 0; k < 2; ++k) dst[n][k] = *(const LAS bf16x8*)(lds + PG8_SB(b, h) + boff + n * 2048 + k * 1024); } while (0)
; #define PG8_MMA(ai, bj, At, Bt) do { __builtin_amdgcn_s_setprio(1); _Pragma("unroll") for (int m = 0; m < 4; ++m) _Pragma("unroll") for (int n = 0; n < 2; ++n) _Pragma("unroll") for (int k = 0; k < 2; ++k) \
;         acc[ai][bj][m][n] = __builtin_amdgcn_mfma_f32_16x16x32_bf16(Bt[n][k], At[m][k], acc[ai][bj][m][n], 0, 0, 0); __builtin_amdgcn_s_setprio(0); } while (0)
; #define PG8_WAIT_V(n) asm volatile("s_waitcnt vmcnt(" #n ")" ::: "memory")
; #define PG8_WAIT_L(n) asm volatile("s_waitcnt lgkmcnt(" #n ")" ::: "memory")
; #define PG8_BAR __builtin_amdgcn_s_barrier()
; #define PG8_SCHED __builtin_amdgcn_sched_barrier(0)
; template <class Epi>
; DI void gemm_phase(LAS unsigned char* lds, const Gemm g, const StaticOrder& S, const Epi& E, int wv0) {
;     ...
;             PG8_WAIT_V(8); PG8_WAIT_L(0); PG8_BAR; PG8_MMA(1, 0, At, B0); PG8_MMA(1, 1, At, B1); PG8_BAR; PG8_SCHED;
;             PG8_LDB(B0, 1, 0); PG8_LDB(B1, 1, 1); PG8_SCHED; PG8_LDA(At, 1, 0); PG8_STAGE(PG8_SA(0, 1), a2 + hstepA, voffA);
;             PG8_WAIT_V(8); PG8_WAIT_L(0); PG8_BAR; PG8_MMA(0, 0, At, B0); PG8_MMA(0, 1, At, B1); PG8_BAR; PG8_SCHED;
;             PG8_LDA(At, 1, 1); PG8_STAGE(PG8_SB(1, 0), b3, voffB); PG8_STAGE(PG8_SB(1, 1), b3 + hstepB, voffB); PG8_STAGE(PG8_SA(1, 0), a3, voffA);
	s_setprio 1
	s_waitcnt lgkmcnt(0)
	v_mfma_f32_16x16x32_bf16 v[62:65], v[144:147], v[210:213], v[62:65]
	v_mfma_f32_16x16x32_bf16 v[58:61], v[152:155], v[210:213], v[58:61]
	v_mfma_f32_16x16x32_bf16 v[46:49], v[144:147], v[218:221], v[46:49]
	v_mfma_f32_16x16x32_bf16 v[42:45], v[152:155], v[218:221], v[42:45]
	v_mfma_f32_16x16x32_bf16 v[30:33], v[144:147], v[226:229], v[30:33]
	v_mfma_f32_16x16x32_bf16 v[26:29], v[152:155], v[226:229], v[26:29]
	v_mfma_f32_16x16x32_bf16 v[14:17], v[144:147], v[234:237], v[14:17]
	v_mfma_f32_16x16x32_bf16 v[10:13], v[152:155], v[234:237], v[10:13]
	v_mfma_f32_16x16x32_bf16 v[62:65], v[148:151], v[214:217], v[62:65]
	v_mfma_f32_16x16x32_bf16 v[58:61], v[178:181], v[214:217], v[58:61]
	v_mfma_f32_16x16x32_bf16 v[46:49], v[148:151], v[222:225], v[46:49]
	v_mfma_f32_16x16x32_bf16 v[42:45], v[178:181], v[222:225], v[42:45]
	v_mfma_f32_16x16x32_bf16 v[30:33], v[148:151], v[230:233], v[30:33]
	v_mfma_f32_16x16x32_bf16 v[26:29], v[178:181], v[230:233], v[26:29]
	v_mfma_f32_16x16x32_bf16 v[14:17], v[148:151], v[238:241], v[14:17]
	v_mfma_f32_16x16x32_bf16 v[10:13], v[178:181], v[238:241], v[10:13]
	v_mfma_f32_16x16x32_bf16 v[54:57], v[182:185], v[210:213], v[54:57]
	v_mfma_f32_16x16x32_bf16 v[50:53], v[190:193], v[210:213], v[50:53]
	v_mfma_f32_16x16x32_bf16 v[38:41], v[182:185], v[218:221], v[38:41]
	v_mfma_f32_16x16x32_bf16 v[34:37], v[190:193], v[218:221], v[34:37]
	v_mfma_f32_16x16x32_bf16 v[22:25], v[182:185], v[226:229], v[22:25]
	v_mfma_f32_16x16x32_bf16 v[18:21], v[190:193], v[226:229], v[18:21]
	v_mfma_f32_16x16x32_bf16 v[6:9], v[182:185], v[234:237], v[6:9]
	v_mfma_f32_16x16x32_bf16 v[2:5], v[190:193], v[234:237], v[2:5]
	v_mfma_f32_16x16x32_bf16 v[54:57], v[186:189], v[214:217], v[54:57]
	v_mfma_f32_16x16x32_bf16 v[50:53], v[194:197], v[214:217], v[50:53]
	v_mfma_f32_16x16x32_bf16 v[38:41], v[186:189], v[222:225], v[38:41]
	v_mfma_f32_16x16x32_bf16 v[34:37], v[194:197], v[222:225], v[34:37]
	v_mfma_f32_16x16x32_bf16 v[22:25], v[186:189], v[230:233], v[22:25]
	v_mfma_f32_16x16x32_bf16 v[18:21], v[194:197], v[230:233], v[18:21]
	v_mfma_f32_16x16x32_bf16 v[6:9], v[186:189], v[238:241], v[6:9]
	v_mfma_f32_16x16x32_bf16 v[2:5], v[194:197], v[238:241], v[2:5]
	s_setprio 0
	s_barrier
	v_add_u32_e32 v164, s68, v142
	ds_read_b128 v[144:147], v164
	ds_read_b128 v[148:151], v164 offset:1024
	ds_read_b128 v[152:155], v164 offset:2048
	ds_read_b128 v[178:181], v164 offset:3072
	v_add_u32_e32 v164, s69, v142
	ds_read_b128 v[182:185], v164
	ds_read_b128 v[186:189], v164 offset:1024
	ds_read_b128 v[190:193], v164 offset:2048
	ds_read_b128 v[194:197], v164 offset:3072
	s_add_u32 s20, s20, 0x40000
	s_addc_u32 s21, s21, 0
	s_mov_b32 m0, s42
	v_lshl_add_u64 v[164:165], s[20:21], 0, v[134:135]
	ds_read_b128 v[210:213], v143 offset:32768
	ds_read_b128 v[214:217], v143 offset:33792
	ds_read_b128 v[218:221], v143 offset:34816
	ds_read_b128 v[222:225], v143 offset:35840
	ds_read_b128 v[226:229], v143 offset:36864
	ds_read_b128 v[230:233], v143 offset:37888
	ds_read_b128 v[234:237], v143 offset:38912
	ds_read_b128 v[238:241], v143 offset:39936
	global_load_lds_dwordx4 v[164:165], off
	v_lshl_add_u64 v[164:165], s[20:21], 0, v[132:133]
	s_mov_b32 m0, s43
	s_nop 0
	global_load_lds_dwordx4 v[164:165], off
	s_waitcnt vmcnt(8)
	s_waitcnt lgkmcnt(0)
	s_barrier
	s_setprio 1
	s_waitcnt lgkmcnt(0)
	v_mfma_f32_16x16x32_bf16 v[126:129], v[144:147], v[210:213], v[126:129]
	v_mfma_f32_16x16x32_bf16 v[122:125], v[152:155], v[210:213], v[122:125]
	v_mfma_f32_16x16x32_bf16 v[110:113], v[144:147], v[218:221], v[110:113]
	v_mfma_f32_16x16x32_bf16 v[106:109], v[152:155], v[218:221], v[106:109]
	v_mfma_f32_16x16x32_bf16 v[94:97], v[144:147], v[226:229], v[94:97]
	v_mfma_f32_16x16x32_bf16 v[90:93], v[152:155], v[226:229], v[90:93]
	v_mfma_f32_16x16x32_bf16 v[78:81], v[144:147], v[234:237], v[78:81]
	v_mfma_f32_16x16x32_bf16 v[74:77], v[152:155], v[234:237], v[74:77]
	v_mfma_f32_16x16x32_bf16 v[126:129], v[148:151], v[214:217], v[126:129]
	v_mfma_f32_16x16x32_bf16 v[122:125], v[178:181], v[214:217], v[122:125]
	v_mfma_f32_16x16x32_bf16 v[110:113], v[148:151], v[222:225], v[110:113]
	v_mfma_f32_16x16x32_bf16 v[106:109], v[178:181], v[222:225], v[106:109]
	v_mfma_f32_16x16x32_bf16 v[94:97], v[148:151], v[230:233], v[94:97]
	v_mfma_f32_16x16x32_bf16 v[90:93], v[178:181], v[230:233], v[90:93]
	v_mfma_f32_16x16x32_bf16 v[78:81], v[148:151], v[238:241], v[78:81]
	v_mfma_f32_16x16x32_bf16 v[74:77], v[178:181], v[238:241], v[74:77]
	v_mfma_f32_16x16x32_bf16 v[118:121], v[182:185], v[210:213], v[118:121]
	v_mfma_f32_16x16x32_bf16 v[114:117], v[190:193], v[210:213], v[114:117]
	v_mfma_f32_16x16x32_bf16 v[102:105], v[182:185], v[218:221], v[102:105]
	v_mfma_f32_16x16x32_bf16 v[98:101], v[190:193], v[218:221], v[98:101]
	v_mfma_f32_16x16x32_bf16 v[86:89], v[182:185], v[226:229], v[86:89]
	v_mfma_f32_16x16x32_bf16 v[82:85], v[190:193], v[226:229], v[82:85]
	v_mfma_f32_16x16x32_bf16 v[70:73], v[182:185], v[234:237], v[70:73]
	v_mfma_f32_16x16x32_bf16 v[66:69], v[190:193], v[234:237], v[66:69]
	v_mfma_f32_16x16x32_bf16 v[118:121], v[186:189], v[214:217], v[118:121]
	v_mfma_f32_16x16x32_bf16 v[114:117], v[194:197], v[214:217], v[114:117]
	v_mfma_f32_16x16x32_bf16 v[102:105], v[186:189], v[222:225], v[102:105]
	v_mfma_f32_16x16x32_bf16 v[98:101], v[194:197], v[222:225], v[98:101]
	v_mfma_f32_16x16x32_bf16 v[86:89], v[186:189], v[230:233], v[86:89]
	v_mfma_f32_16x16x32_bf16 v[82:85], v[194:197], v[230:233], v[82:85]
	v_mfma_f32_16x16x32_bf16 v[70:73], v[186:189], v[238:241], v[70:73]
	v_mfma_f32_16x16x32_bf16 v[66:69], v[194:197], v[238:241], v[66:69]
	s_setprio 0
	s_barrier
; #define PG8_STAGE(bufoff, gbase, voff) do { _Pragma("unroll") for (int _i = 0; _i < 2; ++_i) \
;         __builtin_amdgcn_global_load_lds((const unsigned*)((const char*)(gbase) + (voff)[_i]), (LAS unsigned*)(lds + (bufoff) + ldsw + _i * 8192), 16, 0, 0); } while (0)
; #define PG8_LDA(dst, b, h) do { _Pragma("unroll") for (int m = 0; m < 4; ++m) _Pragma("unroll") for (int k = 0; k < 2; ++k) dst[m][k] = *(const LAS bf16x8*)(lds + PG8_SA(b, h) + aoff + m * 2048 + k * 1024); } while (0)
; #define PG8_MMA(ai, bj, At, Bt) do { __builtin_amdgcn_s_setprio(1); _Pragma("unroll") for (int m = 0; m < 4; ++m) _Pragma("unroll") for (int n = 0; n < 2; ++n) _Pragma("unroll") for (int k = 0; k < 2; ++k) \
;         acc[ai][bj][m][n] = __builtin_amdgcn_mfma_f32_16x16x32_bf16(Bt[n][k], At[m][k], acc[ai][bj][m][n], 0, 0, 0); __builtin_amdgcn_s_setprio(0); } while (0)
; #define PG8_WAIT_V(n) asm volatile("s_waitcnt vmcnt(" #n ")" ::: "memory")
; #define PG8_WAIT_L(n) asm volatile("s_waitcnt lgkmcnt(" #n ")" ::: "memory")
; #define PG8_BAR __builtin_amdgcn_s_barrier()
; #define PG8_SCHED __builtin_amdgcn_sched_barrier(0)
; template <class Epi>
; DI void gemm_phase(LAS unsigned char* lds, const Gemm g, const StaticOrder& S, const Epi& E, int wv0) {
;     ...
;             PG8_LDA(At, 1, 1); PG8_STAGE(PG8_SB(1, 0), b3, voffB); PG8_STAGE(PG8_SB(1, 1), b3 + hstepB, voffB); PG8_STAGE(PG8_SA(1, 0), a3, voffA);
;             PG8_WAIT_V(8); PG8_WAIT_L(0); PG8_BAR; PG8_MMA(1, 0, At, B0); PG8_MMA(1, 1, At, B1); PG8_BAR; PG8_SCHED;
;         }
	s_mov_b32 m0, s46
	v_lshl_add_u64 v[140:141], v[140:141], 0, s[86:87]
	s_add_u32 s18, s18, 0x40080
	ds_read_b128 v[210:213], v143 offset:49152
	ds_read_b128 v[214:217], v143 offset:50176
	ds_read_b128 v[218:221], v143 offset:51200
	ds_read_b128 v[222:225], v143 offset:52224
	ds_read_b128 v[226:229], v143 offset:53248
	ds_read_b128 v[230:233], v143 offset:54272
	ds_read_b128 v[234:237], v143 offset:55296
	ds_read_b128 v[238:241], v143 offset:56320
	global_load_lds_dwordx4 v[140:141], off
	v_lshl_add_u64 v[140:141], v[158:159], 0, s[86:87]
	s_mov_b32 m0, s47
	s_addc_u32 s19, s19, 0
	global_load_lds_dwordx4 v[140:141], off
	v_lshl_add_u64 v[140:141], s[18:19], 0, v[0:1]
	s_mov_b32 m0, s50
	s_nop 0
	global_load_lds_dwordx4 v[140:141], off
	v_lshl_add_u64 v[140:141], s[18:19], 0, v[130:131]
	s_mov_b32 m0, s51
	s_nop 0
	global_load_lds_dwordx4 v[140:141], off
	v_lshl_add_u64 v[140:141], v[160:161], 0, s[86:87]
	s_mov_b32 m0, s48
	s_nop 0
	global_load_lds_dwordx4 v[140:141], off
	v_lshl_add_u64 v[140:141], v[162:163], 0, s[86:87]
	s_mov_b32 m0, s49
	s_nop 0
	global_load_lds_dwordx4 v[140:141], off
	s_waitcnt vmcnt(8)
	s_waitcnt lgkmcnt(0)
	s_barrier
	s_setprio 1
	s_waitcnt lgkmcnt(0)
	v_mfma_f32_16x16x32_bf16 v[62:65], v[144:147], v[210:213], v[62:65]
	v_mfma_f32_16x16x32_bf16 v[58:61], v[152:155], v[210:213], v[58:61]
	v_mfma_f32_16x16x32_bf16 v[46:49], v[144:147], v[218:221], v[46:49]
	v_mfma_f32_16x16x32_bf16 v[42:45], v[152:155], v[218:221], v[42:45]
	v_mfma_f32_16x16x32_bf16 v[30:33], v[144:147], v[226:229], v[30:33]
	v_mfma_f32_16x16x32_bf16 v[26:29], v[152:155], v[226:229], v[26:29]
	v_mfma_f32_16x16x32_bf16 v[14:17], v[144:147], v[234:237], v[14:17]
	v_mfma_f32_16x16x32_bf16 v[10:13], v[152:155], v[234:237], v[10:13]
	v_mfma_f32_16x16x32_bf16 v[62:65], v[148:151], v[214:217], v[62:65]
	v_mfma_f32_16x16x32_bf16 v[58:61], v[178:181], v[214:217], v[58:61]
	v_mfma_f32_16x16x32_bf16 v[46:49], v[148:151], v[222:225], v[46:49]
	v_mfma_f32_16x16x32_bf16 v[42:45], v[178:181], v[222:225], v[42:45]
	v_mfma_f32_16x16x32_bf16 v[30:33], v[148:151], v[230:233], v[30:33]
	v_mfma_f32_16x16x32_bf16 v[26:29], v[178:181], v[230:233], v[26:29]
	v_mfma_f32_16x16x32_bf16 v[14:17], v[148:151], v[238:241], v[14:17]
	v_mfma_f32_16x16x32_bf16 v[10:13], v[178:181], v[238:241], v[10:13]
	v_mfma_f32_16x16x32_bf16 v[54:57], v[182:185], v[210:213], v[54:57]
	v_mfma_f32_16x16x32_bf16 v[50:53], v[190:193], v[210:213], v[50:53]
	v_mfma_f32_16x16x32_bf16 v[38:41], v[182:185], v[218:221], v[38:41]
	v_mfma_f32_16x16x32_bf16 v[34:37], v[190:193], v[218:221], v[34:37]
	v_mfma_f32_16x16x32_bf16 v[22:25], v[182:185], v[226:229], v[22:25]
	v_mfma_f32_16x16x32_bf16 v[18:21], v[190:193], v[226:229], v[18:21]
	v_mfma_f32_16x16x32_bf16 v[6:9], v[182:185], v[234:237], v[6:9]
	v_mfma_f32_16x16x32_bf16 v[2:5], v[190:193], v[234:237], v[2:5]
	v_mfma_f32_16x16x32_bf16 v[54:57], v[186:189], v[214:217], v[54:57]
	v_mfma_f32_16x16x32_bf16 v[50:53], v[194:197], v[214:217], v[50:53]
	v_mfma_f32_16x16x32_bf16 v[38:41], v[186:189], v[222:225], v[38:41]
	v_mfma_f32_16x16x32_bf16 v[34:37], v[194:197], v[222:225], v[34:37]
	v_mfma_f32_16x16x32_bf16 v[22:25], v[186:189], v[230:233], v[22:25]
	v_mfma_f32_16x16x32_bf16 v[18:21], v[194:197], v[230:233], v[18:21]
	v_mfma_f32_16x16x32_bf16 v[6:9], v[186:189], v[238:241], v[6:9]
	v_mfma_f32_16x16x32_bf16 v[2:5], v[194:197], v[238:241], v[2:5]
	s_setprio 0
	s_barrier
	s_add_i32 s57, s57, 2
	s_add_u32 s55, s55, 0x100
	s_addc_u32 s56, s56, 0
	s_add_u32 s16, s16, 0x100
	s_addc_u32 s17, s17, 0
	s_cmp_gt_u32 s57, 13
	s_cbranch_scc0 .LBB0_417
	s_and_b64 vcc, exec, s[6:7]
	s_cbranch_vccz .LBB0_420
	s_barrier

; #define PG8_STAGE(bufoff, gbase, voff) do { _Pragma("unroll") for (int _i = 0; _i < 2; ++_i) \
;         __builtin_amdgcn_global_load_lds((const unsigned*)((const char*)(gbase) + (voff)[_i]), (LAS unsigned*)(lds + (bufoff) + ldsw + _i * 8192), 16, 0, 0); } while (0)
; #define PG8_LDA(dst, b, h) do { _Pragma("unroll") for (int m = 0; m < 4; ++m) _Pragma("unroll") for (int k = 0; k < 2; ++k) dst[m][k] = *(const LAS bf16x8*)(lds + PG8_SA(b, h) + aoff + m * 2048 + k * 1024); } while (0)
; #define PG8_LDB(dst, b, h) do { _Pragma("unroll") for (int n = 0; n < 2; ++n) _Pragma("unroll") for (int k = 0; k < 2; ++k) dst[n][k] = *(const LAS bf16x8*)(lds + PG8_SB(b, h) + boff + n * 2048 + k * 1024); } while (0)
; #define PG8_MMA(ai, bj, At, Bt) do { __builtin_amdgcn_s_setprio(1); _Pragma("unroll") for (int m = 0; m < 4; ++m) _Pragma("unroll") for (int n = 0; n < 2; ++n) _Pragma("unroll") for (int k = 0; k < 2; ++k) \
;         acc[ai][bj][m][n] = __builtin_amdgcn_mfma_f32_16x16x32_bf16(Bt[n][k], At[m][k], acc[ai][bj][m][n], 0, 0, 0); __builtin_amdgcn_s_setprio(0); } while (0)
; #define PG8_WAIT_V(n) asm volatile("s_waitcnt vmcnt(" #n ")" ::: "memory")
; #define PG8_WAIT_L(n) asm volatile("s_waitcnt lgkmcnt(" #n ")" ::: "memory")
; #define PG8_BAR __builtin_amdgcn_s_barrier()
; #define PG8_SCHED __builtin_amdgcn_sched_barrier(0)
; template <class Epi>
; DI void gemm_phase(LAS unsigned char* lds, const Gemm g, const StaticOrder& S, const Epi& E, int wv0) {
;     ...
;             PG8_LDB(B0, 0, 0); PG8_LDB(B1, 0, 1); PG8_SCHED; PG8_LDA(At, 0, 0); PG8_STAGE(PG8_SA(1, 1), a1 + hstepA, voffA);
;             PG8_WAIT_V(8); PG8_WAIT_L(0); PG8_BAR; PG8_MMA(0, 0, At, B0); PG8_MMA(0, 1, At, B1); PG8_BAR; PG8_SCHED;
;             PG8_LDA(At, 0, 1); PG8_STAGE(PG8_SB(0, 0), b2, voffB); PG8_STAGE(PG8_SB(0, 1), b2 + hstepB, voffB); PG8_STAGE(PG8_SA(0, 0), a2, voffA);
;             PG8_WAIT_V(8); PG8_WAIT_L(0); PG8_BAR; PG8_MMA(1, 0, At, B0); PG8_MMA(1, 1, At, B1); PG8_BAR; PG8_SCHED;
.LBB0_485:
	v_add_u32_e32 v140, s66, v142
	ds_read_b128 v[136:139], v140
	ds_read_b128 v[144:147], v140 offset:1024
	ds_read_b128 v[148:151], v140 offset:2048
	ds_read_b128 v[152:155], v140 offset:3072
	v_add_u32_e32 v140, s67, v142
	ds_read_b128 v[178:181], v140
	ds_read_b128 v[182:185], v140 offset:1024
	ds_read_b128 v[186:189], v140 offset:2048
	ds_read_b128 v[190:193], v140 offset:3072
	s_add_u32 s12, s0, 0x100
	s_addc_u32 s13, s1, 0
	s_cmp_eq_u32 s51, 40
	s_cselect_b32 s17, s5, s13
	s_cselect_b32 s16, s4, s12
	s_cselect_b32 s15, s11, s50
	s_cselect_b32 s14, s10, s49
	v_lshl_add_u64 v[140:141], s[0:1], 0, v[134:135]
	s_add_i32 m0, s24, 0xc000
	ds_read_b128 v[194:197], v143
	ds_read_b128 v[210:213], v143 offset:1024
	ds_read_b128 v[214:217], v143 offset:2048
	ds_read_b128 v[218:221], v143 offset:3072
	ds_read_b128 v[222:225], v143 offset:4096
	ds_read_b128 v[226:229], v143 offset:5120
	ds_read_b128 v[230:233], v143 offset:6144
	ds_read_b128 v[234:237], v143 offset:7168
	global_load_lds_dwordx4 v[140:141], off
	v_lshl_add_u64 v[140:141], s[0:1], 0, v[132:133]
	s_add_i32 m0, s24, 0xe000
	s_nop 0
	global_load_lds_dwordx4 v[140:141], off
	s_waitcnt vmcnt(8)
	s_waitcnt lgkmcnt(0)
	s_barrier
	s_setprio 1
	s_waitcnt lgkmcnt(0)
	v_mfma_f32_16x16x32_bf16 v[126:129], v[136:139], v[194:197], v[126:129]
	v_mfma_f32_16x16x32_bf16 v[122:125], v[148:151], v[194:197], v[122:125]
	v_mfma_f32_16x16x32_bf16 v[110:113], v[136:139], v[214:217], v[110:113]
	v_mfma_f32_16x16x32_bf16 v[106:109], v[148:151], v[214:217], v[106:109]
	v_mfma_f32_16x16x32_bf16 v[94:97], v[136:139], v[222:225], v[94:97]
	v_mfma_f32_16x16x32_bf16 v[90:93], v[148:151], v[222:225], v[90:93]
	v_mfma_f32_16x16x32_bf16 v[78:81], v[136:139], v[230:233], v[78:81]
	v_mfma_f32_16x16x32_bf16 v[74:77], v[148:151], v[230:233], v[74:77]
	v_mfma_f32_16x16x32_bf16 v[126:129], v[144:147], v[210:213], v[126:129]
	v_mfma_f32_16x16x32_bf16 v[122:125], v[152:155], v[210:213], v[122:125]
	v_mfma_f32_16x16x32_bf16 v[110:113], v[144:147], v[218:221], v[110:113]
	v_mfma_f32_16x16x32_bf16 v[106:109], v[152:155], v[218:221], v[106:109]
	v_mfma_f32_16x16x32_bf16 v[94:97], v[144:147], v[226:229], v[94:97]
	v_mfma_f32_16x16x32_bf16 v[90:93], v[152:155], v[226:229], v[90:93]
	v_mfma_f32_16x16x32_bf16 v[78:81], v[144:147], v[234:237], v[78:81]
	v_mfma_f32_16x16x32_bf16 v[74:77], v[152:155], v[234:237], v[74:77]
	v_mfma_f32_16x16x32_bf16 v[118:121], v[178:181], v[194:197], v[118:121]
	v_mfma_f32_16x16x32_bf16 v[114:117], v[186:189], v[194:197], v[114:117]
	v_mfma_f32_16x16x32_bf16 v[102:105], v[178:181], v[214:217], v[102:105]
	v_mfma_f32_16x16x32_bf16 v[98:101], v[186:189], v[214:217], v[98:101]
	v_mfma_f32_16x16x32_bf16 v[86:89], v[178:181], v[222:225], v[86:89]
	v_mfma_f32_16x16x32_bf16 v[82:85], v[186:189], v[222:225], v[82:85]
	v_mfma_f32_16x16x32_bf16 v[70:73], v[178:181], v[230:233], v[70:73]
	v_mfma_f32_16x16x32_bf16 v[66:69], v[186:189], v[230:233], v[66:69]
	v_mfma_f32_16x16x32_bf16 v[118:121], v[182:185], v[210:213], v[118:121]
	v_mfma_f32_16x16x32_bf16 v[114:117], v[190:193], v[210:213], v[114:117]
	v_mfma_f32_16x16x32_bf16 v[102:105], v[182:185], v[218:221], v[102:105]
	v_mfma_f32_16x16x32_bf16 v[98:101], v[190:193], v[218:221], v[98:101]
	v_mfma_f32_16x16x32_bf16 v[86:89], v[182:185], v[226:229], v[86:89]
	v_mfma_f32_16x16x32_bf16 v[82:85], v[190:193], v[226:229], v[82:85]
	v_mfma_f32_16x16x32_bf16 v[70:73], v[182:185], v[234:237], v[70:73]
	v_mfma_f32_16x16x32_bf16 v[66:69], v[190:193], v[234:237], v[66:69]
	s_setprio 0
	s_barrier
	s_mov_b32 m0, s20
	v_lshl_add_u64 v[140:141], s[14:15], 0, v[0:1]
	s_add_u32 s0, s14, 0xb0000
	ds_read_b128 v[194:197], v143 offset:16384
	ds_read_b128 v[210:213], v143 offset:17408
	ds_read_b128 v[214:217], v143 offset:18432
	ds_read_b128 v[218:221], v143 offset:19456
	ds_read_b128 v[222:225], v143 offset:20480
	ds_read_b128 v[226:229], v143 offset:21504
	ds_read_b128 v[230:233], v143 offset:22528
	ds_read_b128 v[234:237], v143 offset:23552
	global_load_lds_dwordx4 v[140:141], off
	v_lshl_add_u64 v[158:159], s[14:15], 0, v[130:131]
	s_mov_b32 m0, s21
	s_addc_u32 s1, s15, 0
	global_load_lds_dwordx4 v[158:159], off
	v_lshl_add_u64 v[160:161], s[0:1], 0, v[0:1]
	s_mov_b32 m0, s22
	v_lshl_add_u64 v[162:163], s[16:17], 0, v[130:131]
	global_load_lds_dwordx4 v[160:161], off
	v_lshl_add_u64 v[160:161], s[0:1], 0, v[130:131]
	s_mov_b32 m0, s23
	s_nop 0
	global_load_lds_dwordx4 v[160:161], off
	v_lshl_add_u64 v[160:161], s[16:17], 0, v[0:1]
	s_mov_b32 m0, s24
	s_nop 0
	global_load_lds_dwordx4 v[160:161], off
	s_mov_b32 m0, s25
	s_nop 0
	global_load_lds_dwordx4 v[162:163], off
	s_waitcnt vmcnt(8)
	s_waitcnt lgkmcnt(0)
	s_barrier
; #define PG8_STAGE(bufoff, gbase, voff) do { _Pragma("unroll") for (int _i = 0; _i < 2; ++_i) \
;         __builtin_amdgcn_global_load_lds((const unsigned*)((const char*)(gbase) + (voff)[_i]), (LAS unsigned*)(lds + (bufoff) + ldsw + _i * 8192), 16, 0, 0); } while (0)
; #define PG8_LDA(dst, b, h) do { _Pragma("unroll") for (int m = 0; m < 4; ++m) _Pragma("unroll") for (int k = 0; k < 2; ++k) dst[m][k] = *(const LAS bf16x8*)(lds + PG8_SA(b, h) + aoff + m * 2048 + k * 1024); } while (0)
; #define PG8_LDB(dst, b, h) do { _Pragma("unroll") for (int n = 0; n < 2; ++n) _Pragma("unroll") for (int k = 0; k < 2; ++k) dst[n][k] = *(const LAS bf16x8*)(lds + PG8_SB(b, h) + boff + n * 2048 + k * 1024); } while (0)
; #define PG8_MMA(ai, bj, At, Bt) do { __builtin_amdgcn_s_setprio(1); _Pragma("unroll") for (int m = 0; m < 4; ++m) _Pragma("unroll") for (int n = 0; n < 2; ++n) _Pragma("unroll") for (int k = 0; k < 2; ++k) \
;         acc[ai][bj][m][n] = __builtin_amdgcn_mfma_f32_16x16x32_bf16(Bt[n][k], At[m][k], acc[ai][bj][m][n], 0, 0, 0); __builtin_amdgcn_s_setprio(0); } while (0)
; #define PG8_WAIT_V(n) asm volatile("s_waitcnt vmcnt(" #n ")" ::: "memory")
; #define PG8_WAIT_L(n) asm volatile("s_waitcnt lgkmcnt(" #n ")" ::: "memory")
; #define PG8_BAR __builtin_amdgcn_s_barrier()
; #define PG8_SCHED __builtin_amdgcn_sched_barrier(0)
; template <class Epi>
; DI void gemm_phase(LAS unsigned char* lds, const Gemm g, const StaticOrder& S, const Epi& E, int wv0) {
;     ...
;             PG8_WAIT_V(8); PG8_WAIT_L(0); PG8_BAR; PG8_MMA(1, 0, At, B0); PG8_MMA(1, 1, At, B1); PG8_BAR; PG8_SCHED;
;             PG8_LDB(B0, 1, 0); PG8_LDB(B1, 1, 1); PG8_SCHED; PG8_LDA(At, 1, 0); PG8_STAGE(PG8_SA(0, 1), a2 + hstepA, voffA);
;             PG8_WAIT_V(8); PG8_WAIT_L(0); PG8_BAR; PG8_MMA(0, 0, At, B0); PG8_MMA(0, 1, At, B1); PG8_BAR; PG8_SCHED;
;             PG8_LDA(At, 1, 1); PG8_STAGE(PG8_SB(1, 0), b3, voffB); PG8_STAGE(PG8_SB(1, 1), b3 + hstepB, voffB); PG8_STAGE(PG8_SA(1, 0), a3, voffA);
	s_setprio 1
	s_waitcnt lgkmcnt(0)
	v_mfma_f32_16x16x32_bf16 v[62:65], v[136:139], v[194:197], v[62:65]
	v_mfma_f32_16x16x32_bf16 v[58:61], v[148:151], v[194:197], v[58:61]
	v_mfma_f32_16x16x32_bf16 v[46:49], v[136:139], v[214:217], v[46:49]
	v_mfma_f32_16x16x32_bf16 v[42:45], v[148:151], v[214:217], v[42:45]
	v_mfma_f32_16x16x32_bf16 v[30:33], v[136:139], v[222:225], v[30:33]
	v_mfma_f32_16x16x32_bf16 v[26:29], v[148:151], v[222:225], v[26:29]
	v_mfma_f32_16x16x32_bf16 v[14:17], v[136:139], v[230:233], v[14:17]
	v_mfma_f32_16x16x32_bf16 v[10:13], v[148:151], v[230:233], v[10:13]
	v_mfma_f32_16x16x32_bf16 v[62:65], v[144:147], v[210:213], v[62:65]
	v_mfma_f32_16x16x32_bf16 v[58:61], v[152:155], v[210:213], v[58:61]
	v_mfma_f32_16x16x32_bf16 v[46:49], v[144:147], v[218:221], v[46:49]
	v_mfma_f32_16x16x32_bf16 v[42:45], v[152:155], v[218:221], v[42:45]
	v_mfma_f32_16x16x32_bf16 v[30:33], v[144:147], v[226:229], v[30:33]
	v_mfma_f32_16x16x32_bf16 v[26:29], v[152:155], v[226:229], v[26:29]
	v_mfma_f32_16x16x32_bf16 v[14:17], v[144:147], v[234:237], v[14:17]
	v_mfma_f32_16x16x32_bf16 v[10:13], v[152:155], v[234:237], v[10:13]
	v_mfma_f32_16x16x32_bf16 v[54:57], v[178:181], v[194:197], v[54:57]
	v_mfma_f32_16x16x32_bf16 v[50:53], v[186:189], v[194:197], v[50:53]
	v_mfma_f32_16x16x32_bf16 v[38:41], v[178:181], v[214:217], v[38:41]
	v_mfma_f32_16x16x32_bf16 v[34:37], v[186:189], v[214:217], v[34:37]
	v_mfma_f32_16x16x32_bf16 v[22:25], v[178:181], v[222:225], v[22:25]
	v_mfma_f32_16x16x32_bf16 v[18:21], v[186:189], v[222:225], v[18:21]
	v_mfma_f32_16x16x32_bf16 v[6:9], v[178:181], v[230:233], v[6:9]
	v_mfma_f32_16x16x32_bf16 v[2:5], v[186:189], v[230:233], v[2:5]
	v_mfma_f32_16x16x32_bf16 v[54:57], v[182:185], v[210:213], v[54:57]
	v_mfma_f32_16x16x32_bf16 v[50:53], v[190:193], v[210:213], v[50:53]
	v_mfma_f32_16x16x32_bf16 v[38:41], v[182:185], v[218:221], v[38:41]
	v_mfma_f32_16x16x32_bf16 v[34:37], v[190:193], v[218:221], v[34:37]
	v_mfma_f32_16x16x32_bf16 v[22:25], v[182:185], v[226:229], v[22:25]
	v_mfma_f32_16x16x32_bf16 v[18:21], v[190:193], v[226:229], v[18:21]
	v_mfma_f32_16x16x32_bf16 v[6:9], v[182:185], v[234:237], v[6:9]
	v_mfma_f32_16x16x32_bf16 v[2:5], v[190:193], v[234:237], v[2:5]
	s_setprio 0
	s_barrier
	v_add_u32_e32 v152, s68, v142
	v_add_u32_e32 v164, s69, v142
	ds_read_b128 v[136:139], v152
	ds_read_b128 v[144:147], v152 offset:1024
	ds_read_b128 v[148:151], v152 offset:2048
	ds_read_b128 v[152:155], v152 offset:3072
	ds_read_b128 v[178:181], v164
	ds_read_b128 v[182:185], v164 offset:1024
	ds_read_b128 v[186:189], v164 offset:2048
	ds_read_b128 v[190:193], v164 offset:3072
	s_add_u32 s0, s16, 0xb0000
	s_addc_u32 s1, s17, 0
	s_mov_b32 m0, s26
	v_lshl_add_u64 v[164:165], s[0:1], 0, v[0:1]
	ds_read_b128 v[194:197], v143 offset:32768
	ds_read_b128 v[210:213], v143 offset:33792
	ds_read_b128 v[214:217], v143 offset:34816
	ds_read_b128 v[218:221], v143 offset:35840
	ds_read_b128 v[222:225], v143 offset:36864
	ds_read_b128 v[226:229], v143 offset:37888
	ds_read_b128 v[230:233], v143 offset:38912
	ds_read_b128 v[234:237], v143 offset:39936
	global_load_lds_dwordx4 v[164:165], off
	v_lshl_add_u64 v[164:165], s[0:1], 0, v[130:131]
	s_mov_b32 m0, s27
	s_nop 0
	global_load_lds_dwordx4 v[164:165], off
	s_waitcnt vmcnt(8)
	s_waitcnt lgkmcnt(0)
	s_barrier
	s_setprio 1
	s_waitcnt lgkmcnt(0)
	v_mfma_f32_16x16x32_bf16 v[126:129], v[136:139], v[194:197], v[126:129]
	v_mfma_f32_16x16x32_bf16 v[122:125], v[148:151], v[194:197], v[122:125]
	v_mfma_f32_16x16x32_bf16 v[110:113], v[136:139], v[214:217], v[110:113]
	v_mfma_f32_16x16x32_bf16 v[106:109], v[148:151], v[214:217], v[106:109]
	v_mfma_f32_16x16x32_bf16 v[94:97], v[136:139], v[222:225], v[94:97]
	v_mfma_f32_16x16x32_bf16 v[90:93], v[148:151], v[222:225], v[90:93]
	v_mfma_f32_16x16x32_bf16 v[78:81], v[136:139], v[230:233], v[78:81]
	v_mfma_f32_16x16x32_bf16 v[74:77], v[148:151], v[230:233], v[74:77]
	v_mfma_f32_16x16x32_bf16 v[126:129], v[144:147], v[210:213], v[126:129]
	v_mfma_f32_16x16x32_bf16 v[122:125], v[152:155], v[210:213], v[122:125]
	v_mfma_f32_16x16x32_bf16 v[110:113], v[144:147], v[218:221], v[110:113]
	v_mfma_f32_16x16x32_bf16 v[106:109], v[152:155], v[218:221], v[106:109]
	v_mfma_f32_16x16x32_bf16 v[94:97], v[144:147], v[226:229], v[94:97]
	v_mfma_f32_16x16x32_bf16 v[90:93], v[152:155], v[226:229], v[90:93]
	v_mfma_f32_16x16x32_bf16 v[78:81], v[144:147], v[234:237], v[78:81]
	v_mfma_f32_16x16x32_bf16 v[74:77], v[152:155], v[234:237], v[74:77]
	v_mfma_f32_16x16x32_bf16 v[118:121], v[178:181], v[194:197], v[118:121]
	v_mfma_f32_16x16x32_bf16 v[114:117], v[186:189], v[194:197], v[114:117]
	v_mfma_f32_16x16x32_bf16 v[102:105], v[178:181], v[214:217], v[102:105]
	v_mfma_f32_16x16x32_bf16 v[98:101], v[186:189], v[214:217], v[98:101]
	v_mfma_f32_16x16x32_bf16 v[86:89], v[178:181], v[222:225], v[86:89]
	v_mfma_f32_16x16x32_bf16 v[82:85], v[186:189], v[222:225], v[82:85]
	v_mfma_f32_16x16x32_bf16 v[70:73], v[178:181], v[230:233], v[70:73]
	v_mfma_f32_16x16x32_bf16 v[66:69], v[186:189], v[230:233], v[66:69]
	v_mfma_f32_16x16x32_bf16 v[118:121], v[182:185], v[210:213], v[118:121]
	v_mfma_f32_16x16x32_bf16 v[114:117], v[190:193], v[210:213], v[114:117]
	v_mfma_f32_16x16x32_bf16 v[102:105], v[182:185], v[218:221], v[102:105]
	v_mfma_f32_16x16x32_bf16 v[98:101], v[190:193], v[218:221], v[98:101]
	v_mfma_f32_16x16x32_bf16 v[86:89], v[182:185], v[226:229], v[86:89]
	v_mfma_f32_16x16x32_bf16 v[82:85], v[190:193], v[226:229], v[82:85]
	v_mfma_f32_16x16x32_bf16 v[70:73], v[182:185], v[234:237], v[70:73]
	v_mfma_f32_16x16x32_bf16 v[66:69], v[190:193], v[234:237], v[66:69]
	s_setprio 0
	s_barrier
; #define PG8_STAGE(bufoff, gbase, voff) do { _Pragma("unroll") for (int _i = 0; _i < 2; ++_i) \
;         __builtin_amdgcn_global_load_lds((const unsigned*)((const char*)(gbase) + (voff)[_i]), (LAS unsigned*)(lds + (bufoff) + ldsw + _i * 8192), 16, 0, 0); } while (0)
; #define PG8_LDA(dst, b, h) do { _Pragma("unroll") for (int m = 0; m < 4; ++m) _Pragma("unroll") for (int k = 0; k < 2; ++k) dst[m][k] = *(const LAS bf16x8*)(lds + PG8_SA(b, h) + aoff + m * 2048 + k * 1024); } while (0)
; #define PG8_MMA(ai, bj, At, Bt) do { __builtin_amdgcn_s_setprio(1); _Pragma("unroll") for (int m = 0; m < 4; ++m) _Pragma("unroll") for (int n = 0; n < 2; ++n) _Pragma("unroll") for (int k = 0; k < 2; ++k) \
;         acc[ai][bj][m][n] = __builtin_amdgcn_mfma_f32_16x16x32_bf16(Bt[n][k], At[m][k], acc[ai][bj][m][n], 0, 0, 0); __builtin_amdgcn_s_setprio(0); } while (0)
; #define PG8_WAIT_V(n) asm volatile("s_waitcnt vmcnt(" #n ")" ::: "memory")
; #define PG8_WAIT_L(n) asm volatile("s_waitcnt lgkmcnt(" #n ")" ::: "memory")
; #define PG8_BAR __builtin_amdgcn_s_barrier()
; #define PG8_SCHED __builtin_amdgcn_sched_barrier(0)
; template <class Epi>
; DI void gemm_phase(LAS unsigned char* lds, const Gemm g, const StaticOrder& S, const Epi& E, int wv0) {
;     ...
;             PG8_LDA(At, 1, 1); PG8_STAGE(PG8_SB(1, 0), b3, voffB); PG8_STAGE(PG8_SB(1, 1), b3 + hstepB, voffB); PG8_STAGE(PG8_SA(1, 0), a3, voffA);
;             PG8_WAIT_V(8); PG8_WAIT_L(0); PG8_BAR; PG8_MMA(1, 0, At, B0); PG8_MMA(1, 1, At, B1); PG8_BAR; PG8_SCHED;
;         }
	s_mov_b32 m0, s30
	v_lshl_add_u64 v[140:141], v[140:141], 0, s[86:87]
	s_add_u32 s0, s14, 0xb0080
	ds_read_b128 v[194:197], v143 offset:49152
	ds_read_b128 v[210:213], v143 offset:50176
	ds_read_b128 v[214:217], v143 offset:51200
	ds_read_b128 v[218:221], v143 offset:52224
	ds_read_b128 v[222:225], v143 offset:53248
	ds_read_b128 v[226:229], v143 offset:54272
	ds_read_b128 v[230:233], v143 offset:55296
	ds_read_b128 v[234:237], v143 offset:56320
	global_load_lds_dwordx4 v[140:141], off
	v_lshl_add_u64 v[140:141], v[158:159], 0, s[86:87]
	s_mov_b32 m0, s31
	s_addc_u32 s1, s15, 0
	global_load_lds_dwordx4 v[140:141], off
	v_lshl_add_u64 v[140:141], s[0:1], 0, v[0:1]
	s_mov_b32 m0, s42
	s_nop 0
	global_load_lds_dwordx4 v[140:141], off
	v_lshl_add_u64 v[140:141], s[0:1], 0, v[130:131]
	s_mov_b32 m0, s43
	s_nop 0
	global_load_lds_dwordx4 v[140:141], off
	v_lshl_add_u64 v[140:141], v[160:161], 0, s[86:87]
	s_mov_b32 m0, s40
	s_nop 0
	global_load_lds_dwordx4 v[140:141], off
	v_lshl_add_u64 v[140:141], v[162:163], 0, s[86:87]
	s_mov_b32 m0, s41
	s_nop 0
	global_load_lds_dwordx4 v[140:141], off
	s_waitcnt vmcnt(8)
	s_waitcnt lgkmcnt(0)
	s_barrier
	s_setprio 1
	s_waitcnt lgkmcnt(0)
	v_mfma_f32_16x16x32_bf16 v[62:65], v[136:139], v[194:197], v[62:65]
	v_mfma_f32_16x16x32_bf16 v[58:61], v[148:151], v[194:197], v[58:61]
	v_mfma_f32_16x16x32_bf16 v[46:49], v[136:139], v[214:217], v[46:49]
	v_mfma_f32_16x16x32_bf16 v[42:45], v[148:151], v[214:217], v[42:45]
	v_mfma_f32_16x16x32_bf16 v[30:33], v[136:139], v[222:225], v[30:33]
	v_mfma_f32_16x16x32_bf16 v[26:29], v[148:151], v[222:225], v[26:29]
	v_mfma_f32_16x16x32_bf16 v[14:17], v[136:139], v[230:233], v[14:17]
	v_mfma_f32_16x16x32_bf16 v[10:13], v[148:151], v[230:233], v[10:13]
	v_mfma_f32_16x16x32_bf16 v[62:65], v[144:147], v[210:213], v[62:65]
	v_mfma_f32_16x16x32_bf16 v[58:61], v[152:155], v[210:213], v[58:61]
	v_mfma_f32_16x16x32_bf16 v[46:49], v[144:147], v[218:221], v[46:49]
	v_mfma_f32_16x16x32_bf16 v[42:45], v[152:155], v[218:221], v[42:45]
	v_mfma_f32_16x16x32_bf16 v[30:33], v[144:147], v[226:229], v[30:33]
	v_mfma_f32_16x16x32_bf16 v[26:29], v[152:155], v[226:229], v[26:29]
	v_mfma_f32_16x16x32_bf16 v[14:17], v[144:147], v[234:237], v[14:17]
	v_mfma_f32_16x16x32_bf16 v[10:13], v[152:155], v[234:237], v[10:13]
	v_mfma_f32_16x16x32_bf16 v[54:57], v[178:181], v[194:197], v[54:57]
	v_mfma_f32_16x16x32_bf16 v[50:53], v[186:189], v[194:197], v[50:53]
	v_mfma_f32_16x16x32_bf16 v[38:41], v[178:181], v[214:217], v[38:41]
	v_mfma_f32_16x16x32_bf16 v[34:37], v[186:189], v[214:217], v[34:37]
	v_mfma_f32_16x16x32_bf16 v[22:25], v[178:181], v[222:225], v[22:25]
	v_mfma_f32_16x16x32_bf16 v[18:21], v[186:189], v[222:225], v[18:21]
	v_mfma_f32_16x16x32_bf16 v[6:9], v[178:181], v[230:233], v[6:9]
	v_mfma_f32_16x16x32_bf16 v[2:5], v[186:189], v[230:233], v[2:5]
	v_mfma_f32_16x16x32_bf16 v[54:57], v[182:185], v[210:213], v[54:57]
	v_mfma_f32_16x16x32_bf16 v[50:53], v[190:193], v[210:213], v[50:53]
	v_mfma_f32_16x16x32_bf16 v[38:41], v[182:185], v[218:221], v[38:41]
	v_mfma_f32_16x16x32_bf16 v[34:37], v[190:193], v[218:221], v[34:37]
	v_mfma_f32_16x16x32_bf16 v[22:25], v[182:185], v[226:229], v[22:25]
	v_mfma_f32_16x16x32_bf16 v[18:21], v[190:193], v[226:229], v[18:21]
	v_mfma_f32_16x16x32_bf16 v[6:9], v[182:185], v[234:237], v[6:9]
	v_mfma_f32_16x16x32_bf16 v[2:5], v[190:193], v[234:237], v[2:5]
	s_setprio 0
	s_barrier
	s_add_i32 s51, s51, 2
	s_add_u32 s49, s49, 0x100
	s_addc_u32 s50, s50, 0
	s_cmp_gt_u32 s51, 41
	s_mov_b64 s[0:1], s[12:13]
	s_cbranch_scc0 .LBB0_485
	s_and_b64 vcc, exec, s[8:9]
	s_cbranch_vccz .LBB0_488
	s_barrier

; #define PG8_STAGE(bufoff, gbase, voff) do { _Pragma("unroll") for (int _i = 0; _i < 2; ++_i) \
;         __builtin_amdgcn_global_load_lds((const unsigned*)((const char*)(gbase) + (voff)[_i]), (LAS unsigned*)(lds + (bufoff) + ldsw + _i * 8192), 16, 0, 0); } while (0)
; #define PG8_LDA(dst, b, h) do { _Pragma("unroll") for (int m = 0; m < 4; ++m) _Pragma("unroll") for (int k = 0; k < 2; ++k) dst[m][k] = *(const LAS bf16x8*)(lds + PG8_SA(b, h) + aoff + m * 2048 + k * 1024); } while (0)
; #define PG8_LDB(dst, b, h) do { _Pragma("unroll") for (int n = 0; n < 2; ++n) _Pragma("unroll") for (int k = 0; k < 2; ++k) dst[n][k] = *(const LAS bf16x8*)(lds + PG8_SB(b, h) + boff + n * 2048 + k * 1024); } while (0)
; #define PG8_MMA(ai, bj, At, Bt) do { __builtin_amdgcn_s_setprio(1); _Pragma("unroll") for (int m = 0; m < 4; ++m) _Pragma("unroll") for (int n = 0; n < 2; ++n) _Pragma("unroll") for (int k = 0; k < 2; ++k) \
;         acc[ai][bj][m][n] = __builtin_amdgcn_mfma_f32_16x16x32_bf16(Bt[n][k], At[m][k], acc[ai][bj][m][n], 0, 0, 0); __builtin_amdgcn_s_setprio(0); } while (0)
; #define PG8_WAIT_V(n) asm volatile("s_waitcnt vmcnt(" #n ")" ::: "memory")
; #define PG8_WAIT_L(n) asm volatile("s_waitcnt lgkmcnt(" #n ")" ::: "memory")
; #define PG8_BAR __builtin_amdgcn_s_barrier()
; #define PG8_SCHED __builtin_amdgcn_sched_barrier(0)
; template <class Epi>
; DI void gemm_phase(LAS unsigned char* lds, const Gemm g, const StaticOrder& S, const Epi& E, int wv0) {
;     ...
;             PG8_LDB(B0, 0, 0); PG8_LDB(B1, 0, 1); PG8_SCHED; PG8_LDA(At, 0, 0); PG8_STAGE(PG8_SA(1, 1), a1 + hstepA, voffA);
;             PG8_WAIT_V(8); PG8_WAIT_L(0); PG8_BAR; PG8_MMA(0, 0, At, B0); PG8_MMA(0, 1, At, B1); PG8_BAR; PG8_SCHED;
;             PG8_LDA(At, 0, 1); PG8_STAGE(PG8_SB(0, 0), b2, voffB); PG8_STAGE(PG8_SB(0, 1), b2 + hstepB, voffB); PG8_STAGE(PG8_SA(0, 0), a2, voffA);
;             PG8_WAIT_V(8); PG8_WAIT_L(0); PG8_BAR; PG8_MMA(1, 0, At, B0); PG8_MMA(1, 1, At, B1); PG8_BAR; PG8_SCHED;
.LBB0_601:
	v_add_u32_e32 v154, s34, v144
	ds_read_b128 v[140:143], v154
	ds_read_b128 v[146:149], v154 offset:1024
	ds_read_b128 v[150:153], v154 offset:2048
	ds_read_b128 v[178:181], v154 offset:3072
	v_add_u32_e32 v154, s37, v144
	ds_read_b128 v[182:185], v154
	ds_read_b128 v[186:189], v154 offset:1024
	ds_read_b128 v[190:193], v154 offset:2048
	ds_read_b128 v[194:197], v154 offset:3072
	s_add_u32 s22, s20, 0xfffc0080
	s_addc_u32 s23, s21, -1
	s_cmp_eq_u32 s59, 12
	s_cselect_b32 s25, s5, s23
	s_cselect_b32 s24, s11, s22
	s_cselect_b32 s23, s13, s58
	s_cselect_b32 s22, s15, s57
	v_lshl_add_u64 v[154:155], s[20:21], 0, v[138:139]
	s_add_i32 m0, s40, 0xc000
	ds_read_b128 v[210:213], v145
	ds_read_b128 v[214:217], v145 offset:1024
	ds_read_b128 v[218:221], v145 offset:2048
	ds_read_b128 v[222:225], v145 offset:3072
	ds_read_b128 v[226:229], v145 offset:4096
	ds_read_b128 v[230:233], v145 offset:5120
	ds_read_b128 v[234:237], v145 offset:6144
	ds_read_b128 v[238:241], v145 offset:7168
	global_load_lds_dwordx4 v[154:155], off
	v_lshl_add_u64 v[154:155], s[20:21], 0, v[136:137]
	s_add_i32 m0, s40, 0xe000
	s_nop 0
	global_load_lds_dwordx4 v[154:155], off
	s_waitcnt vmcnt(8)
	s_waitcnt lgkmcnt(0)
	s_barrier
	s_setprio 1
	s_waitcnt lgkmcnt(0)
	v_mfma_f32_16x16x32_bf16 v[126:129], v[140:143], v[210:213], v[126:129]
	v_mfma_f32_16x16x32_bf16 v[122:125], v[150:153], v[210:213], v[122:125]
	v_mfma_f32_16x16x32_bf16 v[118:121], v[140:143], v[218:221], v[118:121]
	v_mfma_f32_16x16x32_bf16 v[110:113], v[150:153], v[218:221], v[110:113]
	v_mfma_f32_16x16x32_bf16 v[102:105], v[140:143], v[226:229], v[102:105]
	v_mfma_f32_16x16x32_bf16 v[94:97], v[150:153], v[226:229], v[94:97]
	v_mfma_f32_16x16x32_bf16 v[86:89], v[140:143], v[234:237], v[86:89]
	v_mfma_f32_16x16x32_bf16 v[78:81], v[150:153], v[234:237], v[78:81]
	v_mfma_f32_16x16x32_bf16 v[126:129], v[146:149], v[214:217], v[126:129]
	v_mfma_f32_16x16x32_bf16 v[122:125], v[178:181], v[214:217], v[122:125]
	v_mfma_f32_16x16x32_bf16 v[118:121], v[146:149], v[222:225], v[118:121]
	v_mfma_f32_16x16x32_bf16 v[110:113], v[178:181], v[222:225], v[110:113]
	v_mfma_f32_16x16x32_bf16 v[102:105], v[146:149], v[230:233], v[102:105]
	v_mfma_f32_16x16x32_bf16 v[94:97], v[178:181], v[230:233], v[94:97]
	v_mfma_f32_16x16x32_bf16 v[86:89], v[146:149], v[238:241], v[86:89]
	v_mfma_f32_16x16x32_bf16 v[78:81], v[178:181], v[238:241], v[78:81]
	v_mfma_f32_16x16x32_bf16 v[114:117], v[182:185], v[210:213], v[114:117]
	v_mfma_f32_16x16x32_bf16 v[106:109], v[190:193], v[210:213], v[106:109]
	v_mfma_f32_16x16x32_bf16 v[98:101], v[182:185], v[218:221], v[98:101]
	v_mfma_f32_16x16x32_bf16 v[90:93], v[190:193], v[218:221], v[90:93]
	v_mfma_f32_16x16x32_bf16 v[82:85], v[182:185], v[226:229], v[82:85]
	v_mfma_f32_16x16x32_bf16 v[74:77], v[190:193], v[226:229], v[74:77]
	v_mfma_f32_16x16x32_bf16 v[70:73], v[182:185], v[234:237], v[70:73]
	v_mfma_f32_16x16x32_bf16 v[66:69], v[190:193], v[234:237], v[66:69]
	v_mfma_f32_16x16x32_bf16 v[114:117], v[186:189], v[214:217], v[114:117]
	v_mfma_f32_16x16x32_bf16 v[106:109], v[194:197], v[214:217], v[106:109]
	v_mfma_f32_16x16x32_bf16 v[98:101], v[186:189], v[222:225], v[98:101]
	v_mfma_f32_16x16x32_bf16 v[90:93], v[194:197], v[222:225], v[90:93]
	v_mfma_f32_16x16x32_bf16 v[82:85], v[186:189], v[230:233], v[82:85]
	v_mfma_f32_16x16x32_bf16 v[74:77], v[194:197], v[230:233], v[74:77]
	v_mfma_f32_16x16x32_bf16 v[70:73], v[186:189], v[238:241], v[70:73]
	v_mfma_f32_16x16x32_bf16 v[66:69], v[194:197], v[238:241], v[66:69]
	s_setprio 0
	s_barrier
	s_mov_b32 m0, s35
	v_lshl_add_u64 v[154:155], s[22:23], 0, v[0:1]
	s_add_u32 s60, s22, 0x40000
	ds_read_b128 v[210:213], v145 offset:16384
	ds_read_b128 v[214:217], v145 offset:17408
	ds_read_b128 v[218:221], v145 offset:18432
	ds_read_b128 v[222:225], v145 offset:19456
	ds_read_b128 v[226:229], v145 offset:20480
	ds_read_b128 v[230:233], v145 offset:21504
	ds_read_b128 v[234:237], v145 offset:22528
	ds_read_b128 v[238:241], v145 offset:23552
	global_load_lds_dwordx4 v[154:155], off
	v_lshl_add_u64 v[158:159], s[22:23], 0, v[134:135]
	s_mov_b32 m0, s36
	s_addc_u32 s61, s23, 0
	global_load_lds_dwordx4 v[158:159], off
	v_lshl_add_u64 v[160:161], s[60:61], 0, v[0:1]
	s_mov_b32 m0, s38
	v_lshl_add_u64 v[162:163], s[24:25], 0, v[132:133]
	global_load_lds_dwordx4 v[160:161], off
	v_lshl_add_u64 v[160:161], s[60:61], 0, v[134:135]
	s_mov_b32 m0, s39
	s_nop 0
	global_load_lds_dwordx4 v[160:161], off
	v_lshl_add_u64 v[160:161], s[24:25], 0, v[130:131]
	s_mov_b32 m0, s40
	s_nop 0
	global_load_lds_dwordx4 v[160:161], off
	s_mov_b32 m0, s41
	s_nop 0
	global_load_lds_dwordx4 v[162:163], off
	s_waitcnt vmcnt(8)
	s_waitcnt lgkmcnt(0)
	s_barrier
; #define PG8_STAGE(bufoff, gbase, voff) do { _Pragma("unroll") for (int _i = 0; _i < 2; ++_i) \
;         __builtin_amdgcn_global_load_lds((const unsigned*)((const char*)(gbase) + (voff)[_i]), (LAS unsigned*)(lds + (bufoff) + ldsw + _i * 8192), 16, 0, 0); } while (0)
; #define PG8_LDA(dst, b, h) do { _Pragma("unroll") for (int m = 0; m < 4; ++m) _Pragma("unroll") for (int k = 0; k < 2; ++k) dst[m][k] = *(const LAS bf16x8*)(lds + PG8_SA(b, h) + aoff + m * 2048 + k * 1024); } while (0)
; #define PG8_LDB(dst, b, h) do { _Pragma("unroll") for (int n = 0; n < 2; ++n) _Pragma("unroll") for (int k = 0; k < 2; ++k) dst[n][k] = *(const LAS bf16x8*)(lds + PG8_SB(b, h) + boff + n * 2048 + k * 1024); } while (0)
; #define PG8_MMA(ai, bj, At, Bt) do { __builtin_amdgcn_s_setprio(1); _Pragma("unroll") for (int m = 0; m < 4; ++m) _Pragma("unroll") for (int n = 0; n < 2; ++n) _Pragma("unroll") for (int k = 0; k < 2; ++k) \
;         acc[ai][bj][m][n] = __builtin_amdgcn_mfma_f32_16x16x32_bf16(Bt[n][k], At[m][k], acc[ai][bj][m][n], 0, 0, 0); __builtin_amdgcn_s_setprio(0); } while (0)
; #define PG8_WAIT_V(n) asm volatile("s_waitcnt vmcnt(" #n ")" ::: "memory")
; #define PG8_WAIT_L(n) asm volatile("s_waitcnt lgkmcnt(" #n ")" ::: "memory")
; #define PG8_BAR __builtin_amdgcn_s_barrier()
; #define PG8_SCHED __builtin_amdgcn_sched_barrier(0)
; template <class Epi>
; DI void gemm_phase(LAS unsigned char* lds, const Gemm g, const StaticOrder& S, const Epi& E, int wv0) {
;     ...
;             PG8_WAIT_V(8); PG8_WAIT_L(0); PG8_BAR; PG8_MMA(1, 0, At, B0); PG8_MMA(1, 1, At, B1); PG8_BAR; PG8_SCHED;
;             PG8_LDB(B0, 1, 0); PG8_LDB(B1, 1, 1); PG8_SCHED; PG8_LDA(At, 1, 0); PG8_STAGE(PG8_SA(0, 1), a2 + hstepA, voffA);
;             PG8_WAIT_V(8); PG8_WAIT_L(0); PG8_BAR; PG8_MMA(0, 0, At, B0); PG8_MMA(0, 1, At, B1); PG8_BAR; PG8_SCHED;
;             PG8_LDA(At, 1, 1); PG8_STAGE(PG8_SB(1, 0), b3, voffB); PG8_STAGE(PG8_SB(1, 1), b3 + hstepB, voffB); PG8_STAGE(PG8_SA(1, 0), a3, voffA);
	s_setprio 1
	s_waitcnt lgkmcnt(0)
	v_mfma_f32_16x16x32_bf16 v[62:65], v[140:143], v[210:213], v[62:65]
	v_mfma_f32_16x16x32_bf16 v[58:61], v[150:153], v[210:213], v[58:61]
	v_mfma_f32_16x16x32_bf16 v[54:57], v[140:143], v[218:221], v[54:57]
	v_mfma_f32_16x16x32_bf16 v[46:49], v[150:153], v[218:221], v[46:49]
	v_mfma_f32_16x16x32_bf16 v[38:41], v[140:143], v[226:229], v[38:41]
	v_mfma_f32_16x16x32_bf16 v[30:33], v[150:153], v[226:229], v[30:33]
	v_mfma_f32_16x16x32_bf16 v[22:25], v[140:143], v[234:237], v[22:25]
	v_mfma_f32_16x16x32_bf16 v[14:17], v[150:153], v[234:237], v[14:17]
	v_mfma_f32_16x16x32_bf16 v[62:65], v[146:149], v[214:217], v[62:65]
	v_mfma_f32_16x16x32_bf16 v[58:61], v[178:181], v[214:217], v[58:61]
	v_mfma_f32_16x16x32_bf16 v[54:57], v[146:149], v[222:225], v[54:57]
	v_mfma_f32_16x16x32_bf16 v[46:49], v[178:181], v[222:225], v[46:49]
	v_mfma_f32_16x16x32_bf16 v[38:41], v[146:149], v[230:233], v[38:41]
	v_mfma_f32_16x16x32_bf16 v[30:33], v[178:181], v[230:233], v[30:33]
	v_mfma_f32_16x16x32_bf16 v[22:25], v[146:149], v[238:241], v[22:25]
	v_mfma_f32_16x16x32_bf16 v[14:17], v[178:181], v[238:241], v[14:17]
	v_mfma_f32_16x16x32_bf16 v[50:53], v[182:185], v[210:213], v[50:53]
	v_mfma_f32_16x16x32_bf16 v[42:45], v[190:193], v[210:213], v[42:45]
	v_mfma_f32_16x16x32_bf16 v[34:37], v[182:185], v[218:221], v[34:37]
	v_mfma_f32_16x16x32_bf16 v[26:29], v[190:193], v[218:221], v[26:29]
	v_mfma_f32_16x16x32_bf16 v[18:21], v[182:185], v[226:229], v[18:21]
	v_mfma_f32_16x16x32_bf16 v[10:13], v[190:193], v[226:229], v[10:13]
	v_mfma_f32_16x16x32_bf16 v[6:9], v[182:185], v[234:237], v[6:9]
	v_mfma_f32_16x16x32_bf16 v[2:5], v[190:193], v[234:237], v[2:5]
	v_mfma_f32_16x16x32_bf16 v[50:53], v[186:189], v[214:217], v[50:53]
	v_mfma_f32_16x16x32_bf16 v[42:45], v[194:197], v[214:217], v[42:45]
	v_mfma_f32_16x16x32_bf16 v[34:37], v[186:189], v[222:225], v[34:37]
	v_mfma_f32_16x16x32_bf16 v[26:29], v[194:197], v[222:225], v[26:29]
	v_mfma_f32_16x16x32_bf16 v[18:21], v[186:189], v[230:233], v[18:21]
	v_mfma_f32_16x16x32_bf16 v[10:13], v[194:197], v[230:233], v[10:13]
	v_mfma_f32_16x16x32_bf16 v[6:9], v[186:189], v[238:241], v[6:9]
	v_mfma_f32_16x16x32_bf16 v[2:5], v[194:197], v[238:241], v[2:5]
	s_setprio 0
	s_barrier
	v_add_u32_e32 v164, s46, v144
	ds_read_b128 v[140:143], v164
	ds_read_b128 v[146:149], v164 offset:1024
	ds_read_b128 v[150:153], v164 offset:2048
	ds_read_b128 v[178:181], v164 offset:3072
	v_add_u32_e32 v164, s51, v144
	ds_read_b128 v[182:185], v164
	ds_read_b128 v[186:189], v164 offset:1024
	ds_read_b128 v[190:193], v164 offset:2048
	ds_read_b128 v[194:197], v164 offset:3072
	s_add_u32 s24, s24, 0x40000
	s_addc_u32 s25, s25, 0
	s_mov_b32 m0, s42
	v_lshl_add_u64 v[164:165], s[24:25], 0, v[130:131]
	ds_read_b128 v[210:213], v145 offset:32768
	ds_read_b128 v[214:217], v145 offset:33792
	ds_read_b128 v[218:221], v145 offset:34816
	ds_read_b128 v[222:225], v145 offset:35840
	ds_read_b128 v[226:229], v145 offset:36864
	ds_read_b128 v[230:233], v145 offset:37888
	ds_read_b128 v[234:237], v145 offset:38912
	ds_read_b128 v[238:241], v145 offset:39936
	global_load_lds_dwordx4 v[164:165], off
	v_lshl_add_u64 v[164:165], s[24:25], 0, v[132:133]
	s_mov_b32 m0, s43
	s_nop 0
	global_load_lds_dwordx4 v[164:165], off
	s_waitcnt vmcnt(8)
	s_waitcnt lgkmcnt(0)
	s_barrier
	s_setprio 1
	s_waitcnt lgkmcnt(0)
	v_mfma_f32_16x16x32_bf16 v[126:129], v[140:143], v[210:213], v[126:129]
	v_mfma_f32_16x16x32_bf16 v[122:125], v[150:153], v[210:213], v[122:125]
	v_mfma_f32_16x16x32_bf16 v[118:121], v[140:143], v[218:221], v[118:121]
	v_mfma_f32_16x16x32_bf16 v[110:113], v[150:153], v[218:221], v[110:113]
	v_mfma_f32_16x16x32_bf16 v[102:105], v[140:143], v[226:229], v[102:105]
	v_mfma_f32_16x16x32_bf16 v[94:97], v[150:153], v[226:229], v[94:97]
	v_mfma_f32_16x16x32_bf16 v[86:89], v[140:143], v[234:237], v[86:89]
	v_mfma_f32_16x16x32_bf16 v[78:81], v[150:153], v[234:237], v[78:81]
	v_mfma_f32_16x16x32_bf16 v[126:129], v[146:149], v[214:217], v[126:129]
	v_mfma_f32_16x16x32_bf16 v[122:125], v[178:181], v[214:217], v[122:125]
	v_mfma_f32_16x16x32_bf16 v[118:121], v[146:149], v[222:225], v[118:121]
	v_mfma_f32_16x16x32_bf16 v[110:113], v[178:181], v[222:225], v[110:113]
	v_mfma_f32_16x16x32_bf16 v[102:105], v[146:149], v[230:233], v[102:105]
	v_mfma_f32_16x16x32_bf16 v[94:97], v[178:181], v[230:233], v[94:97]
	v_mfma_f32_16x16x32_bf16 v[86:89], v[146:149], v[238:241], v[86:89]
	v_mfma_f32_16x16x32_bf16 v[78:81], v[178:181], v[238:241], v[78:81]
	v_mfma_f32_16x16x32_bf16 v[114:117], v[182:185], v[210:213], v[114:117]
	v_mfma_f32_16x16x32_bf16 v[106:109], v[190:193], v[210:213], v[106:109]
	v_mfma_f32_16x16x32_bf16 v[98:101], v[182:185], v[218:221], v[98:101]
	v_mfma_f32_16x16x32_bf16 v[90:93], v[190:193], v[218:221], v[90:93]
	v_mfma_f32_16x16x32_bf16 v[82:85], v[182:185], v[226:229], v[82:85]
	v_mfma_f32_16x16x32_bf16 v[74:77], v[190:193], v[226:229], v[74:77]
	v_mfma_f32_16x16x32_bf16 v[70:73], v[182:185], v[234:237], v[70:73]
	v_mfma_f32_16x16x32_bf16 v[66:69], v[190:193], v[234:237], v[66:69]
	v_mfma_f32_16x16x32_bf16 v[114:117], v[186:189], v[214:217], v[114:117]
	v_mfma_f32_16x16x32_bf16 v[106:109], v[194:197], v[214:217], v[106:109]
	v_mfma_f32_16x16x32_bf16 v[98:101], v[186:189], v[222:225], v[98:101]
	v_mfma_f32_16x16x32_bf16 v[90:93], v[194:197], v[222:225], v[90:93]
	v_mfma_f32_16x16x32_bf16 v[82:85], v[186:189], v[230:233], v[82:85]
	v_mfma_f32_16x16x32_bf16 v[74:77], v[194:197], v[230:233], v[74:77]
	v_mfma_f32_16x16x32_bf16 v[70:73], v[186:189], v[238:241], v[70:73]
	v_mfma_f32_16x16x32_bf16 v[66:69], v[194:197], v[238:241], v[66:69]
	s_setprio 0
	s_barrier
; #define PG8_STAGE(bufoff, gbase, voff) do { _Pragma("unroll") for (int _i = 0; _i < 2; ++_i) \
;         __builtin_amdgcn_global_load_lds((const unsigned*)((const char*)(gbase) + (voff)[_i]), (LAS unsigned*)(lds + (bufoff) + ldsw + _i * 8192), 16, 0, 0); } while (0)
; #define PG8_LDA(dst, b, h) do { _Pragma("unroll") for (int m = 0; m < 4; ++m) _Pragma("unroll") for (int k = 0; k < 2; ++k) dst[m][k] = *(const LAS bf16x8*)(lds + PG8_SA(b, h) + aoff + m * 2048 + k * 1024); } while (0)
; #define PG8_MMA(ai, bj, At, Bt) do { __builtin_amdgcn_s_setprio(1); _Pragma("unroll") for (int m = 0; m < 4; ++m) _Pragma("unroll") for (int n = 0; n < 2; ++n) _Pragma("unroll") for (int k = 0; k < 2; ++k) \
;         acc[ai][bj][m][n] = __builtin_amdgcn_mfma_f32_16x16x32_bf16(Bt[n][k], At[m][k], acc[ai][bj][m][n], 0, 0, 0); __builtin_amdgcn_s_setprio(0); } while (0)
; #define PG8_WAIT_V(n) asm volatile("s_waitcnt vmcnt(" #n ")" ::: "memory")
; #define PG8_WAIT_L(n) asm volatile("s_waitcnt lgkmcnt(" #n ")" ::: "memory")
; #define PG8_BAR __builtin_amdgcn_s_barrier()
; #define PG8_SCHED __builtin_amdgcn_sched_barrier(0)
; template <class Epi>
; DI void gemm_phase(LAS unsigned char* lds, const Gemm g, const StaticOrder& S, const Epi& E, int wv0) {
;     ...
;             PG8_LDA(At, 1, 1); PG8_STAGE(PG8_SB(1, 0), b3, voffB); PG8_STAGE(PG8_SB(1, 1), b3 + hstepB, voffB); PG8_STAGE(PG8_SA(1, 0), a3, voffA);
;             PG8_WAIT_V(8); PG8_WAIT_L(0); PG8_BAR; PG8_MMA(1, 0, At, B0); PG8_MMA(1, 1, At, B1); PG8_BAR; PG8_SCHED;
;         }
	s_mov_b32 m0, s47
	v_lshl_add_u64 v[154:155], v[154:155], 0, s[86:87]
	s_add_u32 s22, s22, 0x40080
	ds_read_b128 v[210:213], v145 offset:49152
	ds_read_b128 v[214:217], v145 offset:50176
	ds_read_b128 v[218:221], v145 offset:51200
	ds_read_b128 v[222:225], v145 offset:52224
	ds_read_b128 v[226:229], v145 offset:53248
	ds_read_b128 v[230:233], v145 offset:54272
	ds_read_b128 v[234:237], v145 offset:55296
	ds_read_b128 v[238:241], v145 offset:56320
	global_load_lds_dwordx4 v[154:155], off
	v_lshl_add_u64 v[154:155], v[158:159], 0, s[86:87]
	s_mov_b32 m0, s48
	s_addc_u32 s23, s23, 0
	global_load_lds_dwordx4 v[154:155], off
	v_lshl_add_u64 v[154:155], s[22:23], 0, v[0:1]
	s_mov_b32 m0, s52
	s_nop 0
	global_load_lds_dwordx4 v[154:155], off
	v_lshl_add_u64 v[154:155], s[22:23], 0, v[134:135]
	s_mov_b32 m0, s53
	s_nop 0
	global_load_lds_dwordx4 v[154:155], off
	v_lshl_add_u64 v[154:155], v[160:161], 0, s[86:87]
	s_mov_b32 m0, s49
	s_nop 0
	global_load_lds_dwordx4 v[154:155], off
	v_lshl_add_u64 v[154:155], v[162:163], 0, s[86:87]
	s_mov_b32 m0, s50
	s_nop 0
	global_load_lds_dwordx4 v[154:155], off
	s_waitcnt vmcnt(8)
	s_waitcnt lgkmcnt(0)
	s_barrier
	s_setprio 1
	s_waitcnt lgkmcnt(0)
	v_mfma_f32_16x16x32_bf16 v[62:65], v[140:143], v[210:213], v[62:65]
	v_mfma_f32_16x16x32_bf16 v[58:61], v[150:153], v[210:213], v[58:61]
	v_mfma_f32_16x16x32_bf16 v[54:57], v[140:143], v[218:221], v[54:57]
	v_mfma_f32_16x16x32_bf16 v[46:49], v[150:153], v[218:221], v[46:49]
	v_mfma_f32_16x16x32_bf16 v[38:41], v[140:143], v[226:229], v[38:41]
	v_mfma_f32_16x16x32_bf16 v[30:33], v[150:153], v[226:229], v[30:33]
	v_mfma_f32_16x16x32_bf16 v[22:25], v[140:143], v[234:237], v[22:25]
	v_mfma_f32_16x16x32_bf16 v[14:17], v[150:153], v[234:237], v[14:17]
	v_mfma_f32_16x16x32_bf16 v[62:65], v[146:149], v[214:217], v[62:65]
	v_mfma_f32_16x16x32_bf16 v[58:61], v[178:181], v[214:217], v[58:61]
	v_mfma_f32_16x16x32_bf16 v[54:57], v[146:149], v[222:225], v[54:57]
	v_mfma_f32_16x16x32_bf16 v[46:49], v[178:181], v[222:225], v[46:49]
	v_mfma_f32_16x16x32_bf16 v[38:41], v[146:149], v[230:233], v[38:41]
	v_mfma_f32_16x16x32_bf16 v[30:33], v[178:181], v[230:233], v[30:33]
	v_mfma_f32_16x16x32_bf16 v[22:25], v[146:149], v[238:241], v[22:25]
	v_mfma_f32_16x16x32_bf16 v[14:17], v[178:181], v[238:241], v[14:17]
	v_mfma_f32_16x16x32_bf16 v[50:53], v[182:185], v[210:213], v[50:53]
	v_mfma_f32_16x16x32_bf16 v[42:45], v[190:193], v[210:213], v[42:45]
	v_mfma_f32_16x16x32_bf16 v[34:37], v[182:185], v[218:221], v[34:37]
	v_mfma_f32_16x16x32_bf16 v[26:29], v[190:193], v[218:221], v[26:29]
	v_mfma_f32_16x16x32_bf16 v[18:21], v[182:185], v[226:229], v[18:21]
	v_mfma_f32_16x16x32_bf16 v[10:13], v[190:193], v[226:229], v[10:13]
	v_mfma_f32_16x16x32_bf16 v[6:9], v[182:185], v[234:237], v[6:9]
	v_mfma_f32_16x16x32_bf16 v[2:5], v[190:193], v[234:237], v[2:5]
	v_mfma_f32_16x16x32_bf16 v[50:53], v[186:189], v[214:217], v[50:53]
	v_mfma_f32_16x16x32_bf16 v[42:45], v[194:197], v[214:217], v[42:45]
	v_mfma_f32_16x16x32_bf16 v[34:37], v[186:189], v[222:225], v[34:37]
	v_mfma_f32_16x16x32_bf16 v[26:29], v[194:197], v[222:225], v[26:29]
	v_mfma_f32_16x16x32_bf16 v[18:21], v[186:189], v[230:233], v[18:21]
	v_mfma_f32_16x16x32_bf16 v[10:13], v[194:197], v[230:233], v[10:13]
	v_mfma_f32_16x16x32_bf16 v[6:9], v[186:189], v[238:241], v[6:9]
	v_mfma_f32_16x16x32_bf16 v[2:5], v[194:197], v[238:241], v[2:5]
	s_setprio 0
	s_barrier
	s_add_i32 s59, s59, 2
	s_add_u32 s57, s57, 0x100
	s_addc_u32 s58, s58, 0
	s_add_u32 s20, s20, 0x100
	s_addc_u32 s21, s21, 0
	s_cmp_gt_u32 s59, 13
	s_cbranch_scc0 .LBB0_601
	s_and_b64 vcc, exec, s[8:9]
	s_cbranch_vccz .LBB0_604
	s_barrier

; #define PG8_STAGE(bufoff, gbase, voff) do { _Pragma("unroll") for (int _i = 0; _i < 2; ++_i) \
;         __builtin_amdgcn_global_load_lds((const unsigned*)((const char*)(gbase) + (voff)[_i]), (LAS unsigned*)(lds + (bufoff) + ldsw + _i * 8192), 16, 0, 0); } while (0)
; #define PG8_LDA(dst, b, h) do { _Pragma("unroll") for (int m = 0; m < 4; ++m) _Pragma("unroll") for (int k = 0; k < 2; ++k) dst[m][k] = *(const LAS bf16x8*)(lds + PG8_SA(b, h) + aoff + m * 2048 + k * 1024); } while (0)
; #define PG8_LDB(dst, b, h) do { _Pragma("unroll") for (int n = 0; n < 2; ++n) _Pragma("unroll") for (int k = 0; k < 2; ++k) dst[n][k] = *(const LAS bf16x8*)(lds + PG8_SB(b, h) + boff + n * 2048 + k * 1024); } while (0)
; #define PG8_MMA(ai, bj, At, Bt) do { __builtin_amdgcn_s_setprio(1); _Pragma("unroll") for (int m = 0; m < 4; ++m) _Pragma("unroll") for (int n = 0; n < 2; ++n) _Pragma("unroll") for (int k = 0; k < 2; ++k) \
;         acc[ai][bj][m][n] = __builtin_amdgcn_mfma_f32_16x16x32_bf16(Bt[n][k], At[m][k], acc[ai][bj][m][n], 0, 0, 0); __builtin_amdgcn_s_setprio(0); } while (0)
; #define PG8_WAIT_V(n) asm volatile("s_waitcnt vmcnt(" #n ")" ::: "memory")
; #define PG8_WAIT_L(n) asm volatile("s_waitcnt lgkmcnt(" #n ")" ::: "memory")
; #define PG8_BAR __builtin_amdgcn_s_barrier()
; #define PG8_SCHED __builtin_amdgcn_sched_barrier(0)
; template <class Epi>
; DI void gemm_phase(LAS unsigned char* lds, const Gemm g, const StaticOrder& S, const Epi& E, int wv0) {
;     ...
;             PG8_LDB(B0, 0, 0); PG8_LDB(B1, 0, 1); PG8_SCHED; PG8_LDA(At, 0, 0); PG8_STAGE(PG8_SA(1, 1), a1 + hstepA, voffA);
;             PG8_WAIT_V(8); PG8_WAIT_L(0); PG8_BAR; PG8_MMA(0, 0, At, B0); PG8_MMA(0, 1, At, B1); PG8_BAR; PG8_SCHED;
;             PG8_LDA(At, 0, 1); PG8_STAGE(PG8_SB(0, 0), b2, voffB); PG8_STAGE(PG8_SB(0, 1), b2 + hstepB, voffB); PG8_STAGE(PG8_SA(0, 0), a2, voffA);
;             PG8_WAIT_V(8); PG8_WAIT_L(0); PG8_BAR; PG8_MMA(1, 0, At, B0); PG8_MMA(1, 1, At, B1); PG8_BAR; PG8_SCHED;
.LBB0_759:
	s_add_u32 s25, s20, s24
	s_addc_u32 s30, s21, 0
	s_add_u32 s28, s25, 0x100
	s_addc_u32 s29, s30, 0
	s_and_b64 s[26:27], s[22:23], exec
	s_cselect_b32 s27, s15, s29
	s_cselect_b32 s26, s14, s28
	s_add_u32 s24, s18, s24
	s_addc_u32 s28, s19, 0
	s_add_u32 s24, s24, 0x100
	s_addc_u32 s28, s28, 0
	s_and_b64 s[22:23], s[22:23], exec
	s_cselect_b32 s29, s11, s28
	s_cselect_b32 s28, s13, s24
	s_add_u32 s36, s25, 0xa0080
	v_add_u32_e32 v150, s44, v140
	v_add_u32_e32 v154, s47, v140
	s_addc_u32 s37, s30, 0
	s_add_i32 m0, s50, 0xc000
	s_add_i32 s69, s50, 0xe000
	ds_read_b128 v[136:139], v150
	ds_read_b128 v[142:145], v150 offset:1024
	ds_read_b128 v[146:149], v150 offset:2048
	ds_read_b128 v[150:153], v150 offset:3072
	ds_read_b128 v[178:181], v154
	ds_read_b128 v[182:185], v154 offset:1024
	ds_read_b128 v[186:189], v154 offset:2048
	ds_read_b128 v[190:193], v154 offset:3072
	s_add_u32 s30, s28, 0x10000
	s_addc_u32 s31, s29, 0
	s_add_u32 s24, s26, 0xa0000
	s_addc_u32 s25, s27, 0
	s_add_u32 s22, s28, 0x10080
	s_addc_u32 s23, s29, 0
	v_lshl_add_u64 v[154:155], s[36:37], 0, v[130:131]
	ds_read_b128 v[194:197], v141
	ds_read_b128 v[210:213], v141 offset:1024
	ds_read_b128 v[214:217], v141 offset:2048
	ds_read_b128 v[218:221], v141 offset:3072
	ds_read_b128 v[222:225], v141 offset:4096
	ds_read_b128 v[226:229], v141 offset:5120
	ds_read_b128 v[230:233], v141 offset:6144
	ds_read_b128 v[234:237], v141 offset:7168
	global_load_lds_dwordx4 v[154:155], off
	v_lshl_add_u64 v[154:155], s[36:37], 0, v[132:133]
	s_mov_b32 m0, s69
	s_nop 0
	global_load_lds_dwordx4 v[154:155], off
	s_waitcnt vmcnt(8)
	s_waitcnt lgkmcnt(0)
	s_barrier
	s_setprio 1
	s_waitcnt lgkmcnt(0)
	v_mfma_f32_16x16x32_bf16 v[126:129], v[136:139], v[194:197], v[126:129]
	v_mfma_f32_16x16x32_bf16 v[122:125], v[146:149], v[194:197], v[122:125]
	v_mfma_f32_16x16x32_bf16 v[118:121], v[136:139], v[214:217], v[118:121]
	v_mfma_f32_16x16x32_bf16 v[110:113], v[146:149], v[214:217], v[110:113]
	v_mfma_f32_16x16x32_bf16 v[102:105], v[136:139], v[222:225], v[102:105]
	v_mfma_f32_16x16x32_bf16 v[94:97], v[146:149], v[222:225], v[94:97]
	v_mfma_f32_16x16x32_bf16 v[86:89], v[136:139], v[230:233], v[86:89]
	v_mfma_f32_16x16x32_bf16 v[78:81], v[146:149], v[230:233], v[78:81]
	v_mfma_f32_16x16x32_bf16 v[126:129], v[142:145], v[210:213], v[126:129]
	v_mfma_f32_16x16x32_bf16 v[122:125], v[150:153], v[210:213], v[122:125]
	v_mfma_f32_16x16x32_bf16 v[118:121], v[142:145], v[218:221], v[118:121]
	v_mfma_f32_16x16x32_bf16 v[110:113], v[150:153], v[218:221], v[110:113]
	v_mfma_f32_16x16x32_bf16 v[102:105], v[142:145], v[226:229], v[102:105]
	v_mfma_f32_16x16x32_bf16 v[94:97], v[150:153], v[226:229], v[94:97]
	v_mfma_f32_16x16x32_bf16 v[86:89], v[142:145], v[234:237], v[86:89]
	v_mfma_f32_16x16x32_bf16 v[78:81], v[150:153], v[234:237], v[78:81]
	v_mfma_f32_16x16x32_bf16 v[114:117], v[178:181], v[194:197], v[114:117]
	v_mfma_f32_16x16x32_bf16 v[106:109], v[186:189], v[194:197], v[106:109]
	v_mfma_f32_16x16x32_bf16 v[98:101], v[178:181], v[214:217], v[98:101]
	v_mfma_f32_16x16x32_bf16 v[90:93], v[186:189], v[214:217], v[90:93]
	v_mfma_f32_16x16x32_bf16 v[82:85], v[178:181], v[222:225], v[82:85]
	v_mfma_f32_16x16x32_bf16 v[74:77], v[186:189], v[222:225], v[74:77]
	v_mfma_f32_16x16x32_bf16 v[70:73], v[178:181], v[230:233], v[70:73]
	v_mfma_f32_16x16x32_bf16 v[66:69], v[186:189], v[230:233], v[66:69]
	v_mfma_f32_16x16x32_bf16 v[114:117], v[182:185], v[210:213], v[114:117]
	v_mfma_f32_16x16x32_bf16 v[106:109], v[190:193], v[210:213], v[106:109]
	v_mfma_f32_16x16x32_bf16 v[98:101], v[182:185], v[218:221], v[98:101]
	v_mfma_f32_16x16x32_bf16 v[90:93], v[190:193], v[218:221], v[90:93]
	v_mfma_f32_16x16x32_bf16 v[82:85], v[182:185], v[226:229], v[82:85]
	v_mfma_f32_16x16x32_bf16 v[74:77], v[190:193], v[226:229], v[74:77]
	v_mfma_f32_16x16x32_bf16 v[70:73], v[182:185], v[234:237], v[70:73]
	v_mfma_f32_16x16x32_bf16 v[66:69], v[190:193], v[234:237], v[66:69]
	s_setprio 0
	s_barrier
	s_mov_b32 m0, s45
	v_lshl_add_u64 v[154:155], s[28:29], 0, v[0:1]
	ds_read_b128 v[194:197], v141 offset:16384
	ds_read_b128 v[210:213], v141 offset:17408
	ds_read_b128 v[214:217], v141 offset:18432
	ds_read_b128 v[218:221], v141 offset:19456
	ds_read_b128 v[222:225], v141 offset:20480
	ds_read_b128 v[226:229], v141 offset:21504
	ds_read_b128 v[230:233], v141 offset:22528
	ds_read_b128 v[234:237], v141 offset:23552
	global_load_lds_dwordx4 v[154:155], off
	v_lshl_add_u64 v[158:159], s[28:29], 0, v[134:135]
	s_mov_b32 m0, s46
	v_lshl_add_u64 v[160:161], s[30:31], 0, v[0:1]
	global_load_lds_dwordx4 v[158:159], off
	s_mov_b32 m0, s48
	v_lshl_add_u64 v[162:163], s[26:27], 0, v[132:133]
	global_load_lds_dwordx4 v[160:161], off
	v_lshl_add_u64 v[160:161], s[30:31], 0, v[134:135]
	s_mov_b32 m0, s49
	s_nop 0
	global_load_lds_dwordx4 v[160:161], off
	v_lshl_add_u64 v[160:161], s[26:27], 0, v[130:131]
	s_mov_b32 m0, s50
	s_nop 0
	global_load_lds_dwordx4 v[160:161], off
	s_mov_b32 m0, s51
	s_nop 0
	global_load_lds_dwordx4 v[162:163], off
	s_waitcnt vmcnt(8)
	s_waitcnt lgkmcnt(0)
	s_barrier
; #define PG8_STAGE(bufoff, gbase, voff) do { _Pragma("unroll") for (int _i = 0; _i < 2; ++_i) \
;         __builtin_amdgcn_global_load_lds((const unsigned*)((const char*)(gbase) + (voff)[_i]), (LAS unsigned*)(lds + (bufoff) + ldsw + _i * 8192), 16, 0, 0); } while (0)
; #define PG8_LDA(dst, b, h) do { _Pragma("unroll") for (int m = 0; m < 4; ++m) _Pragma("unroll") for (int k = 0; k < 2; ++k) dst[m][k] = *(const LAS bf16x8*)(lds + PG8_SA(b, h) + aoff + m * 2048 + k * 1024); } while (0)
; #define PG8_LDB(dst, b, h) do { _Pragma("unroll") for (int n = 0; n < 2; ++n) _Pragma("unroll") for (int k = 0; k < 2; ++k) dst[n][k] = *(const LAS bf16x8*)(lds + PG8_SB(b, h) + boff + n * 2048 + k * 1024); } while (0)
; #define PG8_MMA(ai, bj, At, Bt) do { __builtin_amdgcn_s_setprio(1); _Pragma("unroll") for (int m = 0; m < 4; ++m) _Pragma("unroll") for (int n = 0; n < 2; ++n) _Pragma("unroll") for (int k = 0; k < 2; ++k) \
;         acc[ai][bj][m][n] = __builtin_amdgcn_mfma_f32_16x16x32_bf16(Bt[n][k], At[m][k], acc[ai][bj][m][n], 0, 0, 0); __builtin_amdgcn_s_setprio(0); } while (0)
; #define PG8_WAIT_V(n) asm volatile("s_waitcnt vmcnt(" #n ")" ::: "memory")
; #define PG8_WAIT_L(n) asm volatile("s_waitcnt lgkmcnt(" #n ")" ::: "memory")
; #define PG8_BAR __builtin_amdgcn_s_barrier()
; #define PG8_SCHED __builtin_amdgcn_sched_barrier(0)
; template <class Epi>
; DI void gemm_phase(LAS unsigned char* lds, const Gemm g, const StaticOrder& S, const Epi& E, int wv0) {
;     ...
;             PG8_WAIT_V(8); PG8_WAIT_L(0); PG8_BAR; PG8_MMA(1, 0, At, B0); PG8_MMA(1, 1, At, B1); PG8_BAR; PG8_SCHED;
;             PG8_LDB(B0, 1, 0); PG8_LDB(B1, 1, 1); PG8_SCHED; PG8_LDA(At, 1, 0); PG8_STAGE(PG8_SA(0, 1), a2 + hstepA, voffA);
;             PG8_WAIT_V(8); PG8_WAIT_L(0); PG8_BAR; PG8_MMA(0, 0, At, B0); PG8_MMA(0, 1, At, B1); PG8_BAR; PG8_SCHED;
;             PG8_LDA(At, 1, 1); PG8_STAGE(PG8_SB(1, 0), b3, voffB); PG8_STAGE(PG8_SB(1, 1), b3 + hstepB, voffB); PG8_STAGE(PG8_SA(1, 0), a3, voffA);
	s_setprio 1
	s_waitcnt lgkmcnt(0)
	v_mfma_f32_16x16x32_bf16 v[62:65], v[136:139], v[194:197], v[62:65]
	v_mfma_f32_16x16x32_bf16 v[58:61], v[146:149], v[194:197], v[58:61]
	v_mfma_f32_16x16x32_bf16 v[54:57], v[136:139], v[214:217], v[54:57]
	v_mfma_f32_16x16x32_bf16 v[46:49], v[146:149], v[214:217], v[46:49]
	v_mfma_f32_16x16x32_bf16 v[38:41], v[136:139], v[222:225], v[38:41]
	v_mfma_f32_16x16x32_bf16 v[30:33], v[146:149], v[222:225], v[30:33]
	v_mfma_f32_16x16x32_bf16 v[22:25], v[136:139], v[230:233], v[22:25]
	v_mfma_f32_16x16x32_bf16 v[14:17], v[146:149], v[230:233], v[14:17]
	v_mfma_f32_16x16x32_bf16 v[62:65], v[142:145], v[210:213], v[62:65]
	v_mfma_f32_16x16x32_bf16 v[58:61], v[150:153], v[210:213], v[58:61]
	v_mfma_f32_16x16x32_bf16 v[54:57], v[142:145], v[218:221], v[54:57]
	v_mfma_f32_16x16x32_bf16 v[46:49], v[150:153], v[218:221], v[46:49]
	v_mfma_f32_16x16x32_bf16 v[38:41], v[142:145], v[226:229], v[38:41]
	v_mfma_f32_16x16x32_bf16 v[30:33], v[150:153], v[226:229], v[30:33]
	v_mfma_f32_16x16x32_bf16 v[22:25], v[142:145], v[234:237], v[22:25]
	v_mfma_f32_16x16x32_bf16 v[14:17], v[150:153], v[234:237], v[14:17]
	v_mfma_f32_16x16x32_bf16 v[50:53], v[178:181], v[194:197], v[50:53]
	v_mfma_f32_16x16x32_bf16 v[42:45], v[186:189], v[194:197], v[42:45]
	v_mfma_f32_16x16x32_bf16 v[34:37], v[178:181], v[214:217], v[34:37]
	v_mfma_f32_16x16x32_bf16 v[26:29], v[186:189], v[214:217], v[26:29]
	v_mfma_f32_16x16x32_bf16 v[18:21], v[178:181], v[222:225], v[18:21]
	v_mfma_f32_16x16x32_bf16 v[10:13], v[186:189], v[222:225], v[10:13]
	v_mfma_f32_16x16x32_bf16 v[6:9], v[178:181], v[230:233], v[6:9]
	v_mfma_f32_16x16x32_bf16 v[2:5], v[186:189], v[230:233], v[2:5]
	v_mfma_f32_16x16x32_bf16 v[50:53], v[182:185], v[210:213], v[50:53]
	v_mfma_f32_16x16x32_bf16 v[42:45], v[190:193], v[210:213], v[42:45]
	v_mfma_f32_16x16x32_bf16 v[34:37], v[182:185], v[218:221], v[34:37]
	v_mfma_f32_16x16x32_bf16 v[26:29], v[190:193], v[218:221], v[26:29]
	v_mfma_f32_16x16x32_bf16 v[18:21], v[182:185], v[226:229], v[18:21]
	v_mfma_f32_16x16x32_bf16 v[10:13], v[190:193], v[226:229], v[10:13]
	v_mfma_f32_16x16x32_bf16 v[6:9], v[182:185], v[234:237], v[6:9]
	v_mfma_f32_16x16x32_bf16 v[2:5], v[190:193], v[234:237], v[2:5]
	s_setprio 0
	s_barrier
	v_add_u32_e32 v150, s56, v140
	v_add_u32_e32 v164, s61, v140
	ds_read_b128 v[136:139], v150
	ds_read_b128 v[142:145], v150 offset:1024
	ds_read_b128 v[146:149], v150 offset:2048
	ds_read_b128 v[150:153], v150 offset:3072
	ds_read_b128 v[178:181], v164
	ds_read_b128 v[182:185], v164 offset:1024
	ds_read_b128 v[186:189], v164 offset:2048
	ds_read_b128 v[190:193], v164 offset:3072
	s_mov_b32 m0, s52
	v_lshl_add_u64 v[164:165], s[24:25], 0, v[130:131]
	ds_read_b128 v[194:197], v141 offset:32768
	ds_read_b128 v[210:213], v141 offset:33792
	ds_read_b128 v[214:217], v141 offset:34816
	ds_read_b128 v[218:221], v141 offset:35840
	ds_read_b128 v[222:225], v141 offset:36864
	ds_read_b128 v[226:229], v141 offset:37888
	ds_read_b128 v[230:233], v141 offset:38912
	ds_read_b128 v[234:237], v141 offset:39936
	global_load_lds_dwordx4 v[164:165], off
	v_lshl_add_u64 v[164:165], s[24:25], 0, v[132:133]
	s_mov_b32 m0, s53
	s_nop 0
	global_load_lds_dwordx4 v[164:165], off
	s_waitcnt vmcnt(8)
	s_waitcnt lgkmcnt(0)
	s_barrier
	s_setprio 1
	s_waitcnt lgkmcnt(0)
	v_mfma_f32_16x16x32_bf16 v[126:129], v[136:139], v[194:197], v[126:129]
	v_mfma_f32_16x16x32_bf16 v[122:125], v[146:149], v[194:197], v[122:125]
	v_mfma_f32_16x16x32_bf16 v[118:121], v[136:139], v[214:217], v[118:121]
	v_mfma_f32_16x16x32_bf16 v[110:113], v[146:149], v[214:217], v[110:113]
	v_mfma_f32_16x16x32_bf16 v[102:105], v[136:139], v[222:225], v[102:105]
	v_mfma_f32_16x16x32_bf16 v[94:97], v[146:149], v[222:225], v[94:97]
	v_mfma_f32_16x16x32_bf16 v[86:89], v[136:139], v[230:233], v[86:89]
	v_mfma_f32_16x16x32_bf16 v[78:81], v[146:149], v[230:233], v[78:81]
	v_mfma_f32_16x16x32_bf16 v[126:129], v[142:145], v[210:213], v[126:129]
	v_mfma_f32_16x16x32_bf16 v[122:125], v[150:153], v[210:213], v[122:125]
	v_mfma_f32_16x16x32_bf16 v[118:121], v[142:145], v[218:221], v[118:121]
	v_mfma_f32_16x16x32_bf16 v[110:113], v[150:153], v[218:221], v[110:113]
	v_mfma_f32_16x16x32_bf16 v[102:105], v[142:145], v[226:229], v[102:105]
	v_mfma_f32_16x16x32_bf16 v[94:97], v[150:153], v[226:229], v[94:97]
	v_mfma_f32_16x16x32_bf16 v[86:89], v[142:145], v[234:237], v[86:89]
	v_mfma_f32_16x16x32_bf16 v[78:81], v[150:153], v[234:237], v[78:81]
	v_mfma_f32_16x16x32_bf16 v[114:117], v[178:181], v[194:197], v[114:117]
	v_mfma_f32_16x16x32_bf16 v[106:109], v[186:189], v[194:197], v[106:109]
	v_mfma_f32_16x16x32_bf16 v[98:101], v[178:181], v[214:217], v[98:101]
	v_mfma_f32_16x16x32_bf16 v[90:93], v[186:189], v[214:217], v[90:93]
	v_mfma_f32_16x16x32_bf16 v[82:85], v[178:181], v[222:225], v[82:85]
	v_mfma_f32_16x16x32_bf16 v[74:77], v[186:189], v[222:225], v[74:77]
	v_mfma_f32_16x16x32_bf16 v[70:73], v[178:181], v[230:233], v[70:73]
	v_mfma_f32_16x16x32_bf16 v[66:69], v[186:189], v[230:233], v[66:69]
	v_mfma_f32_16x16x32_bf16 v[114:117], v[182:185], v[210:213], v[114:117]
	v_mfma_f32_16x16x32_bf16 v[106:109], v[190:193], v[210:213], v[106:109]
	v_mfma_f32_16x16x32_bf16 v[98:101], v[182:185], v[218:221], v[98:101]
	v_mfma_f32_16x16x32_bf16 v[90:93], v[190:193], v[218:221], v[90:93]
	v_mfma_f32_16x16x32_bf16 v[82:85], v[182:185], v[226:229], v[82:85]
	v_mfma_f32_16x16x32_bf16 v[74:77], v[190:193], v[226:229], v[74:77]
	v_mfma_f32_16x16x32_bf16 v[70:73], v[182:185], v[234:237], v[70:73]
	v_mfma_f32_16x16x32_bf16 v[66:69], v[190:193], v[234:237], v[66:69]
	s_setprio 0
	s_barrier
; #define PG8_STAGE(bufoff, gbase, voff) do { _Pragma("unroll") for (int _i = 0; _i < 2; ++_i) \
;         __builtin_amdgcn_global_load_lds((const unsigned*)((const char*)(gbase) + (voff)[_i]), (LAS unsigned*)(lds + (bufoff) + ldsw + _i * 8192), 16, 0, 0); } while (0)
; #define PG8_LDA(dst, b, h) do { _Pragma("unroll") for (int m = 0; m < 4; ++m) _Pragma("unroll") for (int k = 0; k < 2; ++k) dst[m][k] = *(const LAS bf16x8*)(lds + PG8_SA(b, h) + aoff + m * 2048 + k * 1024); } while (0)
; #define PG8_MMA(ai, bj, At, Bt) do { __builtin_amdgcn_s_setprio(1); _Pragma("unroll") for (int m = 0; m < 4; ++m) _Pragma("unroll") for (int n = 0; n < 2; ++n) _Pragma("unroll") for (int k = 0; k < 2; ++k) \
;         acc[ai][bj][m][n] = __builtin_amdgcn_mfma_f32_16x16x32_bf16(Bt[n][k], At[m][k], acc[ai][bj][m][n], 0, 0, 0); __builtin_amdgcn_s_setprio(0); } while (0)
; #define PG8_WAIT_V(n) asm volatile("s_waitcnt vmcnt(" #n ")" ::: "memory")
; #define PG8_WAIT_L(n) asm volatile("s_waitcnt lgkmcnt(" #n ")" ::: "memory")
; #define PG8_BAR __builtin_amdgcn_s_barrier()
; #define PG8_SCHED __builtin_amdgcn_sched_barrier(0)
; template <class Epi>
; DI void gemm_phase(LAS unsigned char* lds, const Gemm g, const StaticOrder& S, const Epi& E, int wv0) {
;     ...
;             PG8_LDA(At, 1, 1); PG8_STAGE(PG8_SB(1, 0), b3, voffB); PG8_STAGE(PG8_SB(1, 1), b3 + hstepB, voffB); PG8_STAGE(PG8_SA(1, 0), a3, voffA);
;             PG8_WAIT_V(8); PG8_WAIT_L(0); PG8_BAR; PG8_MMA(1, 0, At, B0); PG8_MMA(1, 1, At, B1); PG8_BAR; PG8_SCHED;
;         }
	s_mov_b32 m0, s57
	v_lshl_add_u64 v[154:155], v[154:155], 0, s[86:87]
	ds_read_b128 v[194:197], v141 offset:49152
	ds_read_b128 v[210:213], v141 offset:50176
	ds_read_b128 v[214:217], v141 offset:51200
	ds_read_b128 v[218:221], v141 offset:52224
	ds_read_b128 v[222:225], v141 offset:53248
	ds_read_b128 v[226:229], v141 offset:54272
	ds_read_b128 v[230:233], v141 offset:55296
	ds_read_b128 v[234:237], v141 offset:56320
	global_load_lds_dwordx4 v[154:155], off
	v_lshl_add_u64 v[154:155], v[158:159], 0, s[86:87]
	s_mov_b32 m0, s58
	s_nop 0
	global_load_lds_dwordx4 v[154:155], off
	v_lshl_add_u64 v[154:155], s[22:23], 0, v[0:1]
	s_mov_b32 m0, s62
	s_nop 0
	global_load_lds_dwordx4 v[154:155], off
	v_lshl_add_u64 v[154:155], s[22:23], 0, v[134:135]
	s_mov_b32 m0, s63
	s_nop 0
	global_load_lds_dwordx4 v[154:155], off
	v_lshl_add_u64 v[154:155], v[160:161], 0, s[86:87]
	s_mov_b32 m0, s59
	s_nop 0
	global_load_lds_dwordx4 v[154:155], off
	v_lshl_add_u64 v[154:155], v[162:163], 0, s[86:87]
	s_mov_b32 m0, s60
	s_nop 0
	global_load_lds_dwordx4 v[154:155], off
	s_waitcnt vmcnt(8)
	s_waitcnt lgkmcnt(0)
	s_barrier
	s_setprio 1
	s_waitcnt lgkmcnt(0)
	v_mfma_f32_16x16x32_bf16 v[62:65], v[136:139], v[194:197], v[62:65]
	v_mfma_f32_16x16x32_bf16 v[58:61], v[146:149], v[194:197], v[58:61]
	v_mfma_f32_16x16x32_bf16 v[54:57], v[136:139], v[214:217], v[54:57]
	v_mfma_f32_16x16x32_bf16 v[46:49], v[146:149], v[214:217], v[46:49]
	v_mfma_f32_16x16x32_bf16 v[38:41], v[136:139], v[222:225], v[38:41]
	v_mfma_f32_16x16x32_bf16 v[30:33], v[146:149], v[222:225], v[30:33]
	v_mfma_f32_16x16x32_bf16 v[22:25], v[136:139], v[230:233], v[22:25]
	v_mfma_f32_16x16x32_bf16 v[14:17], v[146:149], v[230:233], v[14:17]
	v_mfma_f32_16x16x32_bf16 v[62:65], v[142:145], v[210:213], v[62:65]
	v_mfma_f32_16x16x32_bf16 v[58:61], v[150:153], v[210:213], v[58:61]
	v_mfma_f32_16x16x32_bf16 v[54:57], v[142:145], v[218:221], v[54:57]
	v_mfma_f32_16x16x32_bf16 v[46:49], v[150:153], v[218:221], v[46:49]
	v_mfma_f32_16x16x32_bf16 v[38:41], v[142:145], v[226:229], v[38:41]
	v_mfma_f32_16x16x32_bf16 v[30:33], v[150:153], v[226:229], v[30:33]
	v_mfma_f32_16x16x32_bf16 v[22:25], v[142:145], v[234:237], v[22:25]
	v_mfma_f32_16x16x32_bf16 v[14:17], v[150:153], v[234:237], v[14:17]
	v_mfma_f32_16x16x32_bf16 v[50:53], v[178:181], v[194:197], v[50:53]
	v_mfma_f32_16x16x32_bf16 v[42:45], v[186:189], v[194:197], v[42:45]
	v_mfma_f32_16x16x32_bf16 v[34:37], v[178:181], v[214:217], v[34:37]
	v_mfma_f32_16x16x32_bf16 v[26:29], v[186:189], v[214:217], v[26:29]
	v_mfma_f32_16x16x32_bf16 v[18:21], v[178:181], v[222:225], v[18:21]
	v_mfma_f32_16x16x32_bf16 v[10:13], v[186:189], v[222:225], v[10:13]
	v_mfma_f32_16x16x32_bf16 v[6:9], v[178:181], v[230:233], v[6:9]
	v_mfma_f32_16x16x32_bf16 v[2:5], v[186:189], v[230:233], v[2:5]
	v_mfma_f32_16x16x32_bf16 v[50:53], v[182:185], v[210:213], v[50:53]
	v_mfma_f32_16x16x32_bf16 v[42:45], v[190:193], v[210:213], v[42:45]
	v_mfma_f32_16x16x32_bf16 v[34:37], v[182:185], v[218:221], v[34:37]
	v_mfma_f32_16x16x32_bf16 v[26:29], v[190:193], v[218:221], v[26:29]
	v_mfma_f32_16x16x32_bf16 v[18:21], v[182:185], v[226:229], v[18:21]
	v_mfma_f32_16x16x32_bf16 v[10:13], v[190:193], v[226:229], v[10:13]
	v_mfma_f32_16x16x32_bf16 v[6:9], v[182:185], v[234:237], v[6:9]
	v_mfma_f32_16x16x32_bf16 v[2:5], v[190:193], v[234:237], v[2:5]
	s_setprio 0
	s_barrier
	s_movk_i32 s24, 0x100
	s_andn2_b64 vcc, exec, s[4:5]
	s_mov_b64 s[22:23], -1
	s_mov_b64 s[4:5], 0
	s_cbranch_vccz .LBB0_759
	s_and_b64 vcc, exec, s[8:9]
	s_cbranch_vccz .LBB0_762
	s_barrier

; #define PG8_STAGE(bufoff, gbase, voff) do { _Pragma("unroll") for (int _i = 0; _i < 2; ++_i) \
;         __builtin_amdgcn_global_load_lds((const unsigned*)((const char*)(gbase) + (voff)[_i]), (LAS unsigned*)(lds + (bufoff) + ldsw + _i * 8192), 16, 0, 0); } while (0)
; #define PG8_LDA(dst, b, h) do { _Pragma("unroll") for (int m = 0; m < 4; ++m) _Pragma("unroll") for (int k = 0; k < 2; ++k) dst[m][k] = *(const LAS bf16x8*)(lds + PG8_SA(b, h) + aoff + m * 2048 + k * 1024); } while (0)
; #define PG8_LDB(dst, b, h) do { _Pragma("unroll") for (int n = 0; n < 2; ++n) _Pragma("unroll") for (int k = 0; k < 2; ++k) dst[n][k] = *(const LAS bf16x8*)(lds + PG8_SB(b, h) + boff + n * 2048 + k * 1024); } while (0)
; #define PG8_MMA(ai, bj, At, Bt) do { __builtin_amdgcn_s_setprio(1); _Pragma("unroll") for (int m = 0; m < 4; ++m) _Pragma("unroll") for (int n = 0; n < 2; ++n) _Pragma("unroll") for (int k = 0; k < 2; ++k) \
;         acc[ai][bj][m][n] = __builtin_amdgcn_mfma_f32_16x16x32_bf16(Bt[n][k], At[m][k], acc[ai][bj][m][n], 0, 0, 0); __builtin_amdgcn_s_setprio(0); } while (0)
; #define PG8_WAIT_V(n) asm volatile("s_waitcnt vmcnt(" #n ")" ::: "memory")
; #define PG8_WAIT_L(n) asm volatile("s_waitcnt lgkmcnt(" #n ")" ::: "memory")
; #define PG8_BAR __builtin_amdgcn_s_barrier()
; #define PG8_SCHED __builtin_amdgcn_sched_barrier(0)
; template <class Epi>
; DI void gemm_phase(LAS unsigned char* lds, const Gemm g, const StaticOrder& S, const Epi& E, int wv0) {
;     ...
;             PG8_LDB(B0, 0, 0); PG8_LDB(B1, 0, 1); PG8_SCHED; PG8_LDA(At, 0, 0); PG8_STAGE(PG8_SA(1, 1), a1 + hstepA, voffA);
;             PG8_WAIT_V(8); PG8_WAIT_L(0); PG8_BAR; PG8_MMA(0, 0, At, B0); PG8_MMA(0, 1, At, B1); PG8_BAR; PG8_SCHED;
;             PG8_LDA(At, 0, 1); PG8_STAGE(PG8_SB(0, 0), b2, voffB); PG8_STAGE(PG8_SB(0, 1), b2 + hstepB, voffB); PG8_STAGE(PG8_SA(0, 0), a2, voffA);
;             PG8_WAIT_V(8); PG8_WAIT_L(0); PG8_BAR; PG8_MMA(1, 0, At, B0); PG8_MMA(1, 1, At, B1); PG8_BAR; PG8_SCHED;
.LBB0_810:
	v_add_u32_e32 v14, s29, v140
	v_add_u32_e32 v30, s36, v140
	ds_read_b128 v[2:5], v14
	ds_read_b128 v[6:9], v14 offset:1024
	ds_read_b128 v[10:13], v14 offset:2048
	ds_read_b128 v[14:17], v14 offset:3072
	ds_read_b128 v[18:21], v30
	ds_read_b128 v[22:25], v30 offset:1024
	ds_read_b128 v[26:29], v30 offset:2048
	ds_read_b128 v[30:33], v30 offset:3072
	s_ashr_i32 s13, s12, 31
	s_lshl_b64 s[18:19], s[12:13], 16
	s_add_u32 s18, s27, s18
	s_addc_u32 s19, s28, s19
	s_and_b64 s[4:5], s[4:5], exec
	s_cselect_b32 s5, s19, s21
	s_cselect_b32 s4, s18, s20
	s_add_u32 s20, s22, 0xa0080
	s_addc_u32 s21, s23, 0
	v_lshl_add_u64 v[66:67], s[20:21], 0, v[130:131]
	s_add_i32 m0, s39, 0xc000
	ds_read_b128 v[34:37], v141
	ds_read_b128 v[38:41], v141 offset:1024
	ds_read_b128 v[42:45], v141 offset:2048
	ds_read_b128 v[46:49], v141 offset:3072
	ds_read_b128 v[50:53], v141 offset:4096
	ds_read_b128 v[54:57], v141 offset:5120
	ds_read_b128 v[58:61], v141 offset:6144
	ds_read_b128 v[62:65], v141 offset:7168
	global_load_lds_dwordx4 v[66:67], off
	v_lshl_add_u64 v[66:67], s[20:21], 0, v[132:133]
	s_add_i32 m0, s39, 0xe000
	s_nop 0
	global_load_lds_dwordx4 v[66:67], off
	s_waitcnt vmcnt(8)
	s_waitcnt lgkmcnt(0)
	s_barrier
	s_setprio 1
	s_waitcnt lgkmcnt(0)
	v_mfma_f32_16x16x32_bf16 v[66:69], v[2:5], v[34:37], 0
	v_mfma_f32_16x16x32_bf16 v[70:73], v[10:13], v[34:37], 0
	v_mfma_f32_16x16x32_bf16 v[74:77], v[2:5], v[42:45], 0
	v_mfma_f32_16x16x32_bf16 v[78:81], v[10:13], v[42:45], 0
	v_mfma_f32_16x16x32_bf16 v[82:85], v[2:5], v[50:53], 0
	v_mfma_f32_16x16x32_bf16 v[86:89], v[10:13], v[50:53], 0
	v_mfma_f32_16x16x32_bf16 v[90:93], v[2:5], v[58:61], 0
	v_mfma_f32_16x16x32_bf16 v[94:97], v[10:13], v[58:61], 0
	v_mfma_f32_16x16x32_bf16 v[66:69], v[6:9], v[38:41], v[66:69]
	v_mfma_f32_16x16x32_bf16 v[70:73], v[14:17], v[38:41], v[70:73]
	v_mfma_f32_16x16x32_bf16 v[74:77], v[6:9], v[46:49], v[74:77]
	v_mfma_f32_16x16x32_bf16 v[78:81], v[14:17], v[46:49], v[78:81]
	v_mfma_f32_16x16x32_bf16 v[82:85], v[6:9], v[54:57], v[82:85]
	v_mfma_f32_16x16x32_bf16 v[86:89], v[14:17], v[54:57], v[86:89]
	v_mfma_f32_16x16x32_bf16 v[90:93], v[6:9], v[62:65], v[90:93]
	v_mfma_f32_16x16x32_bf16 v[94:97], v[14:17], v[62:65], v[94:97]
	v_mfma_f32_16x16x32_bf16 v[98:101], v[18:21], v[34:37], 0
	v_mfma_f32_16x16x32_bf16 v[34:37], v[26:29], v[34:37], 0
	v_mfma_f32_16x16x32_bf16 v[106:109], v[22:25], v[38:41], v[98:101]
	v_mfma_f32_16x16x32_bf16 v[34:37], v[30:33], v[38:41], v[34:37]
	v_mfma_f32_16x16x32_bf16 v[38:41], v[18:21], v[42:45], 0
	v_mfma_f32_16x16x32_bf16 v[42:45], v[26:29], v[42:45], 0
	v_mfma_f32_16x16x32_bf16 v[38:41], v[22:25], v[46:49], v[38:41]
	v_mfma_f32_16x16x32_bf16 v[42:45], v[30:33], v[46:49], v[42:45]
	v_mfma_f32_16x16x32_bf16 v[46:49], v[18:21], v[50:53], 0
	v_mfma_f32_16x16x32_bf16 v[50:53], v[26:29], v[50:53], 0
	v_mfma_f32_16x16x32_bf16 v[136:139], v[30:33], v[54:57], v[50:53]
	v_mfma_f32_16x16x32_bf16 v[50:53], v[18:21], v[58:61], 0
	v_mfma_f32_16x16x32_bf16 v[142:145], v[22:25], v[62:65], v[50:53]
	v_mfma_f32_16x16x32_bf16 v[50:53], v[26:29], v[58:61], 0
	v_mfma_f32_16x16x32_bf16 v[46:49], v[22:25], v[54:57], v[46:49]
	v_mfma_f32_16x16x32_bf16 v[62:65], v[30:33], v[62:65], v[50:53]
	s_setprio 0
	s_barrier
	s_mov_b32 m0, s30
	v_lshl_add_u64 v[154:155], s[4:5], 0, v[0:1]
	s_add_u32 s20, s4, 0x8000
	s_nop 0
	ds_read_b128 v[50:53], v141 offset:16384
	ds_read_b128 v[54:57], v141 offset:17408
	ds_read_b128 v[58:61], v141 offset:18432
	ds_read_b128 v[98:101], v141 offset:19456
	ds_read_b128 v[102:105], v141 offset:20480
	ds_read_b128 v[110:113], v141 offset:21504
	ds_read_b128 v[114:117], v141 offset:22528
	ds_read_b128 v[118:121], v141 offset:23552
	global_load_lds_dwordx4 v[154:155], off
	v_lshl_add_u64 v[174:175], s[4:5], 0, v[134:135]
	s_mov_b32 m0, s31
	s_addc_u32 s21, s5, 0
	global_load_lds_dwordx4 v[174:175], off
	v_lshl_add_u64 v[122:123], s[20:21], 0, v[0:1]
	s_mov_b32 m0, s37
	v_lshl_add_u64 v[198:199], s[16:17], 0, v[130:131]
	global_load_lds_dwordx4 v[122:123], off
	v_lshl_add_u64 v[122:123], s[20:21], 0, v[134:135]
	s_mov_b32 m0, s38
	v_lshl_add_u64 v[202:203], s[16:17], 0, v[132:133]
	global_load_lds_dwordx4 v[122:123], off
	s_mov_b32 m0, s39
	s_nop 0
	global_load_lds_dwordx4 v[198:199], off
	s_mov_b32 m0, s40
	s_nop 0
	global_load_lds_dwordx4 v[202:203], off
	s_waitcnt vmcnt(8)
	s_waitcnt lgkmcnt(0)
	s_barrier
	s_setprio 1
	s_waitcnt lgkmcnt(0)
	v_mfma_f32_16x16x32_bf16 v[122:125], v[2:5], v[50:53], 0
	v_mfma_f32_16x16x32_bf16 v[146:149], v[6:9], v[54:57], v[122:125]
	v_mfma_f32_16x16x32_bf16 v[122:125], v[10:13], v[50:53], 0
	v_mfma_f32_16x16x32_bf16 v[150:153], v[14:17], v[54:57], v[122:125]
	v_mfma_f32_16x16x32_bf16 v[122:125], v[2:5], v[58:61], 0
	v_mfma_f32_16x16x32_bf16 v[178:181], v[6:9], v[98:101], v[122:125]
	v_mfma_f32_16x16x32_bf16 v[122:125], v[10:13], v[58:61], 0
	v_mfma_f32_16x16x32_bf16 v[182:185], v[14:17], v[98:101], v[122:125]
	v_mfma_f32_16x16x32_bf16 v[122:125], v[2:5], v[102:105], 0
	v_mfma_f32_16x16x32_bf16 v[2:5], v[2:5], v[114:117], 0
	v_mfma_f32_16x16x32_bf16 v[186:189], v[6:9], v[110:113], v[122:125]
	v_mfma_f32_16x16x32_bf16 v[2:5], v[6:9], v[118:121], v[2:5]
	v_mfma_f32_16x16x32_bf16 v[6:9], v[10:13], v[114:117], 0
	v_mfma_f32_16x16x32_bf16 v[122:125], v[10:13], v[102:105], 0
	v_mfma_f32_16x16x32_bf16 v[6:9], v[14:17], v[118:121], v[6:9]
	v_mfma_f32_16x16x32_bf16 v[190:193], v[14:17], v[110:113], v[122:125]
	v_mfma_f32_16x16x32_bf16 v[10:13], v[18:21], v[50:53], 0
	v_mfma_f32_16x16x32_bf16 v[14:17], v[26:29], v[50:53], 0
	v_mfma_f32_16x16x32_bf16 v[50:53], v[18:21], v[58:61], 0
	v_mfma_f32_16x16x32_bf16 v[194:197], v[22:25], v[98:101], v[50:53]
	v_mfma_f32_16x16x32_bf16 v[50:53], v[26:29], v[58:61], 0
	v_mfma_f32_16x16x32_bf16 v[210:213], v[30:33], v[98:101], v[50:53]
	v_mfma_f32_16x16x32_bf16 v[50:53], v[18:21], v[102:105], 0
	v_mfma_f32_16x16x32_bf16 v[18:21], v[18:21], v[114:117], 0
	v_mfma_f32_16x16x32_bf16 v[10:13], v[22:25], v[54:57], v[10:13]
	v_mfma_f32_16x16x32_bf16 v[14:17], v[30:33], v[54:57], v[14:17]
	v_mfma_f32_16x16x32_bf16 v[214:217], v[22:25], v[110:113], v[50:53]
	v_mfma_f32_16x16x32_bf16 v[50:53], v[26:29], v[102:105], 0
	v_mfma_f32_16x16x32_bf16 v[222:225], v[22:25], v[118:121], v[18:21]
	v_mfma_f32_16x16x32_bf16 v[18:21], v[26:29], v[114:117], 0
	v_mfma_f32_16x16x32_bf16 v[218:221], v[30:33], v[110:113], v[50:53]
	v_mfma_f32_16x16x32_bf16 v[226:229], v[30:33], v[118:121], v[18:21]
	s_setprio 0
	s_barrier
; DI int fresh_tid2(int wv) { unsigned z_ = 0u; asm volatile("" : "+v"(z_)); const int l_ = (int)__builtin_amdgcn_mbcnt_hi(~0u, __builtin_amdgcn_mbcnt_lo(~0u, z_)); return (wv << 6) | l_; }
; #define PG8_STAGE(bufoff, gbase, voff) do { _Pragma("unroll") for (int _i = 0; _i < 2; ++_i) \
;         __builtin_amdgcn_global_load_lds((const unsigned*)((const char*)(gbase) + (voff)[_i]), (LAS unsigned*)(lds + (bufoff) + ldsw + _i * 8192), 16, 0, 0); } while (0)
; #define PG8_LDA(dst, b, h) do { _Pragma("unroll") for (int m = 0; m < 4; ++m) _Pragma("unroll") for (int k = 0; k < 2; ++k) dst[m][k] = *(const LAS bf16x8*)(lds + PG8_SA(b, h) + aoff + m * 2048 + k * 1024); } while (0)
; #define PG8_LDB(dst, b, h) do { _Pragma("unroll") for (int n = 0; n < 2; ++n) _Pragma("unroll") for (int k = 0; k < 2; ++k) dst[n][k] = *(const LAS bf16x8*)(lds + PG8_SB(b, h) + boff + n * 2048 + k * 1024); } while (0)
; #define PG8_MMA(ai, bj, At, Bt) do { __builtin_amdgcn_s_setprio(1); _Pragma("unroll") for (int m = 0; m < 4; ++m) _Pragma("unroll") for (int n = 0; n < 2; ++n) _Pragma("unroll") for (int k = 0; k < 2; ++k) \
;         acc[ai][bj][m][n] = __builtin_amdgcn_mfma_f32_16x16x32_bf16(Bt[n][k], At[m][k], acc[ai][bj][m][n], 0, 0, 0); __builtin_amdgcn_s_setprio(0); } while (0)
; #define PG8_WAIT_V(n) asm volatile("s_waitcnt vmcnt(" #n ")" ::: "memory")
; #define PG8_WAIT_L(n) asm volatile("s_waitcnt lgkmcnt(" #n ")" ::: "memory")
; #define PG8_BAR __builtin_amdgcn_s_barrier()
; #define PG8_SCHED __builtin_amdgcn_sched_barrier(0)
; template <class Epi>
; DI void gemm_phase(LAS unsigned char* lds, const Gemm g, const StaticOrder& S, const Epi& E, int wv0) {
;     ...
;             PG8_LDB(B0, 1, 0); PG8_LDB(B1, 1, 1); PG8_SCHED; PG8_LDA(At, 1, 0); PG8_STAGE(PG8_SA(0, 1), a2 + hstepA, voffA);
;             PG8_WAIT_V(8); PG8_WAIT_L(0); PG8_BAR; PG8_MMA(0, 0, At, B0); PG8_MMA(0, 1, At, B1); PG8_BAR; PG8_SCHED;
;             PG8_LDA(At, 1, 1); PG8_STAGE(PG8_SB(1, 0), b3, voffB); PG8_STAGE(PG8_SB(1, 1), b3 + hstepB, voffB); PG8_STAGE(PG8_SA(1, 0), a3, voffA);
;             PG8_WAIT_V(8); PG8_WAIT_L(0); PG8_BAR; PG8_MMA(1, 0, At, B0); PG8_MMA(1, 1, At, B1); PG8_BAR; PG8_SCHED;
;         }
;         if (wr == 0) PG8_BAR;
;         { const int l2_ = fresh_tid2(wv0) & 63; E(acc, cur, wr, wc, l2_ & 15, l2_ >> 4); }
;         if (!has_next) break;
	s_nop 3
	v_add_u32_e32 v18, s45, v140
	ds_read_b128 v[26:29], v18
	ds_read_b128 v[30:33], v18 offset:1024
	ds_read_b128 v[230:233], v18 offset:2048
	ds_read_b128 v[234:237], v18 offset:3072
	v_add_u32_e32 v18, s50, v140
	ds_read_b128 v[238:241], v18
	ds_read_b128 v[242:245], v18 offset:1024
	ds_read_b128 v[246:249], v18 offset:2048
	ds_read_b128 v[250:253], v18 offset:3072
	s_add_u32 s20, s16, 0xa0000
	s_addc_u32 s21, s17, 0
	s_mov_b32 m0, s41
	v_lshl_add_u64 v[50:51], s[20:21], 0, v[130:131]
	ds_read_b128 v[18:21], v141 offset:32768
	ds_read_b128 v[22:25], v141 offset:33792
	ds_read_b128 v[58:61], v141 offset:34816
	ds_read_b128 v[110:113], v141 offset:35840
	ds_read_b128 v[166:169], v141 offset:36864
	ds_read_b128 v[158:161], v141 offset:37888
	ds_read_b128 v[170:173], v141 offset:38912
	ds_read_b128 v[162:165], v141 offset:39936
	global_load_lds_dwordx4 v[50:51], off
	v_lshl_add_u64 v[50:51], s[20:21], 0, v[132:133]
	s_mov_b32 m0, s42
	s_nop 0
	global_load_lds_dwordx4 v[50:51], off
	s_waitcnt vmcnt(8)
	s_waitcnt lgkmcnt(0)
	s_barrier
	s_setprio 1
	s_waitcnt lgkmcnt(0)
	v_mfma_f32_16x16x32_bf16 v[50:53], v[26:29], v[18:21], v[66:69]
	v_mfma_f32_16x16x32_bf16 v[122:125], v[30:33], v[22:25], v[50:53]
	v_mfma_f32_16x16x32_bf16 v[50:53], v[230:233], v[18:21], v[70:73]
	v_mfma_f32_16x16x32_bf16 v[126:129], v[234:237], v[22:25], v[50:53]
	v_mfma_f32_16x16x32_bf16 v[50:53], v[26:29], v[58:61], v[74:77]
	v_mfma_f32_16x16x32_bf16 v[98:101], v[30:33], v[110:113], v[50:53]
	v_mfma_f32_16x16x32_bf16 v[50:53], v[230:233], v[58:61], v[78:81]
	v_mfma_f32_16x16x32_bf16 v[102:105], v[234:237], v[110:113], v[50:53]
	v_mfma_f32_16x16x32_bf16 v[50:53], v[26:29], v[166:169], v[82:85]
	v_mfma_f32_16x16x32_bf16 v[82:85], v[30:33], v[158:161], v[50:53]
	v_mfma_f32_16x16x32_bf16 v[50:53], v[230:233], v[166:169], v[86:89]
	v_mfma_f32_16x16x32_bf16 v[86:89], v[234:237], v[158:161], v[50:53]
	v_mfma_f32_16x16x32_bf16 v[50:53], v[26:29], v[170:173], v[90:93]
	v_mfma_f32_16x16x32_bf16 v[54:57], v[230:233], v[170:173], v[94:97]
	v_mfma_f32_16x16x32_bf16 v[50:53], v[30:33], v[162:165], v[50:53]
	v_mfma_f32_16x16x32_bf16 v[54:57], v[234:237], v[162:165], v[54:57]
	v_mfma_f32_16x16x32_bf16 v[66:69], v[238:241], v[18:21], v[106:109]
	v_mfma_f32_16x16x32_bf16 v[18:21], v[246:249], v[18:21], v[34:37]
	v_mfma_f32_16x16x32_bf16 v[118:121], v[250:253], v[22:25], v[18:21]
	v_mfma_f32_16x16x32_bf16 v[18:21], v[238:241], v[58:61], v[38:41]
	v_mfma_f32_16x16x32_bf16 v[106:109], v[242:245], v[110:113], v[18:21]
	v_mfma_f32_16x16x32_bf16 v[18:21], v[246:249], v[58:61], v[42:45]
	v_mfma_f32_16x16x32_bf16 v[110:113], v[250:253], v[110:113], v[18:21]
	v_mfma_f32_16x16x32_bf16 v[18:21], v[238:241], v[166:169], v[46:49]
	v_mfma_f32_16x16x32_bf16 v[90:93], v[242:245], v[158:161], v[18:21]
	v_mfma_f32_16x16x32_bf16 v[18:21], v[246:249], v[166:169], v[136:139]
	v_mfma_f32_16x16x32_bf16 v[94:97], v[250:253], v[158:161], v[18:21]
	v_mfma_f32_16x16x32_bf16 v[18:21], v[238:241], v[170:173], v[142:145]
	v_mfma_f32_16x16x32_bf16 v[58:61], v[242:245], v[162:165], v[18:21]
	v_mfma_f32_16x16x32_bf16 v[18:21], v[246:249], v[170:173], v[62:65]
	v_mfma_f32_16x16x32_bf16 v[114:117], v[242:245], v[22:25], v[66:69]
	v_mfma_f32_16x16x32_bf16 v[62:65], v[250:253], v[162:165], v[18:21]
	s_setprio 0
	s_barrier
	s_mov_b32 m0, s46
	s_nop 2
	v_lshl_add_u64 v[18:19], v[154:155], 0, s[86:87]
	s_add_u32 s4, s4, 0x8080
	ds_read_b128 v[42:45], v141 offset:49152
	ds_read_b128 v[46:49], v141 offset:50176
	ds_read_b128 v[136:139], v141 offset:51200
	ds_read_b128 v[142:145], v141 offset:52224
	ds_read_b128 v[158:161], v141 offset:53248
	ds_read_b128 v[162:165], v141 offset:54272
	ds_read_b128 v[166:169], v141 offset:55296
	ds_read_b128 v[170:173], v141 offset:56320
	global_load_lds_dwordx4 v[18:19], off
	v_lshl_add_u64 v[18:19], v[174:175], 0, s[86:87]
	s_mov_b32 m0, s47
	s_addc_u32 s5, s5, 0
	global_load_lds_dwordx4 v[18:19], off
	v_lshl_add_u64 v[18:19], s[4:5], 0, v[0:1]
	s_mov_b32 m0, s51
	s_nop 0
	global_load_lds_dwordx4 v[18:19], off
	v_lshl_add_u64 v[18:19], s[4:5], 0, v[134:135]
	s_mov_b32 m0, s52
	s_nop 0
	global_load_lds_dwordx4 v[18:19], off
	v_lshl_add_u64 v[18:19], v[198:199], 0, s[86:87]
	s_mov_b32 m0, s48
	s_nop 0
	global_load_lds_dwordx4 v[18:19], off
	v_lshl_add_u64 v[18:19], v[202:203], 0, s[86:87]
	s_mov_b32 m0, s49
	s_nop 0
	global_load_lds_dwordx4 v[18:19], off
	s_waitcnt vmcnt(8)
	s_waitcnt lgkmcnt(0)
	s_barrier
	s_setprio 1
	s_waitcnt lgkmcnt(0)
	v_mfma_f32_16x16x32_bf16 v[18:21], v[26:29], v[42:45], v[146:149]
	v_mfma_f32_16x16x32_bf16 v[66:69], v[30:33], v[46:49], v[18:21]
	v_mfma_f32_16x16x32_bf16 v[18:21], v[230:233], v[42:45], v[150:153]
	v_mfma_f32_16x16x32_bf16 v[70:73], v[234:237], v[46:49], v[18:21]
	v_mfma_f32_16x16x32_bf16 v[18:21], v[26:29], v[136:139], v[178:181]
	v_mfma_f32_16x16x32_bf16 v[34:37], v[30:33], v[142:145], v[18:21]
	v_mfma_f32_16x16x32_bf16 v[18:21], v[230:233], v[136:139], v[182:185]
	v_mfma_f32_16x16x32_bf16 v[38:41], v[234:237], v[142:145], v[18:21]
	v_mfma_f32_16x16x32_bf16 v[18:21], v[26:29], v[158:161], v[186:189]
	v_mfma_f32_16x16x32_bf16 v[22:25], v[230:233], v[158:161], v[190:193]
	v_mfma_f32_16x16x32_bf16 v[2:5], v[26:29], v[166:169], v[2:5]
	v_mfma_f32_16x16x32_bf16 v[6:9], v[230:233], v[166:169], v[6:9]
	v_mfma_f32_16x16x32_bf16 v[18:21], v[30:33], v[162:165], v[18:21]
	v_mfma_f32_16x16x32_bf16 v[22:25], v[234:237], v[162:165], v[22:25]
	v_mfma_f32_16x16x32_bf16 v[2:5], v[30:33], v[170:173], v[2:5]
	v_mfma_f32_16x16x32_bf16 v[6:9], v[234:237], v[170:173], v[6:9]
	v_mfma_f32_16x16x32_bf16 v[10:13], v[238:241], v[42:45], v[10:13]
	v_mfma_f32_16x16x32_bf16 v[74:77], v[242:245], v[46:49], v[10:13]
	v_mfma_f32_16x16x32_bf16 v[10:13], v[246:249], v[42:45], v[14:17]
	v_mfma_f32_16x16x32_bf16 v[78:81], v[250:253], v[46:49], v[10:13]
	v_mfma_f32_16x16x32_bf16 v[10:13], v[238:241], v[136:139], v[194:197]
	v_mfma_f32_16x16x32_bf16 v[42:45], v[242:245], v[142:145], v[10:13]
	v_mfma_f32_16x16x32_bf16 v[10:13], v[246:249], v[136:139], v[210:213]
	v_mfma_f32_16x16x32_bf16 v[46:49], v[250:253], v[142:145], v[10:13]
	v_mfma_f32_16x16x32_bf16 v[10:13], v[238:241], v[158:161], v[214:217]
	v_mfma_f32_16x16x32_bf16 v[26:29], v[242:245], v[162:165], v[10:13]
	v_mfma_f32_16x16x32_bf16 v[10:13], v[246:249], v[158:161], v[218:221]
	v_mfma_f32_16x16x32_bf16 v[30:33], v[250:253], v[162:165], v[10:13]
	v_mfma_f32_16x16x32_bf16 v[10:13], v[238:241], v[166:169], v[222:225]
	v_mfma_f32_16x16x32_bf16 v[14:17], v[246:249], v[166:169], v[226:229]
	v_mfma_f32_16x16x32_bf16 v[10:13], v[242:245], v[170:173], v[10:13]
	v_mfma_f32_16x16x32_bf16 v[14:17], v[250:253], v[170:173], v[14:17]
	s_setprio 0
	s_barrier
	s_andn2_b64 vcc, exec, s[8:9]
	s_cbranch_vccnz .LBB0_812
	s_barrier

; #define PG8_STAGE(bufoff, gbase, voff) do { _Pragma("unroll") for (int _i = 0; _i < 2; ++_i) \
;         __builtin_amdgcn_global_load_lds((const unsigned*)((const char*)(gbase) + (voff)[_i]), (LAS unsigned*)(lds + (bufoff) + ldsw + _i * 8192), 16, 0, 0); } while (0)
; #define PG8_LDA(dst, b, h) do { _Pragma("unroll") for (int m = 0; m < 4; ++m) _Pragma("unroll") for (int k = 0; k < 2; ++k) dst[m][k] = *(const LAS bf16x8*)(lds + PG8_SA(b, h) + aoff + m * 2048 + k * 1024); } while (0)
; #define PG8_LDB(dst, b, h) do { _Pragma("unroll") for (int n = 0; n < 2; ++n) _Pragma("unroll") for (int k = 0; k < 2; ++k) dst[n][k] = *(const LAS bf16x8*)(lds + PG8_SB(b, h) + boff + n * 2048 + k * 1024); } while (0)
; #define PG8_MMA(ai, bj, At, Bt) do { __builtin_amdgcn_s_setprio(1); _Pragma("unroll") for (int m = 0; m < 4; ++m) _Pragma("unroll") for (int n = 0; n < 2; ++n) _Pragma("unroll") for (int k = 0; k < 2; ++k) \
;         acc[ai][bj][m][n] = __builtin_amdgcn_mfma_f32_16x16x32_bf16(Bt[n][k], At[m][k], acc[ai][bj][m][n], 0, 0, 0); __builtin_amdgcn_s_setprio(0); } while (0)
; #define PG8_WAIT_V(n) asm volatile("s_waitcnt vmcnt(" #n ")" ::: "memory")
; #define PG8_WAIT_L(n) asm volatile("s_waitcnt lgkmcnt(" #n ")" ::: "memory")
; #define PG8_BAR __builtin_amdgcn_s_barrier()
; #define PG8_SCHED __builtin_amdgcn_sched_barrier(0)
; template <class Epi>
; DI void gemm_phase(LAS unsigned char* lds, const Gemm g, const StaticOrder& S, const Epi& E, int wv0) {
;     ...
;             const bool last = (t == nt - 2);
;             const char* a1 = cA + (size_t)(t + 1) * kstep;
;             const char* a2 = last ? nA : cA + (size_t)(t + 2) * kstep; const char* b2 = last ? nB : cB + (size_t)(t + 2) * kstep;
;             const char* a3 = a2 + kstep; const char* b3 = b2 + kstep;
;             PG8_LDB(B0, 0, 0); PG8_LDB(B1, 0, 1); PG8_SCHED; PG8_LDA(At, 0, 0); PG8_STAGE(PG8_SA(1, 1), a1 + hstepA, voffA);
;             PG8_WAIT_V(8); PG8_WAIT_L(0); PG8_BAR; PG8_MMA(0, 0, At, B0); PG8_MMA(0, 1, At, B1); PG8_BAR; PG8_SCHED;
;             PG8_LDA(At, 0, 1); PG8_STAGE(PG8_SB(0, 0), b2, voffB); PG8_STAGE(PG8_SB(0, 1), b2 + hstepB, voffB); PG8_STAGE(PG8_SA(0, 0), a2, voffA);
.LBB0_868:
	v_add_u32_e32 v150, s36, v136
	v_add_u32_e32 v154, s39, v136
	ds_read_b128 v[138:141], v150
	ds_read_b128 v[142:145], v150 offset:1024
	ds_read_b128 v[146:149], v150 offset:2048
	ds_read_b128 v[150:153], v150 offset:3072
	ds_read_b128 v[158:161], v154
	ds_read_b128 v[162:165], v154 offset:1024
	ds_read_b128 v[166:169], v154 offset:2048
	ds_read_b128 v[170:173], v154 offset:3072
	s_add_u32 s22, s20, 0xfff80080
	s_addc_u32 s23, s21, -1
	s_cmp_eq_u32 s62, 4
	s_cselect_b32 s25, s15, s23
	s_cselect_b32 s24, s58, s22
	s_cselect_b32 s23, s13, s61
	s_cselect_b32 s22, s59, s60
	v_lshl_add_u64 v[154:155], s[20:21], 0, v[134:135]
	s_add_i32 m0, s42, 0xc000
	ds_read_b128 v[178:181], v137
	ds_read_b128 v[182:185], v137 offset:1024
	ds_read_b128 v[186:189], v137 offset:2048
	ds_read_b128 v[190:193], v137 offset:3072
	ds_read_b128 v[194:197], v137 offset:4096
	ds_read_b128 v[210:213], v137 offset:5120
	ds_read_b128 v[214:217], v137 offset:6144
	ds_read_b128 v[218:221], v137 offset:7168
	global_load_lds_dwordx4 v[154:155], off
	v_lshl_add_u64 v[154:155], s[20:21], 0, v[132:133]
	s_add_i32 m0, s42, 0xe000
	s_nop 0
	global_load_lds_dwordx4 v[154:155], off
	s_waitcnt vmcnt(8)
	s_waitcnt lgkmcnt(0)
	s_barrier
	s_setprio 1
	s_waitcnt lgkmcnt(0)
	v_mfma_f32_16x16x32_bf16 v[126:129], v[138:141], v[178:181], v[126:129]
	v_mfma_f32_16x16x32_bf16 v[122:125], v[146:149], v[178:181], v[122:125]
	v_mfma_f32_16x16x32_bf16 v[118:121], v[138:141], v[186:189], v[118:121]
	v_mfma_f32_16x16x32_bf16 v[114:117], v[146:149], v[186:189], v[114:117]
	v_mfma_f32_16x16x32_bf16 v[102:105], v[138:141], v[194:197], v[102:105]
	v_mfma_f32_16x16x32_bf16 v[98:101], v[146:149], v[194:197], v[98:101]
	v_mfma_f32_16x16x32_bf16 v[86:89], v[138:141], v[214:217], v[86:89]
	v_mfma_f32_16x16x32_bf16 v[82:85], v[146:149], v[214:217], v[82:85]
	v_mfma_f32_16x16x32_bf16 v[126:129], v[142:145], v[182:185], v[126:129]
	v_mfma_f32_16x16x32_bf16 v[122:125], v[150:153], v[182:185], v[122:125]
	v_mfma_f32_16x16x32_bf16 v[118:121], v[142:145], v[190:193], v[118:121]
	v_mfma_f32_16x16x32_bf16 v[114:117], v[150:153], v[190:193], v[114:117]
	v_mfma_f32_16x16x32_bf16 v[102:105], v[142:145], v[210:213], v[102:105]
	v_mfma_f32_16x16x32_bf16 v[98:101], v[150:153], v[210:213], v[98:101]
	v_mfma_f32_16x16x32_bf16 v[86:89], v[142:145], v[218:221], v[86:89]
	v_mfma_f32_16x16x32_bf16 v[82:85], v[150:153], v[218:221], v[82:85]
	v_mfma_f32_16x16x32_bf16 v[110:113], v[158:161], v[178:181], v[110:113]
	v_mfma_f32_16x16x32_bf16 v[106:109], v[166:169], v[178:181], v[106:109]
	v_mfma_f32_16x16x32_bf16 v[94:97], v[158:161], v[186:189], v[94:97]
	v_mfma_f32_16x16x32_bf16 v[90:93], v[166:169], v[186:189], v[90:93]
	v_mfma_f32_16x16x32_bf16 v[78:81], v[158:161], v[194:197], v[78:81]
	v_mfma_f32_16x16x32_bf16 v[74:77], v[166:169], v[194:197], v[74:77]
	v_mfma_f32_16x16x32_bf16 v[70:73], v[158:161], v[214:217], v[70:73]
	v_mfma_f32_16x16x32_bf16 v[66:69], v[166:169], v[214:217], v[66:69]
	v_mfma_f32_16x16x32_bf16 v[110:113], v[162:165], v[182:185], v[110:113]
	v_mfma_f32_16x16x32_bf16 v[106:109], v[170:173], v[182:185], v[106:109]
	v_mfma_f32_16x16x32_bf16 v[94:97], v[162:165], v[190:193], v[94:97]
	v_mfma_f32_16x16x32_bf16 v[90:93], v[170:173], v[190:193], v[90:93]
	v_mfma_f32_16x16x32_bf16 v[78:81], v[162:165], v[210:213], v[78:81]
	v_mfma_f32_16x16x32_bf16 v[74:77], v[170:173], v[210:213], v[74:77]
	v_mfma_f32_16x16x32_bf16 v[70:73], v[162:165], v[218:221], v[70:73]
	v_mfma_f32_16x16x32_bf16 v[66:69], v[170:173], v[218:221], v[66:69]
	s_setprio 0
	s_barrier
	s_mov_b32 m0, s37
	v_lshl_add_u64 v[154:155], s[22:23], 0, v[0:1]
	s_add_u32 s64, s22, 0x80000
	ds_read_b128 v[178:181], v137 offset:16384
	ds_read_b128 v[182:185], v137 offset:17408
	ds_read_b128 v[186:189], v137 offset:18432
	ds_read_b128 v[190:193], v137 offset:19456
	ds_read_b128 v[194:197], v137 offset:20480
	ds_read_b128 v[210:213], v137 offset:21504
	ds_read_b128 v[214:217], v137 offset:22528
	ds_read_b128 v[218:221], v137 offset:23552
	global_load_lds_dwordx4 v[154:155], off
	v_lshl_add_u64 v[174:175], s[22:23], 0, v[130:131]
	s_mov_b32 m0, s38
	s_addc_u32 s65, s23, 0
	global_load_lds_dwordx4 v[174:175], off
	v_lshl_add_u64 v[198:199], s[64:65], 0, v[0:1]
	s_mov_b32 m0, s40
	v_lshl_add_u64 v[202:203], s[24:25], 0, v[130:131]
	global_load_lds_dwordx4 v[198:199], off
	v_lshl_add_u64 v[198:199], s[64:65], 0, v[130:131]
	s_mov_b32 m0, s41
	s_nop 0
	global_load_lds_dwordx4 v[198:199], off
	v_lshl_add_u64 v[198:199], s[24:25], 0, v[0:1]
	s_mov_b32 m0, s42
	s_nop 0
	global_load_lds_dwordx4 v[198:199], off
	s_mov_b32 m0, s43
	s_nop 0
	global_load_lds_dwordx4 v[202:203], off
	s_waitcnt vmcnt(8)
	s_waitcnt lgkmcnt(0)
	s_barrier
; #define PG8_STAGE(bufoff, gbase, voff) do { _Pragma("unroll") for (int _i = 0; _i < 2; ++_i) \
;         __builtin_amdgcn_global_load_lds((const unsigned*)((const char*)(gbase) + (voff)[_i]), (LAS unsigned*)(lds + (bufoff) + ldsw + _i * 8192), 16, 0, 0); } while (0)
; #define PG8_LDA(dst, b, h) do { _Pragma("unroll") for (int m = 0; m < 4; ++m) _Pragma("unroll") for (int k = 0; k < 2; ++k) dst[m][k] = *(const LAS bf16x8*)(lds + PG8_SA(b, h) + aoff + m * 2048 + k * 1024); } while (0)
; #define PG8_LDB(dst, b, h) do { _Pragma("unroll") for (int n = 0; n < 2; ++n) _Pragma("unroll") for (int k = 0; k < 2; ++k) dst[n][k] = *(const LAS bf16x8*)(lds + PG8_SB(b, h) + boff + n * 2048 + k * 1024); } while (0)
; #define PG8_MMA(ai, bj, At, Bt) do { __builtin_amdgcn_s_setprio(1); _Pragma("unroll") for (int m = 0; m < 4; ++m) _Pragma("unroll") for (int n = 0; n < 2; ++n) _Pragma("unroll") for (int k = 0; k < 2; ++k) \
;         acc[ai][bj][m][n] = __builtin_amdgcn_mfma_f32_16x16x32_bf16(Bt[n][k], At[m][k], acc[ai][bj][m][n], 0, 0, 0); __builtin_amdgcn_s_setprio(0); } while (0)
; #define PG8_WAIT_V(n) asm volatile("s_waitcnt vmcnt(" #n ")" ::: "memory")
; #define PG8_WAIT_L(n) asm volatile("s_waitcnt lgkmcnt(" #n ")" ::: "memory")
; #define PG8_BAR __builtin_amdgcn_s_barrier()
; #define PG8_SCHED __builtin_amdgcn_sched_barrier(0)
; template <class Epi>
; DI void gemm_phase(LAS unsigned char* lds, const Gemm g, const StaticOrder& S, const Epi& E, int wv0) {
;     ...
;             PG8_WAIT_V(8); PG8_WAIT_L(0); PG8_BAR; PG8_MMA(1, 0, At, B0); PG8_MMA(1, 1, At, B1); PG8_BAR; PG8_SCHED;
;             PG8_LDB(B0, 1, 0); PG8_LDB(B1, 1, 1); PG8_SCHED; PG8_LDA(At, 1, 0); PG8_STAGE(PG8_SA(0, 1), a2 + hstepA, voffA);
;             PG8_WAIT_V(8); PG8_WAIT_L(0); PG8_BAR; PG8_MMA(0, 0, At, B0); PG8_MMA(0, 1, At, B1); PG8_BAR; PG8_SCHED;
	s_setprio 1
	s_waitcnt lgkmcnt(0)
	v_mfma_f32_16x16x32_bf16 v[62:65], v[138:141], v[178:181], v[62:65]
	v_mfma_f32_16x16x32_bf16 v[58:61], v[146:149], v[178:181], v[58:61]
	v_mfma_f32_16x16x32_bf16 v[54:57], v[138:141], v[186:189], v[54:57]
	v_mfma_f32_16x16x32_bf16 v[50:53], v[146:149], v[186:189], v[50:53]
	v_mfma_f32_16x16x32_bf16 v[38:41], v[138:141], v[194:197], v[38:41]
	v_mfma_f32_16x16x32_bf16 v[34:37], v[146:149], v[194:197], v[34:37]
	v_mfma_f32_16x16x32_bf16 v[22:25], v[138:141], v[214:217], v[22:25]
	v_mfma_f32_16x16x32_bf16 v[18:21], v[146:149], v[214:217], v[18:21]
	v_mfma_f32_16x16x32_bf16 v[62:65], v[142:145], v[182:185], v[62:65]
	v_mfma_f32_16x16x32_bf16 v[58:61], v[150:153], v[182:185], v[58:61]
	v_mfma_f32_16x16x32_bf16 v[54:57], v[142:145], v[190:193], v[54:57]
	v_mfma_f32_16x16x32_bf16 v[50:53], v[150:153], v[190:193], v[50:53]
	v_mfma_f32_16x16x32_bf16 v[38:41], v[142:145], v[210:213], v[38:41]
	v_mfma_f32_16x16x32_bf16 v[34:37], v[150:153], v[210:213], v[34:37]
	v_mfma_f32_16x16x32_bf16 v[22:25], v[142:145], v[218:221], v[22:25]
	v_mfma_f32_16x16x32_bf16 v[18:21], v[150:153], v[218:221], v[18:21]
	v_mfma_f32_16x16x32_bf16 v[46:49], v[158:161], v[178:181], v[46:49]
	v_mfma_f32_16x16x32_bf16 v[42:45], v[166:169], v[178:181], v[42:45]
	v_mfma_f32_16x16x32_bf16 v[30:33], v[158:161], v[186:189], v[30:33]
	v_mfma_f32_16x16x32_bf16 v[26:29], v[166:169], v[186:189], v[26:29]
	v_mfma_f32_16x16x32_bf16 v[14:17], v[158:161], v[194:197], v[14:17]
	v_mfma_f32_16x16x32_bf16 v[10:13], v[166:169], v[194:197], v[10:13]
	v_mfma_f32_16x16x32_bf16 v[6:9], v[158:161], v[214:217], v[6:9]
	v_mfma_f32_16x16x32_bf16 v[2:5], v[166:169], v[214:217], v[2:5]
	v_mfma_f32_16x16x32_bf16 v[46:49], v[162:165], v[182:185], v[46:49]
	v_mfma_f32_16x16x32_bf16 v[42:45], v[170:173], v[182:185], v[42:45]
	v_mfma_f32_16x16x32_bf16 v[30:33], v[162:165], v[190:193], v[30:33]
	v_mfma_f32_16x16x32_bf16 v[26:29], v[170:173], v[190:193], v[26:29]
	v_mfma_f32_16x16x32_bf16 v[14:17], v[162:165], v[210:213], v[14:17]
	v_mfma_f32_16x16x32_bf16 v[10:13], v[170:173], v[210:213], v[10:13]
	v_mfma_f32_16x16x32_bf16 v[6:9], v[162:165], v[218:221], v[6:9]
	v_mfma_f32_16x16x32_bf16 v[2:5], v[170:173], v[218:221], v[2:5]
	s_setprio 0
	s_barrier
	v_add_u32_e32 v150, s48, v136
	v_add_u32_e32 v170, s53, v136
	ds_read_b128 v[138:141], v150
	ds_read_b128 v[142:145], v150 offset:1024
	ds_read_b128 v[146:149], v150 offset:2048
	ds_read_b128 v[150:153], v150 offset:3072
	ds_read_b128 v[158:161], v170
	ds_read_b128 v[162:165], v170 offset:1024
	ds_read_b128 v[166:169], v170 offset:2048
	ds_read_b128 v[170:173], v170 offset:3072
	s_add_u32 s24, s24, 0x80000
	s_addc_u32 s25, s25, 0
	s_mov_b32 m0, s44
	v_lshl_add_u64 v[222:223], s[24:25], 0, v[0:1]
	ds_read_b128 v[178:181], v137 offset:32768
	ds_read_b128 v[182:185], v137 offset:33792
	ds_read_b128 v[186:189], v137 offset:34816
	ds_read_b128 v[190:193], v137 offset:35840
	ds_read_b128 v[194:197], v137 offset:36864
	ds_read_b128 v[210:213], v137 offset:37888
	ds_read_b128 v[214:217], v137 offset:38912
	ds_read_b128 v[218:221], v137 offset:39936
	global_load_lds_dwordx4 v[222:223], off
	v_lshl_add_u64 v[222:223], s[24:25], 0, v[130:131]
	s_mov_b32 m0, s45
	s_nop 0
	global_load_lds_dwordx4 v[222:223], off
	s_waitcnt vmcnt(8)
	s_waitcnt lgkmcnt(0)
	s_barrier
	s_setprio 1
	s_waitcnt lgkmcnt(0)
	v_mfma_f32_16x16x32_bf16 v[126:129], v[138:141], v[178:181], v[126:129]
	v_mfma_f32_16x16x32_bf16 v[122:125], v[146:149], v[178:181], v[122:125]
	v_mfma_f32_16x16x32_bf16 v[118:121], v[138:141], v[186:189], v[118:121]
	v_mfma_f32_16x16x32_bf16 v[114:117], v[146:149], v[186:189], v[114:117]
	v_mfma_f32_16x16x32_bf16 v[102:105], v[138:141], v[194:197], v[102:105]
	v_mfma_f32_16x16x32_bf16 v[98:101], v[146:149], v[194:197], v[98:101]
	v_mfma_f32_16x16x32_bf16 v[86:89], v[138:141], v[214:217], v[86:89]
	v_mfma_f32_16x16x32_bf16 v[82:85], v[146:149], v[214:217], v[82:85]
	v_mfma_f32_16x16x32_bf16 v[126:129], v[142:145], v[182:185], v[126:129]
	v_mfma_f32_16x16x32_bf16 v[122:125], v[150:153], v[182:185], v[122:125]
	v_mfma_f32_16x16x32_bf16 v[118:121], v[142:145], v[190:193], v[118:121]
	v_mfma_f32_16x16x32_bf16 v[114:117], v[150:153], v[190:193], v[114:117]
	v_mfma_f32_16x16x32_bf16 v[102:105], v[142:145], v[210:213], v[102:105]
	v_mfma_f32_16x16x32_bf16 v[98:101], v[150:153], v[210:213], v[98:101]
	v_mfma_f32_16x16x32_bf16 v[86:89], v[142:145], v[218:221], v[86:89]
	v_mfma_f32_16x16x32_bf16 v[82:85], v[150:153], v[218:221], v[82:85]
	v_mfma_f32_16x16x32_bf16 v[110:113], v[158:161], v[178:181], v[110:113]
	v_mfma_f32_16x16x32_bf16 v[106:109], v[166:169], v[178:181], v[106:109]
	v_mfma_f32_16x16x32_bf16 v[94:97], v[158:161], v[186:189], v[94:97]
	v_mfma_f32_16x16x32_bf16 v[90:93], v[166:169], v[186:189], v[90:93]
	v_mfma_f32_16x16x32_bf16 v[78:81], v[158:161], v[194:197], v[78:81]
	v_mfma_f32_16x16x32_bf16 v[74:77], v[166:169], v[194:197], v[74:77]
	v_mfma_f32_16x16x32_bf16 v[70:73], v[158:161], v[214:217], v[70:73]
	v_mfma_f32_16x16x32_bf16 v[66:69], v[166:169], v[214:217], v[66:69]
	v_mfma_f32_16x16x32_bf16 v[110:113], v[162:165], v[182:185], v[110:113]
	v_mfma_f32_16x16x32_bf16 v[106:109], v[170:173], v[182:185], v[106:109]
	v_mfma_f32_16x16x32_bf16 v[94:97], v[162:165], v[190:193], v[94:97]
	v_mfma_f32_16x16x32_bf16 v[90:93], v[170:173], v[190:193], v[90:93]
	v_mfma_f32_16x16x32_bf16 v[78:81], v[162:165], v[210:213], v[78:81]
	v_mfma_f32_16x16x32_bf16 v[74:77], v[170:173], v[210:213], v[74:77]
	v_mfma_f32_16x16x32_bf16 v[70:73], v[162:165], v[218:221], v[70:73]
	v_mfma_f32_16x16x32_bf16 v[66:69], v[170:173], v[218:221], v[66:69]
	s_setprio 0
	s_barrier
; #define PG8_STAGE(bufoff, gbase, voff) do { _Pragma("unroll") for (int _i = 0; _i < 2; ++_i) \
;         __builtin_amdgcn_global_load_lds((const unsigned*)((const char*)(gbase) + (voff)[_i]), (LAS unsigned*)(lds + (bufoff) + ldsw + _i * 8192), 16, 0, 0); } while (0)
; #define PG8_LDA(dst, b, h) do { _Pragma("unroll") for (int m = 0; m < 4; ++m) _Pragma("unroll") for (int k = 0; k < 2; ++k) dst[m][k] = *(const LAS bf16x8*)(lds + PG8_SA(b, h) + aoff + m * 2048 + k * 1024); } while (0)
; #define PG8_MMA(ai, bj, At, Bt) do { __builtin_amdgcn_s_setprio(1); _Pragma("unroll") for (int m = 0; m < 4; ++m) _Pragma("unroll") for (int n = 0; n < 2; ++n) _Pragma("unroll") for (int k = 0; k < 2; ++k) \
;         acc[ai][bj][m][n] = __builtin_amdgcn_mfma_f32_16x16x32_bf16(Bt[n][k], At[m][k], acc[ai][bj][m][n], 0, 0, 0); __builtin_amdgcn_s_setprio(0); } while (0)
; #define PG8_WAIT_V(n) asm volatile("s_waitcnt vmcnt(" #n ")" ::: "memory")
; #define PG8_WAIT_L(n) asm volatile("s_waitcnt lgkmcnt(" #n ")" ::: "memory")
; #define PG8_BAR __builtin_amdgcn_s_barrier()
; #define PG8_SCHED __builtin_amdgcn_sched_barrier(0)
; template <class Epi>
; DI void gemm_phase(LAS unsigned char* lds, const Gemm g, const StaticOrder& S, const Epi& E, int wv0) {
;     ...
;             PG8_LDA(At, 1, 1); PG8_STAGE(PG8_SB(1, 0), b3, voffB); PG8_STAGE(PG8_SB(1, 1), b3 + hstepB, voffB); PG8_STAGE(PG8_SA(1, 0), a3, voffA);
;             PG8_WAIT_V(8); PG8_WAIT_L(0); PG8_BAR; PG8_MMA(1, 0, At, B0); PG8_MMA(1, 1, At, B1); PG8_BAR; PG8_SCHED;
;         }
	s_mov_b32 m0, s49
	v_lshl_add_u64 v[154:155], v[154:155], 0, s[86:87]
	s_add_u32 s22, s22, 0x80080
	ds_read_b128 v[178:181], v137 offset:49152
	ds_read_b128 v[182:185], v137 offset:50176
	ds_read_b128 v[186:189], v137 offset:51200
	ds_read_b128 v[190:193], v137 offset:52224
	ds_read_b128 v[194:197], v137 offset:53248
	ds_read_b128 v[210:213], v137 offset:54272
	ds_read_b128 v[214:217], v137 offset:55296
	ds_read_b128 v[218:221], v137 offset:56320
	global_load_lds_dwordx4 v[154:155], off
	v_lshl_add_u64 v[154:155], v[174:175], 0, s[86:87]
	s_mov_b32 m0, s50
	s_addc_u32 s23, s23, 0
	global_load_lds_dwordx4 v[154:155], off
	v_lshl_add_u64 v[154:155], s[22:23], 0, v[0:1]
	s_mov_b32 m0, s54
	s_nop 0
	global_load_lds_dwordx4 v[154:155], off
	v_lshl_add_u64 v[154:155], s[22:23], 0, v[130:131]
	s_mov_b32 m0, s55
	s_nop 0
	global_load_lds_dwordx4 v[154:155], off
	v_lshl_add_u64 v[154:155], v[198:199], 0, s[86:87]
	s_mov_b32 m0, s51
	s_nop 0
	global_load_lds_dwordx4 v[154:155], off
	v_lshl_add_u64 v[154:155], v[202:203], 0, s[86:87]
	s_mov_b32 m0, s52
	s_nop 0
	global_load_lds_dwordx4 v[154:155], off
	s_waitcnt vmcnt(8)
	s_waitcnt lgkmcnt(0)
	s_barrier
	s_setprio 1
	s_waitcnt lgkmcnt(0)
	v_mfma_f32_16x16x32_bf16 v[62:65], v[138:141], v[178:181], v[62:65]
	v_mfma_f32_16x16x32_bf16 v[58:61], v[146:149], v[178:181], v[58:61]
	v_mfma_f32_16x16x32_bf16 v[54:57], v[138:141], v[186:189], v[54:57]
	v_mfma_f32_16x16x32_bf16 v[50:53], v[146:149], v[186:189], v[50:53]
	v_mfma_f32_16x16x32_bf16 v[38:41], v[138:141], v[194:197], v[38:41]
	v_mfma_f32_16x16x32_bf16 v[34:37], v[146:149], v[194:197], v[34:37]
	v_mfma_f32_16x16x32_bf16 v[22:25], v[138:141], v[214:217], v[22:25]
	v_mfma_f32_16x16x32_bf16 v[18:21], v[146:149], v[214:217], v[18:21]
	v_mfma_f32_16x16x32_bf16 v[62:65], v[142:145], v[182:185], v[62:65]
	v_mfma_f32_16x16x32_bf16 v[58:61], v[150:153], v[182:185], v[58:61]
	v_mfma_f32_16x16x32_bf16 v[54:57], v[142:145], v[190:193], v[54:57]
	v_mfma_f32_16x16x32_bf16 v[50:53], v[150:153], v[190:193], v[50:53]
	v_mfma_f32_16x16x32_bf16 v[38:41], v[142:145], v[210:213], v[38:41]
	v_mfma_f32_16x16x32_bf16 v[34:37], v[150:153], v[210:213], v[34:37]
	v_mfma_f32_16x16x32_bf16 v[22:25], v[142:145], v[218:221], v[22:25]
	v_mfma_f32_16x16x32_bf16 v[18:21], v[150:153], v[218:221], v[18:21]
	v_mfma_f32_16x16x32_bf16 v[46:49], v[158:161], v[178:181], v[46:49]
	v_mfma_f32_16x16x32_bf16 v[42:45], v[166:169], v[178:181], v[42:45]
	v_mfma_f32_16x16x32_bf16 v[30:33], v[158:161], v[186:189], v[30:33]
	v_mfma_f32_16x16x32_bf16 v[26:29], v[166:169], v[186:189], v[26:29]
	v_mfma_f32_16x16x32_bf16 v[14:17], v[158:161], v[194:197], v[14:17]
	v_mfma_f32_16x16x32_bf16 v[10:13], v[166:169], v[194:197], v[10:13]
	v_mfma_f32_16x16x32_bf16 v[6:9], v[158:161], v[214:217], v[6:9]
	v_mfma_f32_16x16x32_bf16 v[2:5], v[166:169], v[214:217], v[2:5]
	v_mfma_f32_16x16x32_bf16 v[46:49], v[162:165], v[182:185], v[46:49]
	v_mfma_f32_16x16x32_bf16 v[42:45], v[170:173], v[182:185], v[42:45]
	v_mfma_f32_16x16x32_bf16 v[30:33], v[162:165], v[190:193], v[30:33]
	v_mfma_f32_16x16x32_bf16 v[26:29], v[170:173], v[190:193], v[26:29]
	v_mfma_f32_16x16x32_bf16 v[14:17], v[162:165], v[210:213], v[14:17]
	v_mfma_f32_16x16x32_bf16 v[10:13], v[170:173], v[210:213], v[10:13]
	v_mfma_f32_16x16x32_bf16 v[6:9], v[162:165], v[218:221], v[6:9]
	v_mfma_f32_16x16x32_bf16 v[2:5], v[170:173], v[218:221], v[2:5]
	s_setprio 0
	s_barrier
	s_add_i32 s62, s62, 2
	s_add_u32 s60, s60, 0x100
	s_addc_u32 s61, s61, 0
	s_add_u32 s20, s20, 0x100
	s_addc_u32 s21, s21, 0
	s_cmp_gt_u32 s62, 5
	s_cbranch_scc0 .LBB0_868
	s_and_b64 vcc, exec, s[8:9]
	s_cbranch_vccz .LBB0_871
	s_barrier

; #define PG8_STAGE(bufoff, gbase, voff) do { _Pragma("unroll") for (int _i = 0; _i < 2; ++_i) \
;         __builtin_amdgcn_global_load_lds((const unsigned*)((const char*)(gbase) + (voff)[_i]), (LAS unsigned*)(lds + (bufoff) + ldsw + _i * 8192), 16, 0, 0); } while (0)
; #define PG8_LDA(dst, b, h) do { _Pragma("unroll") for (int m = 0; m < 4; ++m) _Pragma("unroll") for (int k = 0; k < 2; ++k) dst[m][k] = *(const LAS bf16x8*)(lds + PG8_SA(b, h) + aoff + m * 2048 + k * 1024); } while (0)
; #define PG8_LDB(dst, b, h) do { _Pragma("unroll") for (int n = 0; n < 2; ++n) _Pragma("unroll") for (int k = 0; k < 2; ++k) dst[n][k] = *(const LAS bf16x8*)(lds + PG8_SB(b, h) + boff + n * 2048 + k * 1024); } while (0)
; #define PG8_MMA(ai, bj, At, Bt) do { __builtin_amdgcn_s_setprio(1); _Pragma("unroll") for (int m = 0; m < 4; ++m) _Pragma("unroll") for (int n = 0; n < 2; ++n) _Pragma("unroll") for (int k = 0; k < 2; ++k) \
;         acc[ai][bj][m][n] = __builtin_amdgcn_mfma_f32_16x16x32_bf16(Bt[n][k], At[m][k], acc[ai][bj][m][n], 0, 0, 0); __builtin_amdgcn_s_setprio(0); } while (0)
; #define PG8_WAIT_V(n) asm volatile("s_waitcnt vmcnt(" #n ")" ::: "memory")
; #define PG8_WAIT_L(n) asm volatile("s_waitcnt lgkmcnt(" #n ")" ::: "memory")
; #define PG8_BAR __builtin_amdgcn_s_barrier()
; #define PG8_SCHED __builtin_amdgcn_sched_barrier(0)
; template <class Epi>
; DI void gemm_phase(LAS unsigned char* lds, const Gemm g, const StaticOrder& S, const Epi& E, int wv0) {
;     ...
;             const bool last = (t == nt - 2);
;             const char* a1 = cA + (size_t)(t + 1) * kstep;
;             const char* a2 = last ? nA : cA + (size_t)(t + 2) * kstep; const char* b2 = last ? nB : cB + (size_t)(t + 2) * kstep;
;             const char* a3 = a2 + kstep; const char* b3 = b2 + kstep;
;             PG8_LDB(B0, 0, 0); PG8_LDB(B1, 0, 1); PG8_SCHED; PG8_LDA(At, 0, 0); PG8_STAGE(PG8_SA(1, 1), a1 + hstepA, voffA);
;             PG8_WAIT_V(8); PG8_WAIT_L(0); PG8_BAR; PG8_MMA(0, 0, At, B0); PG8_MMA(0, 1, At, B1); PG8_BAR; PG8_SCHED;
;             PG8_LDA(At, 0, 1); PG8_STAGE(PG8_SB(0, 0), b2, voffB); PG8_STAGE(PG8_SB(0, 1), b2 + hstepB, voffB); PG8_STAGE(PG8_SA(0, 0), a2, voffA);
.LBB0_984:
	s_add_u32 s29, s20, s28
	s_addc_u32 s38, s21, 0
	s_add_u32 s36, s29, 0x100
	s_addc_u32 s37, s38, 0
	s_and_b64 s[30:31], s[26:27], exec
	s_cselect_b32 s31, s15, s37
	s_cselect_b32 s30, s69, s36
	s_add_u32 s28, s22, s28
	s_addc_u32 s36, s23, 0
	s_add_u32 s28, s28, 0x100
	s_addc_u32 s36, s36, 0
	s_and_b64 s[26:27], s[26:27], exec
	v_add_u32_e32 v140, s46, v142
	s_cselect_b32 s37, s13, s36
	s_cselect_b32 s36, s70, s28
	s_add_u32 s40, s29, 0x10080
	ds_read_b128 v[136:139], v140
	ds_read_b128 v[144:147], v140 offset:1024
	ds_read_b128 v[148:151], v140 offset:2048
	ds_read_b128 v[152:155], v140 offset:3072
	v_add_u32_e32 v140, s49, v142
	s_addc_u32 s41, s38, 0
	s_add_i32 m0, s52, 0xc000
	s_add_i32 s71, s52, 0xe000
	ds_read_b128 v[158:161], v140
	ds_read_b128 v[162:165], v140 offset:1024
	ds_read_b128 v[166:169], v140 offset:2048
	ds_read_b128 v[170:173], v140 offset:3072
	s_add_u32 s38, s36, 0x10000
	s_addc_u32 s39, s37, 0
	s_add_u32 s28, s30, 0x10000
	s_addc_u32 s29, s31, 0
	s_add_u32 s26, s36, 0x10080
	s_addc_u32 s27, s37, 0
	v_lshl_add_u64 v[140:141], s[40:41], 0, v[0:1]
	ds_read_b128 v[178:181], v143
	ds_read_b128 v[182:185], v143 offset:1024
	ds_read_b128 v[186:189], v143 offset:2048
	ds_read_b128 v[190:193], v143 offset:3072
	ds_read_b128 v[194:197], v143 offset:4096
	ds_read_b128 v[210:213], v143 offset:5120
	ds_read_b128 v[214:217], v143 offset:6144
	ds_read_b128 v[218:221], v143 offset:7168
	global_load_lds_dwordx4 v[140:141], off
	v_lshl_add_u64 v[140:141], s[40:41], 0, v[132:133]
	s_mov_b32 m0, s71
	s_nop 0
	global_load_lds_dwordx4 v[140:141], off
	s_waitcnt vmcnt(8)
	s_waitcnt lgkmcnt(0)
	s_barrier
	s_setprio 1
	s_waitcnt lgkmcnt(0)
	v_mfma_f32_16x16x32_bf16 v[126:129], v[136:139], v[178:181], v[126:129]
	v_mfma_f32_16x16x32_bf16 v[122:125], v[148:151], v[178:181], v[122:125]
	v_mfma_f32_16x16x32_bf16 v[114:117], v[136:139], v[186:189], v[114:117]
	v_mfma_f32_16x16x32_bf16 v[106:109], v[148:151], v[186:189], v[106:109]
	v_mfma_f32_16x16x32_bf16 v[98:101], v[136:139], v[194:197], v[98:101]
	v_mfma_f32_16x16x32_bf16 v[90:93], v[148:151], v[194:197], v[90:93]
	v_mfma_f32_16x16x32_bf16 v[82:85], v[136:139], v[214:217], v[82:85]
	v_mfma_f32_16x16x32_bf16 v[74:77], v[148:151], v[214:217], v[74:77]
	v_mfma_f32_16x16x32_bf16 v[126:129], v[144:147], v[182:185], v[126:129]
	v_mfma_f32_16x16x32_bf16 v[122:125], v[152:155], v[182:185], v[122:125]
	v_mfma_f32_16x16x32_bf16 v[114:117], v[144:147], v[190:193], v[114:117]
	v_mfma_f32_16x16x32_bf16 v[106:109], v[152:155], v[190:193], v[106:109]
	v_mfma_f32_16x16x32_bf16 v[98:101], v[144:147], v[210:213], v[98:101]
	v_mfma_f32_16x16x32_bf16 v[90:93], v[152:155], v[210:213], v[90:93]
	v_mfma_f32_16x16x32_bf16 v[82:85], v[144:147], v[218:221], v[82:85]
	v_mfma_f32_16x16x32_bf16 v[74:77], v[152:155], v[218:221], v[74:77]
	v_mfma_f32_16x16x32_bf16 v[118:121], v[158:161], v[178:181], v[118:121]
	v_mfma_f32_16x16x32_bf16 v[110:113], v[166:169], v[178:181], v[110:113]
	v_mfma_f32_16x16x32_bf16 v[102:105], v[158:161], v[186:189], v[102:105]
	v_mfma_f32_16x16x32_bf16 v[94:97], v[166:169], v[186:189], v[94:97]
	v_mfma_f32_16x16x32_bf16 v[86:89], v[158:161], v[194:197], v[86:89]
	v_mfma_f32_16x16x32_bf16 v[78:81], v[166:169], v[194:197], v[78:81]
	v_mfma_f32_16x16x32_bf16 v[70:73], v[158:161], v[214:217], v[70:73]
	v_mfma_f32_16x16x32_bf16 v[66:69], v[166:169], v[214:217], v[66:69]
	v_mfma_f32_16x16x32_bf16 v[118:121], v[162:165], v[182:185], v[118:121]
	v_mfma_f32_16x16x32_bf16 v[110:113], v[170:173], v[182:185], v[110:113]
	v_mfma_f32_16x16x32_bf16 v[102:105], v[162:165], v[190:193], v[102:105]
	v_mfma_f32_16x16x32_bf16 v[94:97], v[170:173], v[190:193], v[94:97]
	v_mfma_f32_16x16x32_bf16 v[86:89], v[162:165], v[210:213], v[86:89]
	v_mfma_f32_16x16x32_bf16 v[78:81], v[170:173], v[210:213], v[78:81]
	v_mfma_f32_16x16x32_bf16 v[70:73], v[162:165], v[218:221], v[70:73]
	v_mfma_f32_16x16x32_bf16 v[66:69], v[170:173], v[218:221], v[66:69]
	s_setprio 0
	s_barrier
	s_mov_b32 m0, s47
	v_lshl_add_u64 v[140:141], s[36:37], 0, v[130:131]
	ds_read_b128 v[178:181], v143 offset:16384
	ds_read_b128 v[182:185], v143 offset:17408
	ds_read_b128 v[186:189], v143 offset:18432
	ds_read_b128 v[190:193], v143 offset:19456
	ds_read_b128 v[194:197], v143 offset:20480
	ds_read_b128 v[210:213], v143 offset:21504
	ds_read_b128 v[214:217], v143 offset:22528
	ds_read_b128 v[218:221], v143 offset:23552
	global_load_lds_dwordx4 v[140:141], off
	v_lshl_add_u64 v[174:175], s[36:37], 0, v[134:135]
	s_mov_b32 m0, s48
	v_lshl_add_u64 v[198:199], s[38:39], 0, v[130:131]
	global_load_lds_dwordx4 v[174:175], off
	s_mov_b32 m0, s50
	v_lshl_add_u64 v[202:203], s[30:31], 0, v[132:133]
	global_load_lds_dwordx4 v[198:199], off
	v_lshl_add_u64 v[198:199], s[38:39], 0, v[134:135]
	s_mov_b32 m0, s51
	s_nop 0
	global_load_lds_dwordx4 v[198:199], off
	v_lshl_add_u64 v[198:199], s[30:31], 0, v[0:1]
	s_mov_b32 m0, s52
	s_nop 0
	global_load_lds_dwordx4 v[198:199], off
	s_mov_b32 m0, s53
	s_nop 0
	global_load_lds_dwordx4 v[202:203], off
	s_waitcnt vmcnt(8)
	s_waitcnt lgkmcnt(0)
	s_barrier
; #define PG8_STAGE(bufoff, gbase, voff) do { _Pragma("unroll") for (int _i = 0; _i < 2; ++_i) \
;         __builtin_amdgcn_global_load_lds((const unsigned*)((const char*)(gbase) + (voff)[_i]), (LAS unsigned*)(lds + (bufoff) + ldsw + _i * 8192), 16, 0, 0); } while (0)
; #define PG8_LDA(dst, b, h) do { _Pragma("unroll") for (int m = 0; m < 4; ++m) _Pragma("unroll") for (int k = 0; k < 2; ++k) dst[m][k] = *(const LAS bf16x8*)(lds + PG8_SA(b, h) + aoff + m * 2048 + k * 1024); } while (0)
; #define PG8_LDB(dst, b, h) do { _Pragma("unroll") for (int n = 0; n < 2; ++n) _Pragma("unroll") for (int k = 0; k < 2; ++k) dst[n][k] = *(const LAS bf16x8*)(lds + PG8_SB(b, h) + boff + n * 2048 + k * 1024); } while (0)
; #define PG8_MMA(ai, bj, At, Bt) do { __builtin_amdgcn_s_setprio(1); _Pragma("unroll") for (int m = 0; m < 4; ++m) _Pragma("unroll") for (int n = 0; n < 2; ++n) _Pragma("unroll") for (int k = 0; k < 2; ++k) \
;         acc[ai][bj][m][n] = __builtin_amdgcn_mfma_f32_16x16x32_bf16(Bt[n][k], At[m][k], acc[ai][bj][m][n], 0, 0, 0); __builtin_amdgcn_s_setprio(0); } while (0)
; #define PG8_WAIT_V(n) asm volatile("s_waitcnt vmcnt(" #n ")" ::: "memory")
; #define PG8_WAIT_L(n) asm volatile("s_waitcnt lgkmcnt(" #n ")" ::: "memory")
; #define PG8_BAR __builtin_amdgcn_s_barrier()
; #define PG8_SCHED __builtin_amdgcn_sched_barrier(0)
; template <class Epi>
; DI void gemm_phase(LAS unsigned char* lds, const Gemm g, const StaticOrder& S, const Epi& E, int wv0) {
;     ...
;             PG8_WAIT_V(8); PG8_WAIT_L(0); PG8_BAR; PG8_MMA(1, 0, At, B0); PG8_MMA(1, 1, At, B1); PG8_BAR; PG8_SCHED;
;             PG8_LDB(B0, 1, 0); PG8_LDB(B1, 1, 1); PG8_SCHED; PG8_LDA(At, 1, 0); PG8_STAGE(PG8_SA(0, 1), a2 + hstepA, voffA);
;             PG8_WAIT_V(8); PG8_WAIT_L(0); PG8_BAR; PG8_MMA(0, 0, At, B0); PG8_MMA(0, 1, At, B1); PG8_BAR; PG8_SCHED;
	s_setprio 1
	s_waitcnt lgkmcnt(0)
	v_mfma_f32_16x16x32_bf16 v[62:65], v[136:139], v[178:181], v[62:65]
	v_mfma_f32_16x16x32_bf16 v[58:61], v[148:151], v[178:181], v[58:61]
	v_mfma_f32_16x16x32_bf16 v[50:53], v[136:139], v[186:189], v[50:53]
	v_mfma_f32_16x16x32_bf16 v[42:45], v[148:151], v[186:189], v[42:45]
	v_mfma_f32_16x16x32_bf16 v[34:37], v[136:139], v[194:197], v[34:37]
	v_mfma_f32_16x16x32_bf16 v[26:29], v[148:151], v[194:197], v[26:29]
	v_mfma_f32_16x16x32_bf16 v[18:21], v[136:139], v[214:217], v[18:21]
	v_mfma_f32_16x16x32_bf16 v[10:13], v[148:151], v[214:217], v[10:13]
	v_mfma_f32_16x16x32_bf16 v[62:65], v[144:147], v[182:185], v[62:65]
	v_mfma_f32_16x16x32_bf16 v[58:61], v[152:155], v[182:185], v[58:61]
	v_mfma_f32_16x16x32_bf16 v[50:53], v[144:147], v[190:193], v[50:53]
	v_mfma_f32_16x16x32_bf16 v[42:45], v[152:155], v[190:193], v[42:45]
	v_mfma_f32_16x16x32_bf16 v[34:37], v[144:147], v[210:213], v[34:37]
	v_mfma_f32_16x16x32_bf16 v[26:29], v[152:155], v[210:213], v[26:29]
	v_mfma_f32_16x16x32_bf16 v[18:21], v[144:147], v[218:221], v[18:21]
	v_mfma_f32_16x16x32_bf16 v[10:13], v[152:155], v[218:221], v[10:13]
	v_mfma_f32_16x16x32_bf16 v[54:57], v[158:161], v[178:181], v[54:57]
	v_mfma_f32_16x16x32_bf16 v[46:49], v[166:169], v[178:181], v[46:49]
	v_mfma_f32_16x16x32_bf16 v[38:41], v[158:161], v[186:189], v[38:41]
	v_mfma_f32_16x16x32_bf16 v[30:33], v[166:169], v[186:189], v[30:33]
	v_mfma_f32_16x16x32_bf16 v[22:25], v[158:161], v[194:197], v[22:25]
	v_mfma_f32_16x16x32_bf16 v[14:17], v[166:169], v[194:197], v[14:17]
	v_mfma_f32_16x16x32_bf16 v[6:9], v[158:161], v[214:217], v[6:9]
	v_mfma_f32_16x16x32_bf16 v[2:5], v[166:169], v[214:217], v[2:5]
	v_mfma_f32_16x16x32_bf16 v[54:57], v[162:165], v[182:185], v[54:57]
	v_mfma_f32_16x16x32_bf16 v[46:49], v[170:173], v[182:185], v[46:49]
	v_mfma_f32_16x16x32_bf16 v[38:41], v[162:165], v[190:193], v[38:41]
	v_mfma_f32_16x16x32_bf16 v[30:33], v[170:173], v[190:193], v[30:33]
	v_mfma_f32_16x16x32_bf16 v[22:25], v[162:165], v[210:213], v[22:25]
	v_mfma_f32_16x16x32_bf16 v[14:17], v[170:173], v[210:213], v[14:17]
	v_mfma_f32_16x16x32_bf16 v[6:9], v[162:165], v[218:221], v[6:9]
	v_mfma_f32_16x16x32_bf16 v[2:5], v[170:173], v[218:221], v[2:5]
	s_setprio 0
	s_barrier
	v_add_u32_e32 v152, s58, v142
	v_add_u32_e32 v170, s63, v142
	ds_read_b128 v[136:139], v152
	ds_read_b128 v[144:147], v152 offset:1024
	ds_read_b128 v[148:151], v152 offset:2048
	ds_read_b128 v[152:155], v152 offset:3072
	ds_read_b128 v[158:161], v170
	ds_read_b128 v[162:165], v170 offset:1024
	ds_read_b128 v[166:169], v170 offset:2048
	ds_read_b128 v[170:173], v170 offset:3072
	s_mov_b32 m0, s54
	v_lshl_add_u64 v[222:223], s[28:29], 0, v[0:1]
	ds_read_b128 v[178:181], v143 offset:32768
	ds_read_b128 v[182:185], v143 offset:33792
	ds_read_b128 v[186:189], v143 offset:34816
	ds_read_b128 v[190:193], v143 offset:35840
	ds_read_b128 v[194:197], v143 offset:36864
	ds_read_b128 v[210:213], v143 offset:37888
	ds_read_b128 v[214:217], v143 offset:38912
	ds_read_b128 v[218:221], v143 offset:39936
	global_load_lds_dwordx4 v[222:223], off
	v_lshl_add_u64 v[222:223], s[28:29], 0, v[132:133]
	s_mov_b32 m0, s55
	s_nop 0
	global_load_lds_dwordx4 v[222:223], off
	s_waitcnt vmcnt(8)
	s_waitcnt lgkmcnt(0)
	s_barrier
	s_setprio 1
	s_waitcnt lgkmcnt(0)
	v_mfma_f32_16x16x32_bf16 v[126:129], v[136:139], v[178:181], v[126:129]
	v_mfma_f32_16x16x32_bf16 v[122:125], v[148:151], v[178:181], v[122:125]
	v_mfma_f32_16x16x32_bf16 v[114:117], v[136:139], v[186:189], v[114:117]
	v_mfma_f32_16x16x32_bf16 v[106:109], v[148:151], v[186:189], v[106:109]
	v_mfma_f32_16x16x32_bf16 v[98:101], v[136:139], v[194:197], v[98:101]
	v_mfma_f32_16x16x32_bf16 v[90:93], v[148:151], v[194:197], v[90:93]
	v_mfma_f32_16x16x32_bf16 v[82:85], v[136:139], v[214:217], v[82:85]
	v_mfma_f32_16x16x32_bf16 v[74:77], v[148:151], v[214:217], v[74:77]
	v_mfma_f32_16x16x32_bf16 v[126:129], v[144:147], v[182:185], v[126:129]
	v_mfma_f32_16x16x32_bf16 v[122:125], v[152:155], v[182:185], v[122:125]
	v_mfma_f32_16x16x32_bf16 v[114:117], v[144:147], v[190:193], v[114:117]
	v_mfma_f32_16x16x32_bf16 v[106:109], v[152:155], v[190:193], v[106:109]
	v_mfma_f32_16x16x32_bf16 v[98:101], v[144:147], v[210:213], v[98:101]
	v_mfma_f32_16x16x32_bf16 v[90:93], v[152:155], v[210:213], v[90:93]
	v_mfma_f32_16x16x32_bf16 v[82:85], v[144:147], v[218:221], v[82:85]
	v_mfma_f32_16x16x32_bf16 v[74:77], v[152:155], v[218:221], v[74:77]
	v_mfma_f32_16x16x32_bf16 v[118:121], v[158:161], v[178:181], v[118:121]
	v_mfma_f32_16x16x32_bf16 v[110:113], v[166:169], v[178:181], v[110:113]
	v_mfma_f32_16x16x32_bf16 v[102:105], v[158:161], v[186:189], v[102:105]
	v_mfma_f32_16x16x32_bf16 v[94:97], v[166:169], v[186:189], v[94:97]
	v_mfma_f32_16x16x32_bf16 v[86:89], v[158:161], v[194:197], v[86:89]
	v_mfma_f32_16x16x32_bf16 v[78:81], v[166:169], v[194:197], v[78:81]
	v_mfma_f32_16x16x32_bf16 v[70:73], v[158:161], v[214:217], v[70:73]
	v_mfma_f32_16x16x32_bf16 v[66:69], v[166:169], v[214:217], v[66:69]
	v_mfma_f32_16x16x32_bf16 v[118:121], v[162:165], v[182:185], v[118:121]
	v_mfma_f32_16x16x32_bf16 v[110:113], v[170:173], v[182:185], v[110:113]
	v_mfma_f32_16x16x32_bf16 v[102:105], v[162:165], v[190:193], v[102:105]
	v_mfma_f32_16x16x32_bf16 v[94:97], v[170:173], v[190:193], v[94:97]
	v_mfma_f32_16x16x32_bf16 v[86:89], v[162:165], v[210:213], v[86:89]
	v_mfma_f32_16x16x32_bf16 v[78:81], v[170:173], v[210:213], v[78:81]
	v_mfma_f32_16x16x32_bf16 v[70:73], v[162:165], v[218:221], v[70:73]
	v_mfma_f32_16x16x32_bf16 v[66:69], v[170:173], v[218:221], v[66:69]
	s_setprio 0
	s_barrier
; #define PG8_STAGE(bufoff, gbase, voff) do { _Pragma("unroll") for (int _i = 0; _i < 2; ++_i) \
;         __builtin_amdgcn_global_load_lds((const unsigned*)((const char*)(gbase) + (voff)[_i]), (LAS unsigned*)(lds + (bufoff) + ldsw + _i * 8192), 16, 0, 0); } while (0)
; #define PG8_LDA(dst, b, h) do { _Pragma("unroll") for (int m = 0; m < 4; ++m) _Pragma("unroll") for (int k = 0; k < 2; ++k) dst[m][k] = *(const LAS bf16x8*)(lds + PG8_SA(b, h) + aoff + m * 2048 + k * 1024); } while (0)
; #define PG8_MMA(ai, bj, At, Bt) do { __builtin_amdgcn_s_setprio(1); _Pragma("unroll") for (int m = 0; m < 4; ++m) _Pragma("unroll") for (int n = 0; n < 2; ++n) _Pragma("unroll") for (int k = 0; k < 2; ++k) \
;         acc[ai][bj][m][n] = __builtin_amdgcn_mfma_f32_16x16x32_bf16(Bt[n][k], At[m][k], acc[ai][bj][m][n], 0, 0, 0); __builtin_amdgcn_s_setprio(0); } while (0)
; #define PG8_WAIT_V(n) asm volatile("s_waitcnt vmcnt(" #n ")" ::: "memory")
; #define PG8_WAIT_L(n) asm volatile("s_waitcnt lgkmcnt(" #n ")" ::: "memory")
; #define PG8_BAR __builtin_amdgcn_s_barrier()
; #define PG8_SCHED __builtin_amdgcn_sched_barrier(0)
; template <class Epi>
; DI void gemm_phase(LAS unsigned char* lds, const Gemm g, const StaticOrder& S, const Epi& E, int wv0) {
;     ...
;             PG8_LDA(At, 1, 1); PG8_STAGE(PG8_SB(1, 0), b3, voffB); PG8_STAGE(PG8_SB(1, 1), b3 + hstepB, voffB); PG8_STAGE(PG8_SA(1, 0), a3, voffA);
;             PG8_WAIT_V(8); PG8_WAIT_L(0); PG8_BAR; PG8_MMA(1, 0, At, B0); PG8_MMA(1, 1, At, B1); PG8_BAR; PG8_SCHED;
;         }
	s_mov_b32 m0, s59
	v_lshl_add_u64 v[140:141], v[140:141], 0, s[86:87]
	ds_read_b128 v[178:181], v143 offset:49152
	ds_read_b128 v[182:185], v143 offset:50176
	ds_read_b128 v[186:189], v143 offset:51200
	ds_read_b128 v[190:193], v143 offset:52224
	ds_read_b128 v[194:197], v143 offset:53248
	ds_read_b128 v[210:213], v143 offset:54272
	ds_read_b128 v[214:217], v143 offset:55296
	ds_read_b128 v[218:221], v143 offset:56320
	global_load_lds_dwordx4 v[140:141], off
	v_lshl_add_u64 v[140:141], v[174:175], 0, s[86:87]
	s_mov_b32 m0, s60
	s_nop 0
	global_load_lds_dwordx4 v[140:141], off
	v_lshl_add_u64 v[140:141], s[26:27], 0, v[130:131]
	s_mov_b32 m0, s64
	s_nop 0
	global_load_lds_dwordx4 v[140:141], off
	v_lshl_add_u64 v[140:141], s[26:27], 0, v[134:135]
	s_mov_b32 m0, s65
	s_nop 0
	global_load_lds_dwordx4 v[140:141], off
	v_lshl_add_u64 v[140:141], v[198:199], 0, s[86:87]
	s_mov_b32 m0, s61
	s_nop 0
	global_load_lds_dwordx4 v[140:141], off
	v_lshl_add_u64 v[140:141], v[202:203], 0, s[86:87]
	s_mov_b32 m0, s62
	s_nop 0
	global_load_lds_dwordx4 v[140:141], off
	s_waitcnt vmcnt(8)
	s_waitcnt lgkmcnt(0)
	s_barrier
	s_setprio 1
	s_waitcnt lgkmcnt(0)
	v_mfma_f32_16x16x32_bf16 v[62:65], v[136:139], v[178:181], v[62:65]
	v_mfma_f32_16x16x32_bf16 v[58:61], v[148:151], v[178:181], v[58:61]
	v_mfma_f32_16x16x32_bf16 v[50:53], v[136:139], v[186:189], v[50:53]
	v_mfma_f32_16x16x32_bf16 v[42:45], v[148:151], v[186:189], v[42:45]
	v_mfma_f32_16x16x32_bf16 v[34:37], v[136:139], v[194:197], v[34:37]
	v_mfma_f32_16x16x32_bf16 v[26:29], v[148:151], v[194:197], v[26:29]
	v_mfma_f32_16x16x32_bf16 v[18:21], v[136:139], v[214:217], v[18:21]
	v_mfma_f32_16x16x32_bf16 v[10:13], v[148:151], v[214:217], v[10:13]
	v_mfma_f32_16x16x32_bf16 v[62:65], v[144:147], v[182:185], v[62:65]
	v_mfma_f32_16x16x32_bf16 v[58:61], v[152:155], v[182:185], v[58:61]
	v_mfma_f32_16x16x32_bf16 v[50:53], v[144:147], v[190:193], v[50:53]
	v_mfma_f32_16x16x32_bf16 v[42:45], v[152:155], v[190:193], v[42:45]
	v_mfma_f32_16x16x32_bf16 v[34:37], v[144:147], v[210:213], v[34:37]
	v_mfma_f32_16x16x32_bf16 v[26:29], v[152:155], v[210:213], v[26:29]
	v_mfma_f32_16x16x32_bf16 v[18:21], v[144:147], v[218:221], v[18:21]
	v_mfma_f32_16x16x32_bf16 v[10:13], v[152:155], v[218:221], v[10:13]
	v_mfma_f32_16x16x32_bf16 v[54:57], v[158:161], v[178:181], v[54:57]
	v_mfma_f32_16x16x32_bf16 v[46:49], v[166:169], v[178:181], v[46:49]
	v_mfma_f32_16x16x32_bf16 v[38:41], v[158:161], v[186:189], v[38:41]
	v_mfma_f32_16x16x32_bf16 v[30:33], v[166:169], v[186:189], v[30:33]
	v_mfma_f32_16x16x32_bf16 v[22:25], v[158:161], v[194:197], v[22:25]
	v_mfma_f32_16x16x32_bf16 v[14:17], v[166:169], v[194:197], v[14:17]
	v_mfma_f32_16x16x32_bf16 v[6:9], v[158:161], v[214:217], v[6:9]
	v_mfma_f32_16x16x32_bf16 v[2:5], v[166:169], v[214:217], v[2:5]
	v_mfma_f32_16x16x32_bf16 v[54:57], v[162:165], v[182:185], v[54:57]
	v_mfma_f32_16x16x32_bf16 v[46:49], v[170:173], v[182:185], v[46:49]
	v_mfma_f32_16x16x32_bf16 v[38:41], v[162:165], v[190:193], v[38:41]
	v_mfma_f32_16x16x32_bf16 v[30:33], v[170:173], v[190:193], v[30:33]
	v_mfma_f32_16x16x32_bf16 v[22:25], v[162:165], v[210:213], v[22:25]
	v_mfma_f32_16x16x32_bf16 v[14:17], v[170:173], v[210:213], v[14:17]
	v_mfma_f32_16x16x32_bf16 v[6:9], v[162:165], v[218:221], v[6:9]
	v_mfma_f32_16x16x32_bf16 v[2:5], v[170:173], v[218:221], v[2:5]
	s_setprio 0
	s_barrier
	s_movk_i32 s28, 0x100
	s_andn2_b64 vcc, exec, s[24:25]
	s_mov_b64 s[26:27], -1
	s_mov_b64 s[24:25], 0
	s_cbranch_vccz .LBB0_984
	s_and_b64 vcc, exec, s[8:9]
	s_cbranch_vccz .LBB0_987
	s_barrier

; #define PG8_STAGE(bufoff, gbase, voff) do { _Pragma("unroll") for (int _i = 0; _i < 2; ++_i) \
;         __builtin_amdgcn_global_load_lds((const unsigned*)((const char*)(gbase) + (voff)[_i]), (LAS unsigned*)(lds + (bufoff) + ldsw + _i * 8192), 16, 0, 0); } while (0)
; #define PG8_LDA(dst, b, h) do { _Pragma("unroll") for (int m = 0; m < 4; ++m) _Pragma("unroll") for (int k = 0; k < 2; ++k) dst[m][k] = *(const LAS bf16x8*)(lds + PG8_SA(b, h) + aoff + m * 2048 + k * 1024); } while (0)
; #define PG8_LDB(dst, b, h) do { _Pragma("unroll") for (int n = 0; n < 2; ++n) _Pragma("unroll") for (int k = 0; k < 2; ++k) dst[n][k] = *(const LAS bf16x8*)(lds + PG8_SB(b, h) + boff + n * 2048 + k * 1024); } while (0)
; #define PG8_MMA(ai, bj, At, Bt) do { __builtin_amdgcn_s_setprio(1); _Pragma("unroll") for (int m = 0; m < 4; ++m) _Pragma("unroll") for (int n = 0; n < 2; ++n) _Pragma("unroll") for (int k = 0; k < 2; ++k) \
;         acc[ai][bj][m][n] = __builtin_amdgcn_mfma_f32_16x16x32_bf16(Bt[n][k], At[m][k], acc[ai][bj][m][n], 0, 0, 0); __builtin_amdgcn_s_setprio(0); } while (0)
; #define PG8_WAIT_V(n) asm volatile("s_waitcnt vmcnt(" #n ")" ::: "memory")
; #define PG8_WAIT_L(n) asm volatile("s_waitcnt lgkmcnt(" #n ")" ::: "memory")
; #define PG8_BAR __builtin_amdgcn_s_barrier()
; #define PG8_SCHED __builtin_amdgcn_sched_barrier(0)
; template <class Epi>
; DI void gemm_phase(LAS unsigned char* lds, const Gemm g, const StaticOrder& S, const Epi& E, int wv0) {
;     ...
;             const bool last = (t == nt - 2);
;             const char* a1 = cA + (size_t)(t + 1) * kstep;
;             const char* a2 = last ? nA : cA + (size_t)(t + 2) * kstep; const char* b2 = last ? nB : cB + (size_t)(t + 2) * kstep;
;             const char* a3 = a2 + kstep; const char* b3 = b2 + kstep;
;             PG8_LDB(B0, 0, 0); PG8_LDB(B1, 0, 1); PG8_SCHED; PG8_LDA(At, 0, 0); PG8_STAGE(PG8_SA(1, 1), a1 + hstepA, voffA);
;             PG8_WAIT_V(8); PG8_WAIT_L(0); PG8_BAR; PG8_MMA(0, 0, At, B0); PG8_MMA(0, 1, At, B1); PG8_BAR; PG8_SCHED;
;             PG8_LDA(At, 0, 1); PG8_STAGE(PG8_SB(0, 0), b2, voffB); PG8_STAGE(PG8_SB(0, 1), b2 + hstepB, voffB); PG8_STAGE(PG8_SA(0, 0), a2, voffA);
.LBB0_1456:
	v_add_u32_e32 v140, s31, v142
	ds_read_b128 v[136:139], v140
	ds_read_b128 v[144:147], v140 offset:1024
	ds_read_b128 v[148:151], v140 offset:2048
	ds_read_b128 v[152:155], v140 offset:3072
	v_add_u32_e32 v140, s36, v142
	ds_read_b128 v[158:161], v140
	ds_read_b128 v[162:165], v140 offset:1024
	ds_read_b128 v[166:169], v140 offset:2048
	ds_read_b128 v[170:173], v140 offset:3072
	s_add_u32 s20, s18, 0xfffc0080
	s_addc_u32 s21, s19, -1
	s_cmp_eq_u32 s59, 12
	s_cselect_b32 s23, s13, s21
	s_cselect_b32 s22, s55, s20
	s_cselect_b32 s21, s11, s58
	s_cselect_b32 s20, s56, s57
	v_lshl_add_u64 v[140:141], s[18:19], 0, v[134:135]
	s_add_i32 m0, s39, 0xc000
	ds_read_b128 v[178:181], v143
	ds_read_b128 v[182:185], v143 offset:1024
	ds_read_b128 v[186:189], v143 offset:2048
	ds_read_b128 v[190:193], v143 offset:3072
	ds_read_b128 v[194:197], v143 offset:4096
	ds_read_b128 v[210:213], v143 offset:5120
	ds_read_b128 v[214:217], v143 offset:6144
	ds_read_b128 v[218:221], v143 offset:7168
	global_load_lds_dwordx4 v[140:141], off
	v_lshl_add_u64 v[140:141], s[18:19], 0, v[132:133]
	s_add_i32 m0, s39, 0xe000
	s_nop 0
	global_load_lds_dwordx4 v[140:141], off
	s_waitcnt vmcnt(8)
	s_waitcnt lgkmcnt(0)
	s_barrier
	s_setprio 1
	s_waitcnt lgkmcnt(0)
	v_mfma_f32_16x16x32_bf16 v[126:129], v[136:139], v[178:181], v[126:129]
	v_mfma_f32_16x16x32_bf16 v[122:125], v[148:151], v[178:181], v[122:125]
	v_mfma_f32_16x16x32_bf16 v[110:113], v[136:139], v[186:189], v[110:113]
	v_mfma_f32_16x16x32_bf16 v[106:109], v[148:151], v[186:189], v[106:109]
	v_mfma_f32_16x16x32_bf16 v[94:97], v[136:139], v[194:197], v[94:97]
	v_mfma_f32_16x16x32_bf16 v[90:93], v[148:151], v[194:197], v[90:93]
	v_mfma_f32_16x16x32_bf16 v[78:81], v[136:139], v[214:217], v[78:81]
	v_mfma_f32_16x16x32_bf16 v[74:77], v[148:151], v[214:217], v[74:77]
	v_mfma_f32_16x16x32_bf16 v[126:129], v[144:147], v[182:185], v[126:129]
	v_mfma_f32_16x16x32_bf16 v[122:125], v[152:155], v[182:185], v[122:125]
	v_mfma_f32_16x16x32_bf16 v[110:113], v[144:147], v[190:193], v[110:113]
	v_mfma_f32_16x16x32_bf16 v[106:109], v[152:155], v[190:193], v[106:109]
	v_mfma_f32_16x16x32_bf16 v[94:97], v[144:147], v[210:213], v[94:97]
	v_mfma_f32_16x16x32_bf16 v[90:93], v[152:155], v[210:213], v[90:93]
	v_mfma_f32_16x16x32_bf16 v[78:81], v[144:147], v[218:221], v[78:81]
	v_mfma_f32_16x16x32_bf16 v[74:77], v[152:155], v[218:221], v[74:77]
	v_mfma_f32_16x16x32_bf16 v[118:121], v[158:161], v[178:181], v[118:121]
	v_mfma_f32_16x16x32_bf16 v[114:117], v[166:169], v[178:181], v[114:117]
	v_mfma_f32_16x16x32_bf16 v[102:105], v[158:161], v[186:189], v[102:105]
	v_mfma_f32_16x16x32_bf16 v[98:101], v[166:169], v[186:189], v[98:101]
	v_mfma_f32_16x16x32_bf16 v[86:89], v[158:161], v[194:197], v[86:89]
	v_mfma_f32_16x16x32_bf16 v[82:85], v[166:169], v[194:197], v[82:85]
	v_mfma_f32_16x16x32_bf16 v[70:73], v[158:161], v[214:217], v[70:73]
	v_mfma_f32_16x16x32_bf16 v[66:69], v[166:169], v[214:217], v[66:69]
	v_mfma_f32_16x16x32_bf16 v[118:121], v[162:165], v[182:185], v[118:121]
	v_mfma_f32_16x16x32_bf16 v[114:117], v[170:173], v[182:185], v[114:117]
	v_mfma_f32_16x16x32_bf16 v[102:105], v[162:165], v[190:193], v[102:105]
	v_mfma_f32_16x16x32_bf16 v[98:101], v[170:173], v[190:193], v[98:101]
	v_mfma_f32_16x16x32_bf16 v[86:89], v[162:165], v[210:213], v[86:89]
	v_mfma_f32_16x16x32_bf16 v[82:85], v[170:173], v[210:213], v[82:85]
	v_mfma_f32_16x16x32_bf16 v[70:73], v[162:165], v[218:221], v[70:73]
	v_mfma_f32_16x16x32_bf16 v[66:69], v[170:173], v[218:221], v[66:69]
	s_setprio 0
	s_barrier
	s_mov_b32 m0, s34
	v_lshl_add_u64 v[140:141], s[20:21], 0, v[0:1]
	s_add_u32 s60, s20, 0x40000
	ds_read_b128 v[178:181], v143 offset:16384
	ds_read_b128 v[182:185], v143 offset:17408
	ds_read_b128 v[186:189], v143 offset:18432
	ds_read_b128 v[190:193], v143 offset:19456
	ds_read_b128 v[194:197], v143 offset:20480
	ds_read_b128 v[210:213], v143 offset:21504
	ds_read_b128 v[214:217], v143 offset:22528
	ds_read_b128 v[218:221], v143 offset:23552
	global_load_lds_dwordx4 v[140:141], off
	v_lshl_add_u64 v[174:175], s[20:21], 0, v[130:131]
	s_mov_b32 m0, s35
	s_addc_u32 s61, s21, 0
	global_load_lds_dwordx4 v[174:175], off
	v_lshl_add_u64 v[198:199], s[60:61], 0, v[0:1]
	s_mov_b32 m0, s37
	v_lshl_add_u64 v[202:203], s[22:23], 0, v[130:131]
	global_load_lds_dwordx4 v[198:199], off
	v_lshl_add_u64 v[198:199], s[60:61], 0, v[130:131]
	s_mov_b32 m0, s38
	s_nop 0
	global_load_lds_dwordx4 v[198:199], off
	v_lshl_add_u64 v[198:199], s[22:23], 0, v[0:1]
	s_mov_b32 m0, s39
	s_nop 0
	global_load_lds_dwordx4 v[198:199], off
	s_mov_b32 m0, s40
	s_nop 0
	global_load_lds_dwordx4 v[202:203], off
	s_waitcnt vmcnt(8)
	s_waitcnt lgkmcnt(0)
	s_barrier
; #define PG8_STAGE(bufoff, gbase, voff) do { _Pragma("unroll") for (int _i = 0; _i < 2; ++_i) \
;         __builtin_amdgcn_global_load_lds((const unsigned*)((const char*)(gbase) + (voff)[_i]), (LAS unsigned*)(lds + (bufoff) + ldsw + _i * 8192), 16, 0, 0); } while (0)
; #define PG8_LDA(dst, b, h) do { _Pragma("unroll") for (int m = 0; m < 4; ++m) _Pragma("unroll") for (int k = 0; k < 2; ++k) dst[m][k] = *(const LAS bf16x8*)(lds + PG8_SA(b, h) + aoff + m * 2048 + k * 1024); } while (0)
; #define PG8_LDB(dst, b, h) do { _Pragma("unroll") for (int n = 0; n < 2; ++n) _Pragma("unroll") for (int k = 0; k < 2; ++k) dst[n][k] = *(const LAS bf16x8*)(lds + PG8_SB(b, h) + boff + n * 2048 + k * 1024); } while (0)
; #define PG8_MMA(ai, bj, At, Bt) do { __builtin_amdgcn_s_setprio(1); _Pragma("unroll") for (int m = 0; m < 4; ++m) _Pragma("unroll") for (int n = 0; n < 2; ++n) _Pragma("unroll") for (int k = 0; k < 2; ++k) \
;         acc[ai][bj][m][n] = __builtin_amdgcn_mfma_f32_16x16x32_bf16(Bt[n][k], At[m][k], acc[ai][bj][m][n], 0, 0, 0); __builtin_amdgcn_s_setprio(0); } while (0)
; #define PG8_WAIT_V(n) asm volatile("s_waitcnt vmcnt(" #n ")" ::: "memory")
; #define PG8_WAIT_L(n) asm volatile("s_waitcnt lgkmcnt(" #n ")" ::: "memory")
; #define PG8_BAR __builtin_amdgcn_s_barrier()
; #define PG8_SCHED __builtin_amdgcn_sched_barrier(0)
; template <class Epi>
; DI void gemm_phase(LAS unsigned char* lds, const Gemm g, const StaticOrder& S, const Epi& E, int wv0) {
;     ...
;             PG8_WAIT_V(8); PG8_WAIT_L(0); PG8_BAR; PG8_MMA(1, 0, At, B0); PG8_MMA(1, 1, At, B1); PG8_BAR; PG8_SCHED;
;             PG8_LDB(B0, 1, 0); PG8_LDB(B1, 1, 1); PG8_SCHED; PG8_LDA(At, 1, 0); PG8_STAGE(PG8_SA(0, 1), a2 + hstepA, voffA);
;             PG8_WAIT_V(8); PG8_WAIT_L(0); PG8_BAR; PG8_MMA(0, 0, At, B0); PG8_MMA(0, 1, At, B1); PG8_BAR; PG8_SCHED;
	s_setprio 1
	s_waitcnt lgkmcnt(0)
	v_mfma_f32_16x16x32_bf16 v[62:65], v[136:139], v[178:181], v[62:65]
	v_mfma_f32_16x16x32_bf16 v[58:61], v[148:151], v[178:181], v[58:61]
	v_mfma_f32_16x16x32_bf16 v[46:49], v[136:139], v[186:189], v[46:49]
	v_mfma_f32_16x16x32_bf16 v[42:45], v[148:151], v[186:189], v[42:45]
	v_mfma_f32_16x16x32_bf16 v[30:33], v[136:139], v[194:197], v[30:33]
	v_mfma_f32_16x16x32_bf16 v[26:29], v[148:151], v[194:197], v[26:29]
	v_mfma_f32_16x16x32_bf16 v[14:17], v[136:139], v[214:217], v[14:17]
	v_mfma_f32_16x16x32_bf16 v[10:13], v[148:151], v[214:217], v[10:13]
	v_mfma_f32_16x16x32_bf16 v[62:65], v[144:147], v[182:185], v[62:65]
	v_mfma_f32_16x16x32_bf16 v[58:61], v[152:155], v[182:185], v[58:61]
	v_mfma_f32_16x16x32_bf16 v[46:49], v[144:147], v[190:193], v[46:49]
	v_mfma_f32_16x16x32_bf16 v[42:45], v[152:155], v[190:193], v[42:45]
	v_mfma_f32_16x16x32_bf16 v[30:33], v[144:147], v[210:213], v[30:33]
	v_mfma_f32_16x16x32_bf16 v[26:29], v[152:155], v[210:213], v[26:29]
	v_mfma_f32_16x16x32_bf16 v[14:17], v[144:147], v[218:221], v[14:17]
	v_mfma_f32_16x16x32_bf16 v[10:13], v[152:155], v[218:221], v[10:13]
	v_mfma_f32_16x16x32_bf16 v[54:57], v[158:161], v[178:181], v[54:57]
	v_mfma_f32_16x16x32_bf16 v[50:53], v[166:169], v[178:181], v[50:53]
	v_mfma_f32_16x16x32_bf16 v[38:41], v[158:161], v[186:189], v[38:41]
	v_mfma_f32_16x16x32_bf16 v[34:37], v[166:169], v[186:189], v[34:37]
	v_mfma_f32_16x16x32_bf16 v[22:25], v[158:161], v[194:197], v[22:25]
	v_mfma_f32_16x16x32_bf16 v[18:21], v[166:169], v[194:197], v[18:21]
	v_mfma_f32_16x16x32_bf16 v[6:9], v[158:161], v[214:217], v[6:9]
	v_mfma_f32_16x16x32_bf16 v[2:5], v[166:169], v[214:217], v[2:5]
	v_mfma_f32_16x16x32_bf16 v[54:57], v[162:165], v[182:185], v[54:57]
	v_mfma_f32_16x16x32_bf16 v[50:53], v[170:173], v[182:185], v[50:53]
	v_mfma_f32_16x16x32_bf16 v[38:41], v[162:165], v[190:193], v[38:41]
	v_mfma_f32_16x16x32_bf16 v[34:37], v[170:173], v[190:193], v[34:37]
	v_mfma_f32_16x16x32_bf16 v[22:25], v[162:165], v[210:213], v[22:25]
	v_mfma_f32_16x16x32_bf16 v[18:21], v[170:173], v[210:213], v[18:21]
	v_mfma_f32_16x16x32_bf16 v[6:9], v[162:165], v[218:221], v[6:9]
	v_mfma_f32_16x16x32_bf16 v[2:5], v[170:173], v[218:221], v[2:5]
	s_setprio 0
	s_barrier
	v_add_u32_e32 v152, s45, v142
	v_add_u32_e32 v170, s50, v142
	ds_read_b128 v[136:139], v152
	ds_read_b128 v[144:147], v152 offset:1024
	ds_read_b128 v[148:151], v152 offset:2048
	ds_read_b128 v[152:155], v152 offset:3072
	ds_read_b128 v[158:161], v170
	ds_read_b128 v[162:165], v170 offset:1024
	ds_read_b128 v[166:169], v170 offset:2048
	ds_read_b128 v[170:173], v170 offset:3072
	s_add_u32 s22, s22, 0x40000
	s_addc_u32 s23, s23, 0
	s_mov_b32 m0, s41
	v_lshl_add_u64 v[222:223], s[22:23], 0, v[0:1]
	ds_read_b128 v[178:181], v143 offset:32768
	ds_read_b128 v[182:185], v143 offset:33792
	ds_read_b128 v[186:189], v143 offset:34816
	ds_read_b128 v[190:193], v143 offset:35840
	ds_read_b128 v[194:197], v143 offset:36864
	ds_read_b128 v[210:213], v143 offset:37888
	ds_read_b128 v[214:217], v143 offset:38912
	ds_read_b128 v[218:221], v143 offset:39936
	global_load_lds_dwordx4 v[222:223], off
	v_lshl_add_u64 v[222:223], s[22:23], 0, v[130:131]
	s_mov_b32 m0, s42
	s_nop 0
	global_load_lds_dwordx4 v[222:223], off
	s_waitcnt vmcnt(8)
	s_waitcnt lgkmcnt(0)
	s_barrier
	s_setprio 1
	s_waitcnt lgkmcnt(0)
	v_mfma_f32_16x16x32_bf16 v[126:129], v[136:139], v[178:181], v[126:129]
	v_mfma_f32_16x16x32_bf16 v[122:125], v[148:151], v[178:181], v[122:125]
	v_mfma_f32_16x16x32_bf16 v[110:113], v[136:139], v[186:189], v[110:113]
	v_mfma_f32_16x16x32_bf16 v[106:109], v[148:151], v[186:189], v[106:109]
	v_mfma_f32_16x16x32_bf16 v[94:97], v[136:139], v[194:197], v[94:97]
	v_mfma_f32_16x16x32_bf16 v[90:93], v[148:151], v[194:197], v[90:93]
	v_mfma_f32_16x16x32_bf16 v[78:81], v[136:139], v[214:217], v[78:81]
	v_mfma_f32_16x16x32_bf16 v[74:77], v[148:151], v[214:217], v[74:77]
	v_mfma_f32_16x16x32_bf16 v[126:129], v[144:147], v[182:185], v[126:129]
	v_mfma_f32_16x16x32_bf16 v[122:125], v[152:155], v[182:185], v[122:125]
	v_mfma_f32_16x16x32_bf16 v[110:113], v[144:147], v[190:193], v[110:113]
	v_mfma_f32_16x16x32_bf16 v[106:109], v[152:155], v[190:193], v[106:109]
	v_mfma_f32_16x16x32_bf16 v[94:97], v[144:147], v[210:213], v[94:97]
	v_mfma_f32_16x16x32_bf16 v[90:93], v[152:155], v[210:213], v[90:93]
	v_mfma_f32_16x16x32_bf16 v[78:81], v[144:147], v[218:221], v[78:81]
	v_mfma_f32_16x16x32_bf16 v[74:77], v[152:155], v[218:221], v[74:77]
	v_mfma_f32_16x16x32_bf16 v[118:121], v[158:161], v[178:181], v[118:121]
	v_mfma_f32_16x16x32_bf16 v[114:117], v[166:169], v[178:181], v[114:117]
	v_mfma_f32_16x16x32_bf16 v[102:105], v[158:161], v[186:189], v[102:105]
	v_mfma_f32_16x16x32_bf16 v[98:101], v[166:169], v[186:189], v[98:101]
	v_mfma_f32_16x16x32_bf16 v[86:89], v[158:161], v[194:197], v[86:89]
	v_mfma_f32_16x16x32_bf16 v[82:85], v[166:169], v[194:197], v[82:85]
	v_mfma_f32_16x16x32_bf16 v[70:73], v[158:161], v[214:217], v[70:73]
	v_mfma_f32_16x16x32_bf16 v[66:69], v[166:169], v[214:217], v[66:69]
	v_mfma_f32_16x16x32_bf16 v[118:121], v[162:165], v[182:185], v[118:121]
	v_mfma_f32_16x16x32_bf16 v[114:117], v[170:173], v[182:185], v[114:117]
	v_mfma_f32_16x16x32_bf16 v[102:105], v[162:165], v[190:193], v[102:105]
	v_mfma_f32_16x16x32_bf16 v[98:101], v[170:173], v[190:193], v[98:101]
	v_mfma_f32_16x16x32_bf16 v[86:89], v[162:165], v[210:213], v[86:89]
	v_mfma_f32_16x16x32_bf16 v[82:85], v[170:173], v[210:213], v[82:85]
	v_mfma_f32_16x16x32_bf16 v[70:73], v[162:165], v[218:221], v[70:73]
	v_mfma_f32_16x16x32_bf16 v[66:69], v[170:173], v[218:221], v[66:69]
	s_setprio 0
	s_barrier
; #define PG8_STAGE(bufoff, gbase, voff) do { _Pragma("unroll") for (int _i = 0; _i < 2; ++_i) \
;         __builtin_amdgcn_global_load_lds((const unsigned*)((const char*)(gbase) + (voff)[_i]), (LAS unsigned*)(lds + (bufoff) + ldsw + _i * 8192), 16, 0, 0); } while (0)
; #define PG8_LDA(dst, b, h) do { _Pragma("unroll") for (int m = 0; m < 4; ++m) _Pragma("unroll") for (int k = 0; k < 2; ++k) dst[m][k] = *(const LAS bf16x8*)(lds + PG8_SA(b, h) + aoff + m * 2048 + k * 1024); } while (0)
; #define PG8_MMA(ai, bj, At, Bt) do { __builtin_amdgcn_s_setprio(1); _Pragma("unroll") for (int m = 0; m < 4; ++m) _Pragma("unroll") for (int n = 0; n < 2; ++n) _Pragma("unroll") for (int k = 0; k < 2; ++k) \
;         acc[ai][bj][m][n] = __builtin_amdgcn_mfma_f32_16x16x32_bf16(Bt[n][k], At[m][k], acc[ai][bj][m][n], 0, 0, 0); __builtin_amdgcn_s_setprio(0); } while (0)
; #define PG8_WAIT_V(n) asm volatile("s_waitcnt vmcnt(" #n ")" ::: "memory")
; #define PG8_WAIT_L(n) asm volatile("s_waitcnt lgkmcnt(" #n ")" ::: "memory")
; #define PG8_BAR __builtin_amdgcn_s_barrier()
; #define PG8_SCHED __builtin_amdgcn_sched_barrier(0)
; template <class Epi>
; DI void gemm_phase(LAS unsigned char* lds, const Gemm g, const StaticOrder& S, const Epi& E, int wv0) {
;     ...
;             PG8_LDA(At, 1, 1); PG8_STAGE(PG8_SB(1, 0), b3, voffB); PG8_STAGE(PG8_SB(1, 1), b3 + hstepB, voffB); PG8_STAGE(PG8_SA(1, 0), a3, voffA);
;             PG8_WAIT_V(8); PG8_WAIT_L(0); PG8_BAR; PG8_MMA(1, 0, At, B0); PG8_MMA(1, 1, At, B1); PG8_BAR; PG8_SCHED;
;         }
	s_mov_b32 m0, s46
	v_lshl_add_u64 v[140:141], v[140:141], 0, s[86:87]
	s_add_u32 s20, s20, 0x40080
	ds_read_b128 v[178:181], v143 offset:49152
	ds_read_b128 v[182:185], v143 offset:50176
	ds_read_b128 v[186:189], v143 offset:51200
	ds_read_b128 v[190:193], v143 offset:52224
	ds_read_b128 v[194:197], v143 offset:53248
	ds_read_b128 v[210:213], v143 offset:54272
	ds_read_b128 v[214:217], v143 offset:55296
	ds_read_b128 v[218:221], v143 offset:56320
	global_load_lds_dwordx4 v[140:141], off
	v_lshl_add_u64 v[140:141], v[174:175], 0, s[86:87]
	s_mov_b32 m0, s47
	s_addc_u32 s21, s21, 0
	global_load_lds_dwordx4 v[140:141], off
	v_lshl_add_u64 v[140:141], s[20:21], 0, v[0:1]
	s_mov_b32 m0, s51
	s_nop 0
	global_load_lds_dwordx4 v[140:141], off
	v_lshl_add_u64 v[140:141], s[20:21], 0, v[130:131]
	s_mov_b32 m0, s52
	s_nop 0
	global_load_lds_dwordx4 v[140:141], off
	v_lshl_add_u64 v[140:141], v[198:199], 0, s[86:87]
	s_mov_b32 m0, s48
	s_nop 0
	global_load_lds_dwordx4 v[140:141], off
	v_lshl_add_u64 v[140:141], v[202:203], 0, s[86:87]
	s_mov_b32 m0, s49
	s_nop 0
	global_load_lds_dwordx4 v[140:141], off
	s_waitcnt vmcnt(8)
	s_waitcnt lgkmcnt(0)
	s_barrier
	s_setprio 1
	s_waitcnt lgkmcnt(0)
	v_mfma_f32_16x16x32_bf16 v[62:65], v[136:139], v[178:181], v[62:65]
	v_mfma_f32_16x16x32_bf16 v[58:61], v[148:151], v[178:181], v[58:61]
	v_mfma_f32_16x16x32_bf16 v[46:49], v[136:139], v[186:189], v[46:49]
	v_mfma_f32_16x16x32_bf16 v[42:45], v[148:151], v[186:189], v[42:45]
	v_mfma_f32_16x16x32_bf16 v[30:33], v[136:139], v[194:197], v[30:33]
	v_mfma_f32_16x16x32_bf16 v[26:29], v[148:151], v[194:197], v[26:29]
	v_mfma_f32_16x16x32_bf16 v[14:17], v[136:139], v[214:217], v[14:17]
	v_mfma_f32_16x16x32_bf16 v[10:13], v[148:151], v[214:217], v[10:13]
	v_mfma_f32_16x16x32_bf16 v[62:65], v[144:147], v[182:185], v[62:65]
	v_mfma_f32_16x16x32_bf16 v[58:61], v[152:155], v[182:185], v[58:61]
	v_mfma_f32_16x16x32_bf16 v[46:49], v[144:147], v[190:193], v[46:49]
	v_mfma_f32_16x16x32_bf16 v[42:45], v[152:155], v[190:193], v[42:45]
	v_mfma_f32_16x16x32_bf16 v[30:33], v[144:147], v[210:213], v[30:33]
	v_mfma_f32_16x16x32_bf16 v[26:29], v[152:155], v[210:213], v[26:29]
	v_mfma_f32_16x16x32_bf16 v[14:17], v[144:147], v[218:221], v[14:17]
	v_mfma_f32_16x16x32_bf16 v[10:13], v[152:155], v[218:221], v[10:13]
	v_mfma_f32_16x16x32_bf16 v[54:57], v[158:161], v[178:181], v[54:57]
	v_mfma_f32_16x16x32_bf16 v[50:53], v[166:169], v[178:181], v[50:53]
	v_mfma_f32_16x16x32_bf16 v[38:41], v[158:161], v[186:189], v[38:41]
	v_mfma_f32_16x16x32_bf16 v[34:37], v[166:169], v[186:189], v[34:37]
	v_mfma_f32_16x16x32_bf16 v[22:25], v[158:161], v[194:197], v[22:25]
	v_mfma_f32_16x16x32_bf16 v[18:21], v[166:169], v[194:197], v[18:21]
	v_mfma_f32_16x16x32_bf16 v[6:9], v[158:161], v[214:217], v[6:9]
	v_mfma_f32_16x16x32_bf16 v[2:5], v[166:169], v[214:217], v[2:5]
	v_mfma_f32_16x16x32_bf16 v[54:57], v[162:165], v[182:185], v[54:57]
	v_mfma_f32_16x16x32_bf16 v[50:53], v[170:173], v[182:185], v[50:53]
	v_mfma_f32_16x16x32_bf16 v[38:41], v[162:165], v[190:193], v[38:41]
	v_mfma_f32_16x16x32_bf16 v[34:37], v[170:173], v[190:193], v[34:37]
	v_mfma_f32_16x16x32_bf16 v[22:25], v[162:165], v[210:213], v[22:25]
	v_mfma_f32_16x16x32_bf16 v[18:21], v[170:173], v[210:213], v[18:21]
	v_mfma_f32_16x16x32_bf16 v[6:9], v[162:165], v[218:221], v[6:9]
	v_mfma_f32_16x16x32_bf16 v[2:5], v[170:173], v[218:221], v[2:5]
	s_setprio 0
	s_barrier
	s_add_i32 s59, s59, 2
	s_add_u32 s57, s57, 0x100
	s_addc_u32 s58, s58, 0
	s_add_u32 s18, s18, 0x100
	s_addc_u32 s19, s19, 0
	s_cmp_gt_u32 s59, 13
	s_cbranch_scc0 .LBB0_1456
	s_and_b64 vcc, exec, s[8:9]
	s_cbranch_vccz .LBB0_1459
	s_barrier

; #define PG8_STAGE(bufoff, gbase, voff) do { _Pragma("unroll") for (int _i = 0; _i < 2; ++_i) \
;         __builtin_amdgcn_global_load_lds((const unsigned*)((const char*)(gbase) + (voff)[_i]), (LAS unsigned*)(lds + (bufoff) + ldsw + _i * 8192), 16, 0, 0); } while (0)
; #define PG8_LDA(dst, b, h) do { _Pragma("unroll") for (int m = 0; m < 4; ++m) _Pragma("unroll") for (int k = 0; k < 2; ++k) dst[m][k] = *(const LAS bf16x8*)(lds + PG8_SA(b, h) + aoff + m * 2048 + k * 1024); } while (0)
; #define PG8_LDB(dst, b, h) do { _Pragma("unroll") for (int n = 0; n < 2; ++n) _Pragma("unroll") for (int k = 0; k < 2; ++k) dst[n][k] = *(const LAS bf16x8*)(lds + PG8_SB(b, h) + boff + n * 2048 + k * 1024); } while (0)
; #define PG8_MMA(ai, bj, At, Bt) do { __builtin_amdgcn_s_setprio(1); _Pragma("unroll") for (int m = 0; m < 4; ++m) _Pragma("unroll") for (int n = 0; n < 2; ++n) _Pragma("unroll") for (int k = 0; k < 2; ++k) \
;         acc[ai][bj][m][n] = __builtin_amdgcn_mfma_f32_16x16x32_bf16(Bt[n][k], At[m][k], acc[ai][bj][m][n], 0, 0, 0); __builtin_amdgcn_s_setprio(0); } while (0)
; #define PG8_WAIT_V(n) asm volatile("s_waitcnt vmcnt(" #n ")" ::: "memory")
; #define PG8_WAIT_L(n) asm volatile("s_waitcnt lgkmcnt(" #n ")" ::: "memory")
; #define PG8_BAR __builtin_amdgcn_s_barrier()
; #define PG8_SCHED __builtin_amdgcn_sched_barrier(0)
; template <class Epi>
; DI void gemm_phase(LAS unsigned char* lds, const Gemm g, const StaticOrder& S, const Epi& E, int wv0) {
;     ...
;             const bool last = (t == nt - 2);
;             const char* a1 = cA + (size_t)(t + 1) * kstep;
;             const char* a2 = last ? nA : cA + (size_t)(t + 2) * kstep; const char* b2 = last ? nB : cB + (size_t)(t + 2) * kstep;
;             const char* a3 = a2 + kstep; const char* b3 = b2 + kstep;
;             PG8_LDB(B0, 0, 0); PG8_LDB(B1, 0, 1); PG8_SCHED; PG8_LDA(At, 0, 0); PG8_STAGE(PG8_SA(1, 1), a1 + hstepA, voffA);
;             PG8_WAIT_V(8); PG8_WAIT_L(0); PG8_BAR; PG8_MMA(0, 0, At, B0); PG8_MMA(0, 1, At, B1); PG8_BAR; PG8_SCHED;
;             PG8_LDA(At, 0, 1); PG8_STAGE(PG8_SB(0, 0), b2, voffB); PG8_STAGE(PG8_SB(0, 1), b2 + hstepB, voffB); PG8_STAGE(PG8_SA(0, 0), a2, voffA);
.LBB0_1563:
	v_add_u32_e32 v140, s64, v142
	ds_read_b128 v[144:147], v140
	ds_read_b128 v[148:151], v140 offset:1024
	ds_read_b128 v[152:155], v140 offset:2048
	ds_read_b128 v[158:161], v140 offset:3072
	v_add_u32_e32 v140, s65, v142
	ds_read_b128 v[162:165], v140
	ds_read_b128 v[166:169], v140 offset:1024
	ds_read_b128 v[170:173], v140 offset:2048
	ds_read_b128 v[178:181], v140 offset:3072
	s_add_u32 s18, s16, 0xfffc0080
	s_addc_u32 s19, s17, -1
	s_cmp_eq_u32 s55, 12
	s_cselect_b32 s21, s11, s19
	s_cselect_b32 s20, s51, s18
	s_cselect_b32 s19, s9, s54
	s_cselect_b32 s18, s52, s53
	v_lshl_add_u64 v[140:141], s[16:17], 0, v[138:139]
	s_add_i32 m0, s30, 0xc000
	ds_read_b128 v[182:185], v143
	ds_read_b128 v[186:189], v143 offset:1024
	ds_read_b128 v[190:193], v143 offset:2048
	ds_read_b128 v[194:197], v143 offset:3072
	ds_read_b128 v[210:213], v143 offset:4096
	ds_read_b128 v[214:217], v143 offset:5120
	ds_read_b128 v[218:221], v143 offset:6144
	ds_read_b128 v[222:225], v143 offset:7168
	global_load_lds_dwordx4 v[140:141], off
	v_lshl_add_u64 v[140:141], s[16:17], 0, v[136:137]
	s_add_i32 m0, s30, 0xe000
	s_nop 0
	global_load_lds_dwordx4 v[140:141], off
	s_waitcnt vmcnt(8)
	s_waitcnt lgkmcnt(0)
	s_barrier
	s_setprio 1
	s_waitcnt lgkmcnt(0)
	v_mfma_f32_16x16x32_bf16 v[126:129], v[144:147], v[182:185], v[126:129]
	v_mfma_f32_16x16x32_bf16 v[122:125], v[152:155], v[182:185], v[122:125]
	v_mfma_f32_16x16x32_bf16 v[110:113], v[144:147], v[190:193], v[110:113]
	v_mfma_f32_16x16x32_bf16 v[106:109], v[152:155], v[190:193], v[106:109]
	v_mfma_f32_16x16x32_bf16 v[94:97], v[144:147], v[210:213], v[94:97]
	v_mfma_f32_16x16x32_bf16 v[90:93], v[152:155], v[210:213], v[90:93]
	v_mfma_f32_16x16x32_bf16 v[78:81], v[144:147], v[218:221], v[78:81]
	v_mfma_f32_16x16x32_bf16 v[74:77], v[152:155], v[218:221], v[74:77]
	v_mfma_f32_16x16x32_bf16 v[126:129], v[148:151], v[186:189], v[126:129]
	v_mfma_f32_16x16x32_bf16 v[122:125], v[158:161], v[186:189], v[122:125]
	v_mfma_f32_16x16x32_bf16 v[110:113], v[148:151], v[194:197], v[110:113]
	v_mfma_f32_16x16x32_bf16 v[106:109], v[158:161], v[194:197], v[106:109]
	v_mfma_f32_16x16x32_bf16 v[94:97], v[148:151], v[214:217], v[94:97]
	v_mfma_f32_16x16x32_bf16 v[90:93], v[158:161], v[214:217], v[90:93]
	v_mfma_f32_16x16x32_bf16 v[78:81], v[148:151], v[222:225], v[78:81]
	v_mfma_f32_16x16x32_bf16 v[74:77], v[158:161], v[222:225], v[74:77]
	v_mfma_f32_16x16x32_bf16 v[118:121], v[162:165], v[182:185], v[118:121]
	v_mfma_f32_16x16x32_bf16 v[114:117], v[170:173], v[182:185], v[114:117]
	v_mfma_f32_16x16x32_bf16 v[102:105], v[162:165], v[190:193], v[102:105]
	v_mfma_f32_16x16x32_bf16 v[98:101], v[170:173], v[190:193], v[98:101]
	v_mfma_f32_16x16x32_bf16 v[86:89], v[162:165], v[210:213], v[86:89]
	v_mfma_f32_16x16x32_bf16 v[82:85], v[170:173], v[210:213], v[82:85]
	v_mfma_f32_16x16x32_bf16 v[70:73], v[162:165], v[218:221], v[70:73]
	v_mfma_f32_16x16x32_bf16 v[66:69], v[170:173], v[218:221], v[66:69]
	v_mfma_f32_16x16x32_bf16 v[118:121], v[166:169], v[186:189], v[118:121]
	v_mfma_f32_16x16x32_bf16 v[114:117], v[178:181], v[186:189], v[114:117]
	v_mfma_f32_16x16x32_bf16 v[102:105], v[166:169], v[194:197], v[102:105]
	v_mfma_f32_16x16x32_bf16 v[98:101], v[178:181], v[194:197], v[98:101]
	v_mfma_f32_16x16x32_bf16 v[86:89], v[166:169], v[214:217], v[86:89]
	v_mfma_f32_16x16x32_bf16 v[82:85], v[178:181], v[214:217], v[82:85]
	v_mfma_f32_16x16x32_bf16 v[70:73], v[166:169], v[222:225], v[70:73]
	v_mfma_f32_16x16x32_bf16 v[66:69], v[178:181], v[222:225], v[66:69]
	s_setprio 0
	s_barrier
	s_mov_b32 m0, s26
	v_lshl_add_u64 v[140:141], s[18:19], 0, v[0:1]
	s_add_u32 s56, s18, 0x40000
	ds_read_b128 v[182:185], v143 offset:16384
	ds_read_b128 v[186:189], v143 offset:17408
	ds_read_b128 v[190:193], v143 offset:18432
	ds_read_b128 v[194:197], v143 offset:19456
	ds_read_b128 v[210:213], v143 offset:20480
	ds_read_b128 v[214:217], v143 offset:21504
	ds_read_b128 v[218:221], v143 offset:22528
	ds_read_b128 v[222:225], v143 offset:23552
	global_load_lds_dwordx4 v[140:141], off
	v_lshl_add_u64 v[174:175], s[18:19], 0, v[130:131]
	s_mov_b32 m0, s27
	s_addc_u32 s57, s19, 0
	global_load_lds_dwordx4 v[174:175], off
	v_lshl_add_u64 v[198:199], s[56:57], 0, v[0:1]
	s_mov_b32 m0, s28
	v_lshl_add_u64 v[202:203], s[20:21], 0, v[132:133]
	global_load_lds_dwordx4 v[198:199], off
	v_lshl_add_u64 v[198:199], s[56:57], 0, v[130:131]
	s_mov_b32 m0, s29
	s_nop 0
	global_load_lds_dwordx4 v[198:199], off
	v_lshl_add_u64 v[198:199], s[20:21], 0, v[134:135]
	s_mov_b32 m0, s30
	s_nop 0
	global_load_lds_dwordx4 v[198:199], off
	s_mov_b32 m0, s31
	s_nop 0
	global_load_lds_dwordx4 v[202:203], off
	s_waitcnt vmcnt(8)
	s_waitcnt lgkmcnt(0)
	s_barrier
; #define PG8_STAGE(bufoff, gbase, voff) do { _Pragma("unroll") for (int _i = 0; _i < 2; ++_i) \
;         __builtin_amdgcn_global_load_lds((const unsigned*)((const char*)(gbase) + (voff)[_i]), (LAS unsigned*)(lds + (bufoff) + ldsw + _i * 8192), 16, 0, 0); } while (0)
; #define PG8_LDA(dst, b, h) do { _Pragma("unroll") for (int m = 0; m < 4; ++m) _Pragma("unroll") for (int k = 0; k < 2; ++k) dst[m][k] = *(const LAS bf16x8*)(lds + PG8_SA(b, h) + aoff + m * 2048 + k * 1024); } while (0)
; #define PG8_LDB(dst, b, h) do { _Pragma("unroll") for (int n = 0; n < 2; ++n) _Pragma("unroll") for (int k = 0; k < 2; ++k) dst[n][k] = *(const LAS bf16x8*)(lds + PG8_SB(b, h) + boff + n * 2048 + k * 1024); } while (0)
; #define PG8_MMA(ai, bj, At, Bt) do { __builtin_amdgcn_s_setprio(1); _Pragma("unroll") for (int m = 0; m < 4; ++m) _Pragma("unroll") for (int n = 0; n < 2; ++n) _Pragma("unroll") for (int k = 0; k < 2; ++k) \
;         acc[ai][bj][m][n] = __builtin_amdgcn_mfma_f32_16x16x32_bf16(Bt[n][k], At[m][k], acc[ai][bj][m][n], 0, 0, 0); __builtin_amdgcn_s_setprio(0); } while (0)
; #define PG8_WAIT_V(n) asm volatile("s_waitcnt vmcnt(" #n ")" ::: "memory")
; #define PG8_WAIT_L(n) asm volatile("s_waitcnt lgkmcnt(" #n ")" ::: "memory")
; #define PG8_BAR __builtin_amdgcn_s_barrier()
; #define PG8_SCHED __builtin_amdgcn_sched_barrier(0)
; template <class Epi>
; DI void gemm_phase(LAS unsigned char* lds, const Gemm g, const StaticOrder& S, const Epi& E, int wv0) {
;     ...
;             PG8_WAIT_V(8); PG8_WAIT_L(0); PG8_BAR; PG8_MMA(1, 0, At, B0); PG8_MMA(1, 1, At, B1); PG8_BAR; PG8_SCHED;
;             PG8_LDB(B0, 1, 0); PG8_LDB(B1, 1, 1); PG8_SCHED; PG8_LDA(At, 1, 0); PG8_STAGE(PG8_SA(0, 1), a2 + hstepA, voffA);
;             PG8_WAIT_V(8); PG8_WAIT_L(0); PG8_BAR; PG8_MMA(0, 0, At, B0); PG8_MMA(0, 1, At, B1); PG8_BAR; PG8_SCHED;
	s_setprio 1
	s_waitcnt lgkmcnt(0)
	v_mfma_f32_16x16x32_bf16 v[62:65], v[144:147], v[182:185], v[62:65]
	v_mfma_f32_16x16x32_bf16 v[58:61], v[152:155], v[182:185], v[58:61]
	v_mfma_f32_16x16x32_bf16 v[46:49], v[144:147], v[190:193], v[46:49]
	v_mfma_f32_16x16x32_bf16 v[42:45], v[152:155], v[190:193], v[42:45]
	v_mfma_f32_16x16x32_bf16 v[30:33], v[144:147], v[210:213], v[30:33]
	v_mfma_f32_16x16x32_bf16 v[26:29], v[152:155], v[210:213], v[26:29]
	v_mfma_f32_16x16x32_bf16 v[14:17], v[144:147], v[218:221], v[14:17]
	v_mfma_f32_16x16x32_bf16 v[10:13], v[152:155], v[218:221], v[10:13]
	v_mfma_f32_16x16x32_bf16 v[62:65], v[148:151], v[186:189], v[62:65]
	v_mfma_f32_16x16x32_bf16 v[58:61], v[158:161], v[186:189], v[58:61]
	v_mfma_f32_16x16x32_bf16 v[46:49], v[148:151], v[194:197], v[46:49]
	v_mfma_f32_16x16x32_bf16 v[42:45], v[158:161], v[194:197], v[42:45]
	v_mfma_f32_16x16x32_bf16 v[30:33], v[148:151], v[214:217], v[30:33]
	v_mfma_f32_16x16x32_bf16 v[26:29], v[158:161], v[214:217], v[26:29]
	v_mfma_f32_16x16x32_bf16 v[14:17], v[148:151], v[222:225], v[14:17]
	v_mfma_f32_16x16x32_bf16 v[10:13], v[158:161], v[222:225], v[10:13]
	v_mfma_f32_16x16x32_bf16 v[54:57], v[162:165], v[182:185], v[54:57]
	v_mfma_f32_16x16x32_bf16 v[50:53], v[170:173], v[182:185], v[50:53]
	v_mfma_f32_16x16x32_bf16 v[38:41], v[162:165], v[190:193], v[38:41]
	v_mfma_f32_16x16x32_bf16 v[34:37], v[170:173], v[190:193], v[34:37]
	v_mfma_f32_16x16x32_bf16 v[22:25], v[162:165], v[210:213], v[22:25]
	v_mfma_f32_16x16x32_bf16 v[18:21], v[170:173], v[210:213], v[18:21]
	v_mfma_f32_16x16x32_bf16 v[6:9], v[162:165], v[218:221], v[6:9]
	v_mfma_f32_16x16x32_bf16 v[2:5], v[170:173], v[218:221], v[2:5]
	v_mfma_f32_16x16x32_bf16 v[54:57], v[166:169], v[186:189], v[54:57]
	v_mfma_f32_16x16x32_bf16 v[50:53], v[178:181], v[186:189], v[50:53]
	v_mfma_f32_16x16x32_bf16 v[38:41], v[166:169], v[194:197], v[38:41]
	v_mfma_f32_16x16x32_bf16 v[34:37], v[178:181], v[194:197], v[34:37]
	v_mfma_f32_16x16x32_bf16 v[22:25], v[166:169], v[214:217], v[22:25]
	v_mfma_f32_16x16x32_bf16 v[18:21], v[178:181], v[214:217], v[18:21]
	v_mfma_f32_16x16x32_bf16 v[6:9], v[166:169], v[222:225], v[6:9]
	v_mfma_f32_16x16x32_bf16 v[2:5], v[178:181], v[222:225], v[2:5]
	s_setprio 0
	s_barrier
	v_add_u32_e32 v158, s66, v142
	v_add_u32_e32 v176, s67, v142
	ds_read_b128 v[144:147], v158
	ds_read_b128 v[148:151], v158 offset:1024
	ds_read_b128 v[152:155], v158 offset:2048
	ds_read_b128 v[158:161], v158 offset:3072
	ds_read_b128 v[162:165], v176
	ds_read_b128 v[166:169], v176 offset:1024
	ds_read_b128 v[170:173], v176 offset:2048
	ds_read_b128 v[178:181], v176 offset:3072
	s_add_u32 s20, s20, 0x40000
	s_addc_u32 s21, s21, 0
	s_mov_b32 m0, s40
	v_lshl_add_u64 v[226:227], s[20:21], 0, v[134:135]
	ds_read_b128 v[182:185], v143 offset:32768
	ds_read_b128 v[186:189], v143 offset:33792
	ds_read_b128 v[190:193], v143 offset:34816
	ds_read_b128 v[194:197], v143 offset:35840
	ds_read_b128 v[210:213], v143 offset:36864
	ds_read_b128 v[214:217], v143 offset:37888
	ds_read_b128 v[218:221], v143 offset:38912
	ds_read_b128 v[222:225], v143 offset:39936
	global_load_lds_dwordx4 v[226:227], off
	v_lshl_add_u64 v[226:227], s[20:21], 0, v[132:133]
	s_mov_b32 m0, s41
	s_nop 0
	global_load_lds_dwordx4 v[226:227], off
	s_waitcnt vmcnt(8)
	s_waitcnt lgkmcnt(0)
	s_barrier
	s_setprio 1
	s_waitcnt lgkmcnt(0)
	v_mfma_f32_16x16x32_bf16 v[126:129], v[144:147], v[182:185], v[126:129]
	v_mfma_f32_16x16x32_bf16 v[122:125], v[152:155], v[182:185], v[122:125]
	v_mfma_f32_16x16x32_bf16 v[110:113], v[144:147], v[190:193], v[110:113]
	v_mfma_f32_16x16x32_bf16 v[106:109], v[152:155], v[190:193], v[106:109]
	v_mfma_f32_16x16x32_bf16 v[94:97], v[144:147], v[210:213], v[94:97]
	v_mfma_f32_16x16x32_bf16 v[90:93], v[152:155], v[210:213], v[90:93]
	v_mfma_f32_16x16x32_bf16 v[78:81], v[144:147], v[218:221], v[78:81]
	v_mfma_f32_16x16x32_bf16 v[74:77], v[152:155], v[218:221], v[74:77]
	v_mfma_f32_16x16x32_bf16 v[126:129], v[148:151], v[186:189], v[126:129]
	v_mfma_f32_16x16x32_bf16 v[122:125], v[158:161], v[186:189], v[122:125]
	v_mfma_f32_16x16x32_bf16 v[110:113], v[148:151], v[194:197], v[110:113]
	v_mfma_f32_16x16x32_bf16 v[106:109], v[158:161], v[194:197], v[106:109]
	v_mfma_f32_16x16x32_bf16 v[94:97], v[148:151], v[214:217], v[94:97]
	v_mfma_f32_16x16x32_bf16 v[90:93], v[158:161], v[214:217], v[90:93]
	v_mfma_f32_16x16x32_bf16 v[78:81], v[148:151], v[222:225], v[78:81]
	v_mfma_f32_16x16x32_bf16 v[74:77], v[158:161], v[222:225], v[74:77]
	v_mfma_f32_16x16x32_bf16 v[118:121], v[162:165], v[182:185], v[118:121]
	v_mfma_f32_16x16x32_bf16 v[114:117], v[170:173], v[182:185], v[114:117]
	v_mfma_f32_16x16x32_bf16 v[102:105], v[162:165], v[190:193], v[102:105]
	v_mfma_f32_16x16x32_bf16 v[98:101], v[170:173], v[190:193], v[98:101]
	v_mfma_f32_16x16x32_bf16 v[86:89], v[162:165], v[210:213], v[86:89]
	v_mfma_f32_16x16x32_bf16 v[82:85], v[170:173], v[210:213], v[82:85]
	v_mfma_f32_16x16x32_bf16 v[70:73], v[162:165], v[218:221], v[70:73]
	v_mfma_f32_16x16x32_bf16 v[66:69], v[170:173], v[218:221], v[66:69]
	v_mfma_f32_16x16x32_bf16 v[118:121], v[166:169], v[186:189], v[118:121]
	v_mfma_f32_16x16x32_bf16 v[114:117], v[178:181], v[186:189], v[114:117]
	v_mfma_f32_16x16x32_bf16 v[102:105], v[166:169], v[194:197], v[102:105]
	v_mfma_f32_16x16x32_bf16 v[98:101], v[178:181], v[194:197], v[98:101]
	v_mfma_f32_16x16x32_bf16 v[86:89], v[166:169], v[214:217], v[86:89]
	v_mfma_f32_16x16x32_bf16 v[82:85], v[178:181], v[214:217], v[82:85]
	v_mfma_f32_16x16x32_bf16 v[70:73], v[166:169], v[222:225], v[70:73]
	v_mfma_f32_16x16x32_bf16 v[66:69], v[178:181], v[222:225], v[66:69]
	s_setprio 0
	s_barrier
; #define PG8_STAGE(bufoff, gbase, voff) do { _Pragma("unroll") for (int _i = 0; _i < 2; ++_i) \
;         __builtin_amdgcn_global_load_lds((const unsigned*)((const char*)(gbase) + (voff)[_i]), (LAS unsigned*)(lds + (bufoff) + ldsw + _i * 8192), 16, 0, 0); } while (0)
; #define PG8_LDA(dst, b, h) do { _Pragma("unroll") for (int m = 0; m < 4; ++m) _Pragma("unroll") for (int k = 0; k < 2; ++k) dst[m][k] = *(const LAS bf16x8*)(lds + PG8_SA(b, h) + aoff + m * 2048 + k * 1024); } while (0)
; #define PG8_MMA(ai, bj, At, Bt) do { __builtin_amdgcn_s_setprio(1); _Pragma("unroll") for (int m = 0; m < 4; ++m) _Pragma("unroll") for (int n = 0; n < 2; ++n) _Pragma("unroll") for (int k = 0; k < 2; ++k) \
;         acc[ai][bj][m][n] = __builtin_amdgcn_mfma_f32_16x16x32_bf16(Bt[n][k], At[m][k], acc[ai][bj][m][n], 0, 0, 0); __builtin_amdgcn_s_setprio(0); } while (0)
; #define PG8_WAIT_V(n) asm volatile("s_waitcnt vmcnt(" #n ")" ::: "memory")
; #define PG8_WAIT_L(n) asm volatile("s_waitcnt lgkmcnt(" #n ")" ::: "memory")
; #define PG8_BAR __builtin_amdgcn_s_barrier()
; #define PG8_SCHED __builtin_amdgcn_sched_barrier(0)
; template <class Epi>
; DI void gemm_phase(LAS unsigned char* lds, const Gemm g, const StaticOrder& S, const Epi& E, int wv0) {
;     ...
;             PG8_LDA(At, 1, 1); PG8_STAGE(PG8_SB(1, 0), b3, voffB); PG8_STAGE(PG8_SB(1, 1), b3 + hstepB, voffB); PG8_STAGE(PG8_SA(1, 0), a3, voffA);
;             PG8_WAIT_V(8); PG8_WAIT_L(0); PG8_BAR; PG8_MMA(1, 0, At, B0); PG8_MMA(1, 1, At, B1); PG8_BAR; PG8_SCHED;
;         }
	s_mov_b32 m0, s44
	v_lshl_add_u64 v[140:141], v[140:141], 0, s[86:87]
	s_add_u32 s18, s18, 0x40080
	ds_read_b128 v[182:185], v143 offset:49152
	ds_read_b128 v[186:189], v143 offset:50176
	ds_read_b128 v[190:193], v143 offset:51200
	ds_read_b128 v[194:197], v143 offset:52224
	ds_read_b128 v[210:213], v143 offset:53248
	ds_read_b128 v[214:217], v143 offset:54272
	ds_read_b128 v[218:221], v143 offset:55296
	ds_read_b128 v[222:225], v143 offset:56320
	global_load_lds_dwordx4 v[140:141], off
	v_lshl_add_u64 v[140:141], v[174:175], 0, s[86:87]
	s_mov_b32 m0, s45
	s_addc_u32 s19, s19, 0
	global_load_lds_dwordx4 v[140:141], off
	v_lshl_add_u64 v[140:141], s[18:19], 0, v[0:1]
	s_mov_b32 m0, s48
	s_nop 0
	global_load_lds_dwordx4 v[140:141], off
	v_lshl_add_u64 v[140:141], s[18:19], 0, v[130:131]
	s_mov_b32 m0, s49
	s_nop 0
	global_load_lds_dwordx4 v[140:141], off
	v_lshl_add_u64 v[140:141], v[198:199], 0, s[86:87]
	s_mov_b32 m0, s46
	s_nop 0
	global_load_lds_dwordx4 v[140:141], off
	v_lshl_add_u64 v[140:141], v[202:203], 0, s[86:87]
	s_mov_b32 m0, s47
	s_nop 0
	global_load_lds_dwordx4 v[140:141], off
	s_waitcnt vmcnt(8)
	s_waitcnt lgkmcnt(0)
	s_barrier
	s_setprio 1
	s_waitcnt lgkmcnt(0)
	v_mfma_f32_16x16x32_bf16 v[62:65], v[144:147], v[182:185], v[62:65]
	v_mfma_f32_16x16x32_bf16 v[58:61], v[152:155], v[182:185], v[58:61]
	v_mfma_f32_16x16x32_bf16 v[46:49], v[144:147], v[190:193], v[46:49]
	v_mfma_f32_16x16x32_bf16 v[42:45], v[152:155], v[190:193], v[42:45]
	v_mfma_f32_16x16x32_bf16 v[30:33], v[144:147], v[210:213], v[30:33]
	v_mfma_f32_16x16x32_bf16 v[26:29], v[152:155], v[210:213], v[26:29]
	v_mfma_f32_16x16x32_bf16 v[14:17], v[144:147], v[218:221], v[14:17]
	v_mfma_f32_16x16x32_bf16 v[10:13], v[152:155], v[218:221], v[10:13]
	v_mfma_f32_16x16x32_bf16 v[62:65], v[148:151], v[186:189], v[62:65]
	v_mfma_f32_16x16x32_bf16 v[58:61], v[158:161], v[186:189], v[58:61]
	v_mfma_f32_16x16x32_bf16 v[46:49], v[148:151], v[194:197], v[46:49]
	v_mfma_f32_16x16x32_bf16 v[42:45], v[158:161], v[194:197], v[42:45]
	v_mfma_f32_16x16x32_bf16 v[30:33], v[148:151], v[214:217], v[30:33]
	v_mfma_f32_16x16x32_bf16 v[26:29], v[158:161], v[214:217], v[26:29]
	v_mfma_f32_16x16x32_bf16 v[14:17], v[148:151], v[222:225], v[14:17]
	v_mfma_f32_16x16x32_bf16 v[10:13], v[158:161], v[222:225], v[10:13]
	v_mfma_f32_16x16x32_bf16 v[54:57], v[162:165], v[182:185], v[54:57]
	v_mfma_f32_16x16x32_bf16 v[50:53], v[170:173], v[182:185], v[50:53]
	v_mfma_f32_16x16x32_bf16 v[38:41], v[162:165], v[190:193], v[38:41]
	v_mfma_f32_16x16x32_bf16 v[34:37], v[170:173], v[190:193], v[34:37]
	v_mfma_f32_16x16x32_bf16 v[22:25], v[162:165], v[210:213], v[22:25]
	v_mfma_f32_16x16x32_bf16 v[18:21], v[170:173], v[210:213], v[18:21]
	v_mfma_f32_16x16x32_bf16 v[6:9], v[162:165], v[218:221], v[6:9]
	v_mfma_f32_16x16x32_bf16 v[2:5], v[170:173], v[218:221], v[2:5]
	v_mfma_f32_16x16x32_bf16 v[54:57], v[166:169], v[186:189], v[54:57]
	v_mfma_f32_16x16x32_bf16 v[50:53], v[178:181], v[186:189], v[50:53]
	v_mfma_f32_16x16x32_bf16 v[38:41], v[166:169], v[194:197], v[38:41]
	v_mfma_f32_16x16x32_bf16 v[34:37], v[178:181], v[194:197], v[34:37]
	v_mfma_f32_16x16x32_bf16 v[22:25], v[166:169], v[214:217], v[22:25]
	v_mfma_f32_16x16x32_bf16 v[18:21], v[178:181], v[214:217], v[18:21]
	v_mfma_f32_16x16x32_bf16 v[6:9], v[166:169], v[222:225], v[6:9]
	v_mfma_f32_16x16x32_bf16 v[2:5], v[178:181], v[222:225], v[2:5]
	s_setprio 0
	s_barrier
	s_add_i32 s55, s55, 2
	s_add_u32 s53, s53, 0x100
	s_addc_u32 s54, s54, 0
	s_add_u32 s16, s16, 0x100
	s_addc_u32 s17, s17, 0
	s_cmp_gt_u32 s55, 13
	s_cbranch_scc0 .LBB0_1563
	s_and_b64 vcc, exec, s[6:7]
	s_cbranch_vccz .LBB0_1566
	s_barrier

; #define PG8_STAGE(bufoff, gbase, voff) do { _Pragma("unroll") for (int _i = 0; _i < 2; ++_i) \
;         __builtin_amdgcn_global_load_lds((const unsigned*)((const char*)(gbase) + (voff)[_i]), (LAS unsigned*)(lds + (bufoff) + ldsw + _i * 8192), 16, 0, 0); } while (0)
; #define PG8_LDA(dst, b, h) do { _Pragma("unroll") for (int m = 0; m < 4; ++m) _Pragma("unroll") for (int k = 0; k < 2; ++k) dst[m][k] = *(const LAS bf16x8*)(lds + PG8_SA(b, h) + aoff + m * 2048 + k * 1024); } while (0)
; #define PG8_LDB(dst, b, h) do { _Pragma("unroll") for (int n = 0; n < 2; ++n) _Pragma("unroll") for (int k = 0; k < 2; ++k) dst[n][k] = *(const LAS bf16x8*)(lds + PG8_SB(b, h) + boff + n * 2048 + k * 1024); } while (0)
; #define PG8_MMA(ai, bj, At, Bt) do { __builtin_amdgcn_s_setprio(1); _Pragma("unroll") for (int m = 0; m < 4; ++m) _Pragma("unroll") for (int n = 0; n < 2; ++n) _Pragma("unroll") for (int k = 0; k < 2; ++k) \
;         acc[ai][bj][m][n] = __builtin_amdgcn_mfma_f32_16x16x32_bf16(Bt[n][k], At[m][k], acc[ai][bj][m][n], 0, 0, 0); __builtin_amdgcn_s_setprio(0); } while (0)
; #define PG8_WAIT_V(n) asm volatile("s_waitcnt vmcnt(" #n ")" ::: "memory")
; #define PG8_WAIT_L(n) asm volatile("s_waitcnt lgkmcnt(" #n ")" ::: "memory")
; #define PG8_BAR __builtin_amdgcn_s_barrier()
; #define PG8_SCHED __builtin_amdgcn_sched_barrier(0)
; template <class Epi>
; DI void gemm_phase(LAS unsigned char* lds, const Gemm g, const StaticOrder& S, const Epi& E, int wv0) {
;     ...
;             const bool last = (t == nt - 2);
;             const char* a1 = cA + (size_t)(t + 1) * kstep;
;             const char* a2 = last ? nA : cA + (size_t)(t + 2) * kstep; const char* b2 = last ? nB : cB + (size_t)(t + 2) * kstep;
;             const char* a3 = a2 + kstep; const char* b3 = b2 + kstep;
;             PG8_LDB(B0, 0, 0); PG8_LDB(B1, 0, 1); PG8_SCHED; PG8_LDA(At, 0, 0); PG8_STAGE(PG8_SA(1, 1), a1 + hstepA, voffA);
;             PG8_WAIT_V(8); PG8_WAIT_L(0); PG8_BAR; PG8_MMA(0, 0, At, B0); PG8_MMA(0, 1, At, B1); PG8_BAR; PG8_SCHED;
;             PG8_LDA(At, 0, 1); PG8_STAGE(PG8_SB(0, 0), b2, voffB); PG8_STAGE(PG8_SB(0, 1), b2 + hstepB, voffB); PG8_STAGE(PG8_SA(0, 0), a2, voffA);
.LBB0_1631:
	v_add_u32_e32 v140, s64, v142
	ds_read_b128 v[136:139], v140
	ds_read_b128 v[144:147], v140 offset:1024
	ds_read_b128 v[148:151], v140 offset:2048
	ds_read_b128 v[152:155], v140 offset:3072
	v_add_u32_e32 v140, s65, v142
	ds_read_b128 v[158:161], v140
	ds_read_b128 v[162:165], v140 offset:1024
	ds_read_b128 v[166:169], v140 offset:2048
	ds_read_b128 v[170:173], v140 offset:3072
	s_add_u32 s12, s0, 0x100
	s_addc_u32 s13, s1, 0
	s_cmp_eq_u32 s49, 40
	s_cselect_b32 s17, s5, s13
	s_cselect_b32 s16, s4, s12
	s_cselect_b32 s15, s11, s48
	s_cselect_b32 s14, s10, s47
	v_lshl_add_u64 v[140:141], s[0:1], 0, v[134:135]
	s_add_i32 m0, s24, 0xc000
	ds_read_b128 v[178:181], v143
	ds_read_b128 v[182:185], v143 offset:1024
	ds_read_b128 v[186:189], v143 offset:2048
	ds_read_b128 v[190:193], v143 offset:3072
	ds_read_b128 v[194:197], v143 offset:4096
	ds_read_b128 v[210:213], v143 offset:5120
	ds_read_b128 v[214:217], v143 offset:6144
	ds_read_b128 v[218:221], v143 offset:7168
	global_load_lds_dwordx4 v[140:141], off
	v_lshl_add_u64 v[140:141], s[0:1], 0, v[132:133]
	s_add_i32 m0, s24, 0xe000
	s_nop 0
	global_load_lds_dwordx4 v[140:141], off
	s_waitcnt vmcnt(8)
	s_waitcnt lgkmcnt(0)
	s_barrier
	s_setprio 1
	s_waitcnt lgkmcnt(0)
	v_mfma_f32_16x16x32_bf16 v[126:129], v[136:139], v[178:181], v[126:129]
	v_mfma_f32_16x16x32_bf16 v[122:125], v[148:151], v[178:181], v[122:125]
	v_mfma_f32_16x16x32_bf16 v[110:113], v[136:139], v[186:189], v[110:113]
	v_mfma_f32_16x16x32_bf16 v[106:109], v[148:151], v[186:189], v[106:109]
	v_mfma_f32_16x16x32_bf16 v[94:97], v[136:139], v[194:197], v[94:97]
	v_mfma_f32_16x16x32_bf16 v[90:93], v[148:151], v[194:197], v[90:93]
	v_mfma_f32_16x16x32_bf16 v[78:81], v[136:139], v[214:217], v[78:81]
	v_mfma_f32_16x16x32_bf16 v[74:77], v[148:151], v[214:217], v[74:77]
	v_mfma_f32_16x16x32_bf16 v[126:129], v[144:147], v[182:185], v[126:129]
	v_mfma_f32_16x16x32_bf16 v[122:125], v[152:155], v[182:185], v[122:125]
	v_mfma_f32_16x16x32_bf16 v[110:113], v[144:147], v[190:193], v[110:113]
	v_mfma_f32_16x16x32_bf16 v[106:109], v[152:155], v[190:193], v[106:109]
	v_mfma_f32_16x16x32_bf16 v[94:97], v[144:147], v[210:213], v[94:97]
	v_mfma_f32_16x16x32_bf16 v[90:93], v[152:155], v[210:213], v[90:93]
	v_mfma_f32_16x16x32_bf16 v[78:81], v[144:147], v[218:221], v[78:81]
	v_mfma_f32_16x16x32_bf16 v[74:77], v[152:155], v[218:221], v[74:77]
	v_mfma_f32_16x16x32_bf16 v[118:121], v[158:161], v[178:181], v[118:121]
	v_mfma_f32_16x16x32_bf16 v[114:117], v[166:169], v[178:181], v[114:117]
	v_mfma_f32_16x16x32_bf16 v[102:105], v[158:161], v[186:189], v[102:105]
	v_mfma_f32_16x16x32_bf16 v[98:101], v[166:169], v[186:189], v[98:101]
	v_mfma_f32_16x16x32_bf16 v[86:89], v[158:161], v[194:197], v[86:89]
	v_mfma_f32_16x16x32_bf16 v[82:85], v[166:169], v[194:197], v[82:85]
	v_mfma_f32_16x16x32_bf16 v[70:73], v[158:161], v[214:217], v[70:73]
	v_mfma_f32_16x16x32_bf16 v[66:69], v[166:169], v[214:217], v[66:69]
	v_mfma_f32_16x16x32_bf16 v[118:121], v[162:165], v[182:185], v[118:121]
	v_mfma_f32_16x16x32_bf16 v[114:117], v[170:173], v[182:185], v[114:117]
	v_mfma_f32_16x16x32_bf16 v[102:105], v[162:165], v[190:193], v[102:105]
	v_mfma_f32_16x16x32_bf16 v[98:101], v[170:173], v[190:193], v[98:101]
	v_mfma_f32_16x16x32_bf16 v[86:89], v[162:165], v[210:213], v[86:89]
	v_mfma_f32_16x16x32_bf16 v[82:85], v[170:173], v[210:213], v[82:85]
	v_mfma_f32_16x16x32_bf16 v[70:73], v[162:165], v[218:221], v[70:73]
	v_mfma_f32_16x16x32_bf16 v[66:69], v[170:173], v[218:221], v[66:69]
	s_setprio 0
	s_barrier
	s_mov_b32 m0, s20
	v_lshl_add_u64 v[140:141], s[14:15], 0, v[0:1]
	s_add_u32 s0, s14, 0xb0000
	ds_read_b128 v[178:181], v143 offset:16384
	ds_read_b128 v[182:185], v143 offset:17408
	ds_read_b128 v[186:189], v143 offset:18432
	ds_read_b128 v[190:193], v143 offset:19456
	ds_read_b128 v[194:197], v143 offset:20480
	ds_read_b128 v[210:213], v143 offset:21504
	ds_read_b128 v[214:217], v143 offset:22528
	ds_read_b128 v[218:221], v143 offset:23552
	global_load_lds_dwordx4 v[140:141], off
	v_lshl_add_u64 v[174:175], s[14:15], 0, v[130:131]
	s_mov_b32 m0, s21
	s_addc_u32 s1, s15, 0
	global_load_lds_dwordx4 v[174:175], off
	v_lshl_add_u64 v[198:199], s[0:1], 0, v[0:1]
	s_mov_b32 m0, s22
	v_lshl_add_u64 v[202:203], s[16:17], 0, v[130:131]
	global_load_lds_dwordx4 v[198:199], off
	v_lshl_add_u64 v[198:199], s[0:1], 0, v[130:131]
	s_mov_b32 m0, s23
	s_nop 0
	global_load_lds_dwordx4 v[198:199], off
	v_lshl_add_u64 v[198:199], s[16:17], 0, v[0:1]
	s_mov_b32 m0, s24
	s_nop 0
	global_load_lds_dwordx4 v[198:199], off
	s_mov_b32 m0, s25
	s_nop 0
	global_load_lds_dwordx4 v[202:203], off
	s_waitcnt vmcnt(8)
	s_waitcnt lgkmcnt(0)
	s_barrier
; #define PG8_STAGE(bufoff, gbase, voff) do { _Pragma("unroll") for (int _i = 0; _i < 2; ++_i) \
;         __builtin_amdgcn_global_load_lds((const unsigned*)((const char*)(gbase) + (voff)[_i]), (LAS unsigned*)(lds + (bufoff) + ldsw + _i * 8192), 16, 0, 0); } while (0)
; #define PG8_LDA(dst, b, h) do { _Pragma("unroll") for (int m = 0; m < 4; ++m) _Pragma("unroll") for (int k = 0; k < 2; ++k) dst[m][k] = *(const LAS bf16x8*)(lds + PG8_SA(b, h) + aoff + m * 2048 + k * 1024); } while (0)
; #define PG8_LDB(dst, b, h) do { _Pragma("unroll") for (int n = 0; n < 2; ++n) _Pragma("unroll") for (int k = 0; k < 2; ++k) dst[n][k] = *(const LAS bf16x8*)(lds + PG8_SB(b, h) + boff + n * 2048 + k * 1024); } while (0)
; #define PG8_MMA(ai, bj, At, Bt) do { __builtin_amdgcn_s_setprio(1); _Pragma("unroll") for (int m = 0; m < 4; ++m) _Pragma("unroll") for (int n = 0; n < 2; ++n) _Pragma("unroll") for (int k = 0; k < 2; ++k) \
;         acc[ai][bj][m][n] = __builtin_amdgcn_mfma_f32_16x16x32_bf16(Bt[n][k], At[m][k], acc[ai][bj][m][n], 0, 0, 0); __builtin_amdgcn_s_setprio(0); } while (0)
; #define PG8_WAIT_V(n) asm volatile("s_waitcnt vmcnt(" #n ")" ::: "memory")
; #define PG8_WAIT_L(n) asm volatile("s_waitcnt lgkmcnt(" #n ")" ::: "memory")
; #define PG8_BAR __builtin_amdgcn_s_barrier()
; #define PG8_SCHED __builtin_amdgcn_sched_barrier(0)
; template <class Epi>
; DI void gemm_phase(LAS unsigned char* lds, const Gemm g, const StaticOrder& S, const Epi& E, int wv0) {
;     ...
;             PG8_WAIT_V(8); PG8_WAIT_L(0); PG8_BAR; PG8_MMA(1, 0, At, B0); PG8_MMA(1, 1, At, B1); PG8_BAR; PG8_SCHED;
;             PG8_LDB(B0, 1, 0); PG8_LDB(B1, 1, 1); PG8_SCHED; PG8_LDA(At, 1, 0); PG8_STAGE(PG8_SA(0, 1), a2 + hstepA, voffA);
;             PG8_WAIT_V(8); PG8_WAIT_L(0); PG8_BAR; PG8_MMA(0, 0, At, B0); PG8_MMA(0, 1, At, B1); PG8_BAR; PG8_SCHED;
	s_setprio 1
	s_waitcnt lgkmcnt(0)
	v_mfma_f32_16x16x32_bf16 v[62:65], v[136:139], v[178:181], v[62:65]
	v_mfma_f32_16x16x32_bf16 v[58:61], v[148:151], v[178:181], v[58:61]
	v_mfma_f32_16x16x32_bf16 v[46:49], v[136:139], v[186:189], v[46:49]
	v_mfma_f32_16x16x32_bf16 v[42:45], v[148:151], v[186:189], v[42:45]
	v_mfma_f32_16x16x32_bf16 v[30:33], v[136:139], v[194:197], v[30:33]
	v_mfma_f32_16x16x32_bf16 v[26:29], v[148:151], v[194:197], v[26:29]
	v_mfma_f32_16x16x32_bf16 v[14:17], v[136:139], v[214:217], v[14:17]
	v_mfma_f32_16x16x32_bf16 v[10:13], v[148:151], v[214:217], v[10:13]
	v_mfma_f32_16x16x32_bf16 v[62:65], v[144:147], v[182:185], v[62:65]
	v_mfma_f32_16x16x32_bf16 v[58:61], v[152:155], v[182:185], v[58:61]
	v_mfma_f32_16x16x32_bf16 v[46:49], v[144:147], v[190:193], v[46:49]
	v_mfma_f32_16x16x32_bf16 v[42:45], v[152:155], v[190:193], v[42:45]
	v_mfma_f32_16x16x32_bf16 v[30:33], v[144:147], v[210:213], v[30:33]
	v_mfma_f32_16x16x32_bf16 v[26:29], v[152:155], v[210:213], v[26:29]
	v_mfma_f32_16x16x32_bf16 v[14:17], v[144:147], v[218:221], v[14:17]
	v_mfma_f32_16x16x32_bf16 v[10:13], v[152:155], v[218:221], v[10:13]
	v_mfma_f32_16x16x32_bf16 v[54:57], v[158:161], v[178:181], v[54:57]
	v_mfma_f32_16x16x32_bf16 v[50:53], v[166:169], v[178:181], v[50:53]
	v_mfma_f32_16x16x32_bf16 v[38:41], v[158:161], v[186:189], v[38:41]
	v_mfma_f32_16x16x32_bf16 v[34:37], v[166:169], v[186:189], v[34:37]
	v_mfma_f32_16x16x32_bf16 v[22:25], v[158:161], v[194:197], v[22:25]
	v_mfma_f32_16x16x32_bf16 v[18:21], v[166:169], v[194:197], v[18:21]
	v_mfma_f32_16x16x32_bf16 v[6:9], v[158:161], v[214:217], v[6:9]
	v_mfma_f32_16x16x32_bf16 v[2:5], v[166:169], v[214:217], v[2:5]
	v_mfma_f32_16x16x32_bf16 v[54:57], v[162:165], v[182:185], v[54:57]
	v_mfma_f32_16x16x32_bf16 v[50:53], v[170:173], v[182:185], v[50:53]
	v_mfma_f32_16x16x32_bf16 v[38:41], v[162:165], v[190:193], v[38:41]
	v_mfma_f32_16x16x32_bf16 v[34:37], v[170:173], v[190:193], v[34:37]
	v_mfma_f32_16x16x32_bf16 v[22:25], v[162:165], v[210:213], v[22:25]
	v_mfma_f32_16x16x32_bf16 v[18:21], v[170:173], v[210:213], v[18:21]
	v_mfma_f32_16x16x32_bf16 v[6:9], v[162:165], v[218:221], v[6:9]
	v_mfma_f32_16x16x32_bf16 v[2:5], v[170:173], v[218:221], v[2:5]
	s_setprio 0
	s_barrier
	v_add_u32_e32 v152, s66, v142
	v_add_u32_e32 v170, s67, v142
	ds_read_b128 v[136:139], v152
	ds_read_b128 v[144:147], v152 offset:1024
	ds_read_b128 v[148:151], v152 offset:2048
	ds_read_b128 v[152:155], v152 offset:3072
	ds_read_b128 v[158:161], v170
	ds_read_b128 v[162:165], v170 offset:1024
	ds_read_b128 v[166:169], v170 offset:2048
	ds_read_b128 v[170:173], v170 offset:3072
	s_add_u32 s0, s16, 0xb0000
	s_addc_u32 s1, s17, 0
	s_mov_b32 m0, s26
	v_lshl_add_u64 v[222:223], s[0:1], 0, v[0:1]
	ds_read_b128 v[178:181], v143 offset:32768
	ds_read_b128 v[182:185], v143 offset:33792
	ds_read_b128 v[186:189], v143 offset:34816
	ds_read_b128 v[190:193], v143 offset:35840
	ds_read_b128 v[194:197], v143 offset:36864
	ds_read_b128 v[210:213], v143 offset:37888
	ds_read_b128 v[214:217], v143 offset:38912
	ds_read_b128 v[218:221], v143 offset:39936
	global_load_lds_dwordx4 v[222:223], off
	v_lshl_add_u64 v[222:223], s[0:1], 0, v[130:131]
	s_mov_b32 m0, s27
	s_nop 0
	global_load_lds_dwordx4 v[222:223], off
	s_waitcnt vmcnt(8)
	s_waitcnt lgkmcnt(0)
	s_barrier
	s_setprio 1
	s_waitcnt lgkmcnt(0)
	v_mfma_f32_16x16x32_bf16 v[126:129], v[136:139], v[178:181], v[126:129]
	v_mfma_f32_16x16x32_bf16 v[122:125], v[148:151], v[178:181], v[122:125]
	v_mfma_f32_16x16x32_bf16 v[110:113], v[136:139], v[186:189], v[110:113]
	v_mfma_f32_16x16x32_bf16 v[106:109], v[148:151], v[186:189], v[106:109]
	v_mfma_f32_16x16x32_bf16 v[94:97], v[136:139], v[194:197], v[94:97]
	v_mfma_f32_16x16x32_bf16 v[90:93], v[148:151], v[194:197], v[90:93]
	v_mfma_f32_16x16x32_bf16 v[78:81], v[136:139], v[214:217], v[78:81]
	v_mfma_f32_16x16x32_bf16 v[74:77], v[148:151], v[214:217], v[74:77]
	v_mfma_f32_16x16x32_bf16 v[126:129], v[144:147], v[182:185], v[126:129]
	v_mfma_f32_16x16x32_bf16 v[122:125], v[152:155], v[182:185], v[122:125]
	v_mfma_f32_16x16x32_bf16 v[110:113], v[144:147], v[190:193], v[110:113]
	v_mfma_f32_16x16x32_bf16 v[106:109], v[152:155], v[190:193], v[106:109]
	v_mfma_f32_16x16x32_bf16 v[94:97], v[144:147], v[210:213], v[94:97]
	v_mfma_f32_16x16x32_bf16 v[90:93], v[152:155], v[210:213], v[90:93]
	v_mfma_f32_16x16x32_bf16 v[78:81], v[144:147], v[218:221], v[78:81]
	v_mfma_f32_16x16x32_bf16 v[74:77], v[152:155], v[218:221], v[74:77]
	v_mfma_f32_16x16x32_bf16 v[118:121], v[158:161], v[178:181], v[118:121]
	v_mfma_f32_16x16x32_bf16 v[114:117], v[166:169], v[178:181], v[114:117]
	v_mfma_f32_16x16x32_bf16 v[102:105], v[158:161], v[186:189], v[102:105]
	v_mfma_f32_16x16x32_bf16 v[98:101], v[166:169], v[186:189], v[98:101]
	v_mfma_f32_16x16x32_bf16 v[86:89], v[158:161], v[194:197], v[86:89]
	v_mfma_f32_16x16x32_bf16 v[82:85], v[166:169], v[194:197], v[82:85]
	v_mfma_f32_16x16x32_bf16 v[70:73], v[158:161], v[214:217], v[70:73]
	v_mfma_f32_16x16x32_bf16 v[66:69], v[166:169], v[214:217], v[66:69]
	v_mfma_f32_16x16x32_bf16 v[118:121], v[162:165], v[182:185], v[118:121]
	v_mfma_f32_16x16x32_bf16 v[114:117], v[170:173], v[182:185], v[114:117]
	v_mfma_f32_16x16x32_bf16 v[102:105], v[162:165], v[190:193], v[102:105]
	v_mfma_f32_16x16x32_bf16 v[98:101], v[170:173], v[190:193], v[98:101]
	v_mfma_f32_16x16x32_bf16 v[86:89], v[162:165], v[210:213], v[86:89]
	v_mfma_f32_16x16x32_bf16 v[82:85], v[170:173], v[210:213], v[82:85]
	v_mfma_f32_16x16x32_bf16 v[70:73], v[162:165], v[218:221], v[70:73]
	v_mfma_f32_16x16x32_bf16 v[66:69], v[170:173], v[218:221], v[66:69]
	s_setprio 0
	s_barrier
; #define PG8_STAGE(bufoff, gbase, voff) do { _Pragma("unroll") for (int _i = 0; _i < 2; ++_i) \
;         __builtin_amdgcn_global_load_lds((const unsigned*)((const char*)(gbase) + (voff)[_i]), (LAS unsigned*)(lds + (bufoff) + ldsw + _i * 8192), 16, 0, 0); } while (0)
; #define PG8_LDA(dst, b, h) do { _Pragma("unroll") for (int m = 0; m < 4; ++m) _Pragma("unroll") for (int k = 0; k < 2; ++k) dst[m][k] = *(const LAS bf16x8*)(lds + PG8_SA(b, h) + aoff + m * 2048 + k * 1024); } while (0)
; #define PG8_MMA(ai, bj, At, Bt) do { __builtin_amdgcn_s_setprio(1); _Pragma("unroll") for (int m = 0; m < 4; ++m) _Pragma("unroll") for (int n = 0; n < 2; ++n) _Pragma("unroll") for (int k = 0; k < 2; ++k) \
;         acc[ai][bj][m][n] = __builtin_amdgcn_mfma_f32_16x16x32_bf16(Bt[n][k], At[m][k], acc[ai][bj][m][n], 0, 0, 0); __builtin_amdgcn_s_setprio(0); } while (0)
; #define PG8_WAIT_V(n) asm volatile("s_waitcnt vmcnt(" #n ")" ::: "memory")
; #define PG8_WAIT_L(n) asm volatile("s_waitcnt lgkmcnt(" #n ")" ::: "memory")
; #define PG8_BAR __builtin_amdgcn_s_barrier()
; #define PG8_SCHED __builtin_amdgcn_sched_barrier(0)
; template <class Epi>
; DI void gemm_phase(LAS unsigned char* lds, const Gemm g, const StaticOrder& S, const Epi& E, int wv0) {
;     ...
;             PG8_LDA(At, 1, 1); PG8_STAGE(PG8_SB(1, 0), b3, voffB); PG8_STAGE(PG8_SB(1, 1), b3 + hstepB, voffB); PG8_STAGE(PG8_SA(1, 0), a3, voffA);
;             PG8_WAIT_V(8); PG8_WAIT_L(0); PG8_BAR; PG8_MMA(1, 0, At, B0); PG8_MMA(1, 1, At, B1); PG8_BAR; PG8_SCHED;
;         }
	s_mov_b32 m0, s30
	v_lshl_add_u64 v[140:141], v[140:141], 0, s[86:87]
	s_add_u32 s0, s14, 0xb0080
	ds_read_b128 v[178:181], v143 offset:49152
	ds_read_b128 v[182:185], v143 offset:50176
	ds_read_b128 v[186:189], v143 offset:51200
	ds_read_b128 v[190:193], v143 offset:52224
	ds_read_b128 v[194:197], v143 offset:53248
	ds_read_b128 v[210:213], v143 offset:54272
	ds_read_b128 v[214:217], v143 offset:55296
	ds_read_b128 v[218:221], v143 offset:56320
	global_load_lds_dwordx4 v[140:141], off
	v_lshl_add_u64 v[140:141], v[174:175], 0, s[86:87]
	s_mov_b32 m0, s31
	s_addc_u32 s1, s15, 0
	global_load_lds_dwordx4 v[140:141], off
	v_lshl_add_u64 v[140:141], s[0:1], 0, v[0:1]
	s_mov_b32 m0, s40
	s_nop 0
	global_load_lds_dwordx4 v[140:141], off
	v_lshl_add_u64 v[140:141], s[0:1], 0, v[130:131]
	s_mov_b32 m0, s41
	s_nop 0
	global_load_lds_dwordx4 v[140:141], off
	v_lshl_add_u64 v[140:141], v[198:199], 0, s[86:87]
	s_mov_b32 m0, s38
	s_nop 0
	global_load_lds_dwordx4 v[140:141], off
	v_lshl_add_u64 v[140:141], v[202:203], 0, s[86:87]
	s_mov_b32 m0, s39
	s_nop 0
	global_load_lds_dwordx4 v[140:141], off
	s_waitcnt vmcnt(8)
	s_waitcnt lgkmcnt(0)
	s_barrier
	s_setprio 1
	s_waitcnt lgkmcnt(0)
	v_mfma_f32_16x16x32_bf16 v[62:65], v[136:139], v[178:181], v[62:65]
	v_mfma_f32_16x16x32_bf16 v[58:61], v[148:151], v[178:181], v[58:61]
	v_mfma_f32_16x16x32_bf16 v[46:49], v[136:139], v[186:189], v[46:49]
	v_mfma_f32_16x16x32_bf16 v[42:45], v[148:151], v[186:189], v[42:45]
	v_mfma_f32_16x16x32_bf16 v[30:33], v[136:139], v[194:197], v[30:33]
	v_mfma_f32_16x16x32_bf16 v[26:29], v[148:151], v[194:197], v[26:29]
	v_mfma_f32_16x16x32_bf16 v[14:17], v[136:139], v[214:217], v[14:17]
	v_mfma_f32_16x16x32_bf16 v[10:13], v[148:151], v[214:217], v[10:13]
	v_mfma_f32_16x16x32_bf16 v[62:65], v[144:147], v[182:185], v[62:65]
	v_mfma_f32_16x16x32_bf16 v[58:61], v[152:155], v[182:185], v[58:61]
	v_mfma_f32_16x16x32_bf16 v[46:49], v[144:147], v[190:193], v[46:49]
	v_mfma_f32_16x16x32_bf16 v[42:45], v[152:155], v[190:193], v[42:45]
	v_mfma_f32_16x16x32_bf16 v[30:33], v[144:147], v[210:213], v[30:33]
	v_mfma_f32_16x16x32_bf16 v[26:29], v[152:155], v[210:213], v[26:29]
	v_mfma_f32_16x16x32_bf16 v[14:17], v[144:147], v[218:221], v[14:17]
	v_mfma_f32_16x16x32_bf16 v[10:13], v[152:155], v[218:221], v[10:13]
	v_mfma_f32_16x16x32_bf16 v[54:57], v[158:161], v[178:181], v[54:57]
	v_mfma_f32_16x16x32_bf16 v[50:53], v[166:169], v[178:181], v[50:53]
	v_mfma_f32_16x16x32_bf16 v[38:41], v[158:161], v[186:189], v[38:41]
	v_mfma_f32_16x16x32_bf16 v[34:37], v[166:169], v[186:189], v[34:37]
	v_mfma_f32_16x16x32_bf16 v[22:25], v[158:161], v[194:197], v[22:25]
	v_mfma_f32_16x16x32_bf16 v[18:21], v[166:169], v[194:197], v[18:21]
	v_mfma_f32_16x16x32_bf16 v[6:9], v[158:161], v[214:217], v[6:9]
	v_mfma_f32_16x16x32_bf16 v[2:5], v[166:169], v[214:217], v[2:5]
	v_mfma_f32_16x16x32_bf16 v[54:57], v[162:165], v[182:185], v[54:57]
	v_mfma_f32_16x16x32_bf16 v[50:53], v[170:173], v[182:185], v[50:53]
	v_mfma_f32_16x16x32_bf16 v[38:41], v[162:165], v[190:193], v[38:41]
	v_mfma_f32_16x16x32_bf16 v[34:37], v[170:173], v[190:193], v[34:37]
	v_mfma_f32_16x16x32_bf16 v[22:25], v[162:165], v[210:213], v[22:25]
	v_mfma_f32_16x16x32_bf16 v[18:21], v[170:173], v[210:213], v[18:21]
	v_mfma_f32_16x16x32_bf16 v[6:9], v[162:165], v[218:221], v[6:9]
	v_mfma_f32_16x16x32_bf16 v[2:5], v[170:173], v[218:221], v[2:5]
	s_setprio 0
	s_barrier
	s_add_i32 s49, s49, 2
	s_add_u32 s47, s47, 0x100
	s_addc_u32 s48, s48, 0
	s_cmp_gt_u32 s49, 41
	s_mov_b64 s[0:1], s[12:13]
	s_cbranch_scc0 .LBB0_1631
	s_and_b64 vcc, exec, s[8:9]
	s_cbranch_vccz .LBB0_1634
	s_barrier
